# router weights in LDS padded to a conflict-free 144-B lane stride; MoE dispatch row gather with all 32 loads per wave in flight
# speedup vs baseline: 1.0196x; 1.0120x over previous
.LBB0_991:
	ds_read_b128 v[146:149], v142
	ds_read_b128 v[192:195], v142 offset:1024
	ds_read_b128 v[152:155], v142 offset:2048
	ds_read_b128 v[196:199], v142 offset:3072
	ds_read_b128 v[158:161], v143
	ds_read_b128 v[200:203], v143 offset:1024
	ds_read_b128 v[164:167], v143 offset:2048
	ds_read_b128 v[204:207], v143 offset:3072
	v_lshl_add_u64 v[150:151], s[54:55], 0, v[136:137]
	s_add_i32 m0, s29, 0xc000
	ds_read_b128 v[170:173], v144
	ds_read_b128 v[208:211], v144 offset:1024
	ds_read_b128 v[176:179], v144 offset:2048
	ds_read_b128 v[212:215], v144 offset:3072
	ds_read_b128 v[182:185], v144 offset:4096
	ds_read_b128 v[216:219], v144 offset:5120
	ds_read_b128 v[188:191], v144 offset:6144
	ds_read_b128 v[220:223], v144 offset:7168
	global_load_lds_dwordx4 v[150:151], off
	s_add_i32 m0, s29, 0xe000
	v_lshl_add_u64 v[150:151], v[150:151], 0, s[10:11]
	global_load_lds_dwordx4 v[150:151], off
	s_waitcnt vmcnt(8)
	s_waitcnt lgkmcnt(0)
	s_barrier
	s_waitcnt lgkmcnt(0)
	v_mov_b32_e32 v150, v192
	v_mov_b32_e32 v151, v193
	v_mov_b32_e32 v156, v196
	v_mov_b32_e32 v157, v197
	v_mov_b32_e32 v174, v208
	v_mov_b32_e32 v175, v209
	v_mov_b32_e32 v180, v212
	v_mov_b32_e32 v181, v213
	v_mov_b32_e32 v186, v216
	v_mov_b32_e32 v187, v217
	v_mov_b32_e32 v192, v220
	v_mov_b32_e32 v193, v221
	v_mfma_scale_f32_16x16x128_f8f6f4 v[128:131], v[146:151], v[170:175], v[128:131], v194, v210 op_sel_hi:[0,0,0] cbsz:2 blgp:2
	v_mfma_scale_f32_16x16x128_f8f6f4 v[124:127], v[152:157], v[170:175], v[124:127], v198, v210 op_sel_hi:[0,0,0] cbsz:2 blgp:2
	v_mfma_scale_f32_16x16x128_f8f6f4 v[120:123], v[146:151], v[176:181], v[120:123], v194, v214 op_sel_hi:[0,0,0] cbsz:2 blgp:2
	v_mfma_scale_f32_16x16x128_f8f6f4 v[116:119], v[152:157], v[176:181], v[116:119], v198, v214 op_sel_hi:[0,0,0] cbsz:2 blgp:2
	s_add_u32 s56, s54, 0xfffc0080
	s_addc_u32 s57, s55, -1
	s_cmp_eq_u32 s86, 12
	s_cselect_b32 s57, s4, s57
	s_cselect_b32 s56, s5, s56
	s_cselect_b32 s59, s39, s85
	s_cselect_b32 s58, s45, s84
	s_add_i32 s100, s61, s24
	s_add_i32 s101, s62, s24
	v_lshl_add_u64 v[236:237], s[58:59], 0, v[132:133]
	v_lshl_add_u64 v[238:239], s[56:57], 0, v[134:135]
	v_lshl_add_u64 v[240:241], v[236:237], 0, s[10:11]
	v_lshl_add_u64 v[242:243], v[236:237], 0, s[12:13]
	v_lshl_add_u64 v[244:245], v[236:237], 0, s[14:15]
	v_lshl_add_u64 v[246:247], v[238:239], 0, s[10:11]
	v_mfma_scale_f32_16x16x128_f8f6f4 v[112:115], v[146:151], v[182:187], v[112:115], v194, v218 op_sel_hi:[0,0,0] cbsz:2 blgp:2
	v_mfma_scale_f32_16x16x128_f8f6f4 v[108:111], v[152:157], v[182:187], v[108:111], v198, v218 op_sel_hi:[0,0,0] cbsz:2 blgp:2
	v_mfma_scale_f32_16x16x128_f8f6f4 v[104:107], v[146:151], v[188:193], v[104:107], v194, v222 op_sel_hi:[0,0,0] cbsz:2 blgp:2
	v_mfma_scale_f32_16x16x128_f8f6f4 v[100:103], v[152:157], v[188:193], v[100:103], v198, v222 op_sel_hi:[0,0,0] cbsz:2 blgp:2
	v_mov_b32_e32 v168, v204
	v_mov_b32_e32 v169, v205
	v_mov_b32_e32 v162, v200
	v_mov_b32_e32 v163, v201
	v_mfma_scale_f32_16x16x128_f8f6f4 v[30:33], v[164:169], v[188:193], v[30:33], v206, v222 op_sel_hi:[0,0,0] cbsz:2 blgp:2
	s_nop 0
	v_mfma_scale_f32_16x16x128_f8f6f4 v[224:227], v[158:163], v[170:175], v[2:5], v202, v210 op_sel_hi:[0,0,0] cbsz:2 blgp:2
	v_mfma_scale_f32_16x16x128_f8f6f4 v[170:173], v[164:169], v[170:175], v[6:9], v206, v210 op_sel_hi:[0,0,0] cbsz:2 blgp:2
	v_mfma_scale_f32_16x16x128_f8f6f4 v[208:211], v[158:163], v[176:181], v[10:13], v202, v214 op_sel_hi:[0,0,0] cbsz:2 blgp:2
	v_mfma_scale_f32_16x16x128_f8f6f4 v[174:177], v[164:169], v[176:181], v[14:17], v206, v214 op_sel_hi:[0,0,0] cbsz:2 blgp:2
	v_mfma_scale_f32_16x16x128_f8f6f4 v[178:181], v[158:163], v[182:187], v[18:21], v202, v218 op_sel_hi:[0,0,0] cbsz:2 blgp:2
	v_mfma_scale_f32_16x16x128_f8f6f4 v[182:185], v[164:169], v[182:187], v[22:25], v206, v218 op_sel_hi:[0,0,0] cbsz:2 blgp:2
	v_mfma_scale_f32_16x16x128_f8f6f4 v[212:215], v[158:163], v[188:193], v[26:29], v202, v222 op_sel_hi:[0,0,0] cbsz:2 blgp:2
	s_barrier
	s_mov_b32 m0, s100
	ds_read_b128 v[2:5], v144 offset:16384
	ds_read_b128 v[24:27], v144 offset:17408
	ds_read_b128 v[8:11], v144 offset:18432
	global_load_lds_dwordx4 v[236:237], off
	s_add_i32 m0, s100, 0x2000
	ds_read_b128 v[186:189], v144 offset:19456
	global_load_lds_dwordx4 v[240:241], off
	s_mov_b32 m0, s101
	ds_read_b128 v[14:17], v144 offset:20480
	global_load_lds_dwordx4 v[242:243], off
	s_add_i32 m0, s101, 0x2000
	ds_read_b128 v[190:193], v144 offset:21504
	global_load_lds_dwordx4 v[244:245], off
	s_mov_b32 m0, s29
	ds_read_b128 v[20:23], v144 offset:22528
	global_load_lds_dwordx4 v[238:239], off
	s_mov_b32 m0, s33
	ds_read_b128 v[216:219], v144 offset:23552
	global_load_lds_dwordx4 v[246:247], off
	s_waitcnt vmcnt(8)
	s_waitcnt lgkmcnt(0)
	s_barrier
	s_waitcnt lgkmcnt(0)
	v_mov_b32_e32 v6, v24
	v_mov_b32_e32 v7, v25
	v_mov_b32_e32 v12, v186
	v_mov_b32_e32 v13, v187
	v_mov_b32_e32 v18, v190
	v_mov_b32_e32 v19, v191
	v_mfma_scale_f32_16x16x128_f8f6f4 v[96:99], v[146:151], v[2:7], v[96:99], v194, v26 op_sel_hi:[0,0,0] cbsz:2 blgp:2
	v_mov_b32_e32 v24, v216
	v_mov_b32_e32 v25, v217
	v_mfma_scale_f32_16x16x128_f8f6f4 v[92:95], v[152:157], v[2:7], v[92:95], v198, v26 op_sel_hi:[0,0,0] cbsz:2 blgp:2
	v_mfma_scale_f32_16x16x128_f8f6f4 v[80:83], v[146:151], v[8:13], v[80:83], v194, v188 op_sel_hi:[0,0,0] cbsz:2 blgp:2
	v_mfma_scale_f32_16x16x128_f8f6f4 v[76:79], v[152:157], v[8:13], v[76:79], v198, v188 op_sel_hi:[0,0,0] cbsz:2 blgp:2
	s_add_i32 s56, 0, 0x18000
	s_add_i32 s57, 0, 0x1c000
	v_add_u32_e32 v252, 0x18000, v1
	v_add_u32_e32 v253, 0x1c000, v1
	v_lshl_add_u64 v[248:249], v[238:239], 0, s[12:13]
	v_lshl_add_u64 v[250:251], v[238:239], 0, s[14:15]
	v_mfma_scale_f32_16x16x128_f8f6f4 v[68:71], v[146:151], v[14:19], v[68:71], v194, v192 op_sel_hi:[0,0,0] cbsz:2 blgp:2
	v_mfma_scale_f32_16x16x128_f8f6f4 v[56:59], v[152:157], v[14:19], v[56:59], v198, v192 op_sel_hi:[0,0,0] cbsz:2 blgp:2
	v_mfma_scale_f32_16x16x128_f8f6f4 v[194:197], v[146:151], v[20:25], v[52:55], v194, v218 op_sel_hi:[0,0,0] cbsz:2 blgp:2
	v_mfma_scale_f32_16x16x128_f8f6f4 v[198:201], v[152:157], v[20:25], v[44:47], v198, v218 op_sel_hi:[0,0,0] cbsz:2 blgp:2
	v_mfma_scale_f32_16x16x128_f8f6f4 v[88:91], v[158:163], v[2:7], v[88:91], v202, v26 op_sel_hi:[0,0,0] cbsz:2 blgp:2
	v_mfma_scale_f32_16x16x128_f8f6f4 v[84:87], v[164:169], v[2:7], v[84:87], v206, v26 op_sel_hi:[0,0,0] cbsz:2 blgp:2
	v_mfma_scale_f32_16x16x128_f8f6f4 v[72:75], v[158:163], v[8:13], v[72:75], v202, v188 op_sel_hi:[0,0,0] cbsz:2 blgp:2
	v_mfma_scale_f32_16x16x128_f8f6f4 v[186:189], v[164:169], v[8:13], v[64:67], v206, v188 op_sel_hi:[0,0,0] cbsz:2 blgp:2
	v_mfma_scale_f32_16x16x128_f8f6f4 v[220:223], v[158:163], v[14:19], v[60:63], v202, v192 op_sel_hi:[0,0,0] cbsz:2 blgp:2
	v_mfma_scale_f32_16x16x128_f8f6f4 v[190:193], v[164:169], v[14:19], v[48:51], v206, v192 op_sel_hi:[0,0,0] cbsz:2 blgp:2
	v_mfma_scale_f32_16x16x128_f8f6f4 v[202:205], v[158:163], v[20:25], v[40:43], v202, v218 op_sel_hi:[0,0,0] cbsz:2 blgp:2
	v_mfma_scale_f32_16x16x128_f8f6f4 v[216:219], v[164:169], v[20:25], v[36:39], v206, v218 op_sel_hi:[0,0,0] cbsz:2 blgp:2
	s_barrier
	s_mov_b32 m0, s40
	ds_read_b128 v[36:39], v252
	ds_read_b128 v[52:55], v252 offset:1024
	ds_read_b128 v[42:45], v252 offset:2048
	ds_read_b128 v[64:67], v252 offset:3072
	ds_read_b128 v[146:149], v253
	ds_read_b128 v[228:231], v253 offset:1024
	ds_read_b128 v[152:155], v253 offset:2048
	ds_read_b128 v[232:235], v253 offset:3072
	ds_read_b128 v[6:9], v144 offset:32768
	ds_read_b128 v[10:13], v144 offset:33792
	ds_read_b128 v[14:17], v144 offset:34816
	ds_read_b128 v[18:21], v144 offset:35840
	ds_read_b128 v[22:25], v144 offset:36864
	ds_read_b128 v[26:29], v144 offset:37888
	global_load_lds_dwordx4 v[248:249], off
	s_mov_b32 m0, s41
	ds_read_b128 v[48:51], v144 offset:38912
	ds_read_b128 v[60:63], v144 offset:39936
	global_load_lds_dwordx4 v[250:251], off
	s_waitcnt vmcnt(8)
	s_waitcnt lgkmcnt(0)
	s_barrier
	s_waitcnt lgkmcnt(0)
	v_mov_b32_e32 v40, v52
	v_mov_b32_e32 v41, v53
	v_mov_b32_e32 v46, v64
	v_mov_b32_e32 v47, v65
	v_mov_b32_e32 v52, v60
	v_mov_b32_e32 v53, v61
	v_mfma_scale_f32_16x16x128_f8f6f4 v[128:131], v[36:41], v[6:11], v[128:131], v54, v12 op_sel_hi:[0,0,0] cbsz:2 blgp:2
	v_mfma_scale_f32_16x16x128_f8f6f4 v[124:127], v[42:47], v[6:11], v[124:127], v66, v12 op_sel_hi:[0,0,0] cbsz:2 blgp:2
	v_mfma_scale_f32_16x16x128_f8f6f4 v[120:123], v[36:41], v[14:19], v[120:123], v54, v20 op_sel_hi:[0,0,0] cbsz:2 blgp:2
	v_mfma_scale_f32_16x16x128_f8f6f4 v[116:119], v[42:47], v[14:19], v[116:119], v66, v20 op_sel_hi:[0,0,0] cbsz:2 blgp:2
	s_add_i32 s100, s56, s24
	s_add_i32 s101, s57, s24
	s_add_i32 s56, s57, s24
	v_lshl_add_u64 v[240:241], v[236:237], 0, s[22:23]
	v_lshl_add_u64 v[242:243], v[236:237], 0, s[26:27]
	v_lshl_add_u64 v[244:245], v[236:237], 0, s[30:31]
	v_lshl_add_u64 v[246:247], v[236:237], 0, s[34:35]
	v_lshl_add_u64 v[248:249], v[238:239], 0, s[22:23]
	v_lshl_add_u64 v[250:251], v[238:239], 0, s[26:27]
	v_mfma_scale_f32_16x16x128_f8f6f4 v[112:115], v[36:41], v[22:27], v[112:115], v54, v28 op_sel_hi:[0,0,0] cbsz:2 blgp:2
	v_mfma_scale_f32_16x16x128_f8f6f4 v[108:111], v[42:47], v[22:27], v[108:111], v66, v28 op_sel_hi:[0,0,0] cbsz:2 blgp:2
	v_mfma_scale_f32_16x16x128_f8f6f4 v[104:107], v[36:41], v[48:53], v[104:107], v54, v62 op_sel_hi:[0,0,0] cbsz:2 blgp:2
	v_mfma_scale_f32_16x16x128_f8f6f4 v[100:103], v[42:47], v[48:53], v[100:103], v66, v62 op_sel_hi:[0,0,0] cbsz:2 blgp:2
	v_mov_b32_e32 v150, v228
	v_mov_b32_e32 v151, v229
	v_mov_b32_e32 v156, v232
	v_mov_b32_e32 v157, v233
	v_mfma_scale_f32_16x16x128_f8f6f4 v[2:5], v[146:151], v[6:11], v[224:227], v230, v12 op_sel_hi:[0,0,0] cbsz:2 blgp:2
	s_nop 0
	v_mfma_scale_f32_16x16x128_f8f6f4 v[6:9], v[152:157], v[6:11], v[170:173], v234, v12 op_sel_hi:[0,0,0] cbsz:2 blgp:2
	v_mfma_scale_f32_16x16x128_f8f6f4 v[10:13], v[146:151], v[14:19], v[208:211], v230, v20 op_sel_hi:[0,0,0] cbsz:2 blgp:2
	v_mfma_scale_f32_16x16x128_f8f6f4 v[14:17], v[152:157], v[14:19], v[174:177], v234, v20 op_sel_hi:[0,0,0] cbsz:2 blgp:2
	v_mfma_scale_f32_16x16x128_f8f6f4 v[18:21], v[146:151], v[22:27], v[178:181], v230, v28 op_sel_hi:[0,0,0] cbsz:2 blgp:2
	v_mfma_scale_f32_16x16x128_f8f6f4 v[22:25], v[152:157], v[22:27], v[182:185], v234, v28 op_sel_hi:[0,0,0] cbsz:2 blgp:2
	v_mfma_scale_f32_16x16x128_f8f6f4 v[26:29], v[146:151], v[48:53], v[212:215], v230, v62 op_sel_hi:[0,0,0] cbsz:2 blgp:2
	v_mfma_scale_f32_16x16x128_f8f6f4 v[30:33], v[152:157], v[48:53], v[30:33], v234, v62 op_sel_hi:[0,0,0] cbsz:2 blgp:2
	s_barrier
	s_mov_b32 m0, s100
	ds_read_b128 v[60:63], v144 offset:49152
	ds_read_b128 v[48:51], v144 offset:50176
	ds_read_b128 v[158:161], v144 offset:51200
	global_load_lds_dwordx4 v[240:241], off
	s_add_i32 m0, s100, 0x2000
	ds_read_b128 v[174:177], v144 offset:52224
	global_load_lds_dwordx4 v[242:243], off
	s_mov_b32 m0, s101
	ds_read_b128 v[164:167], v144 offset:53248
	global_load_lds_dwordx4 v[244:245], off
	s_add_i32 m0, s101, 0x2000
	ds_read_b128 v[178:181], v144 offset:54272
	global_load_lds_dwordx4 v[246:247], off
	s_mov_b32 m0, s43
	ds_read_b128 v[170:173], v144 offset:55296
	global_load_lds_dwordx4 v[248:249], off
	s_mov_b32 m0, s50
	ds_read_b128 v[182:185], v144 offset:56320
	global_load_lds_dwordx4 v[250:251], off
	s_waitcnt vmcnt(8)
	s_waitcnt lgkmcnt(0)
	s_barrier
	s_waitcnt lgkmcnt(0)
	v_mov_b32_e32 v64, v48
	v_mov_b32_e32 v65, v49
	v_mov_b32_e32 v162, v174
	v_mov_b32_e32 v163, v175
	v_mov_b32_e32 v168, v178
	v_mov_b32_e32 v169, v179
	v_mov_b32_e32 v174, v182
	v_mov_b32_e32 v175, v183
	v_mfma_scale_f32_16x16x128_f8f6f4 v[96:99], v[36:41], v[60:65], v[96:99], v54, v50 op_sel_hi:[0,0,0] cbsz:2 blgp:2
	v_mfma_scale_f32_16x16x128_f8f6f4 v[92:95], v[42:47], v[60:65], v[92:95], v66, v50 op_sel_hi:[0,0,0] cbsz:2 blgp:2
	v_mfma_scale_f32_16x16x128_f8f6f4 v[80:83], v[36:41], v[158:163], v[80:83], v54, v176 op_sel_hi:[0,0,0] cbsz:2 blgp:2
	v_mfma_scale_f32_16x16x128_f8f6f4 v[76:79], v[42:47], v[158:163], v[76:79], v66, v176 op_sel_hi:[0,0,0] cbsz:2 blgp:2
	s_add_i32 s86, s86, 2
	s_add_u32 s54, s54, 0x100
	s_addc_u32 s55, s55, 0
	s_add_u32 s84, s84, 0x100
	s_addc_u32 s85, s85, 0
	v_mfma_scale_f32_16x16x128_f8f6f4 v[68:71], v[36:41], v[164:169], v[68:71], v54, v180 op_sel_hi:[0,0,0] cbsz:2 blgp:2
	v_mfma_scale_f32_16x16x128_f8f6f4 v[56:59], v[42:47], v[164:169], v[56:59], v66, v180 op_sel_hi:[0,0,0] cbsz:2 blgp:2
	v_mfma_scale_f32_16x16x128_f8f6f4 v[52:55], v[36:41], v[170:175], v[194:197], v54, v184 op_sel_hi:[0,0,0] cbsz:2 blgp:2
	v_mfma_scale_f32_16x16x128_f8f6f4 v[44:47], v[42:47], v[170:175], v[198:201], v66, v184 op_sel_hi:[0,0,0] cbsz:2 blgp:2
	v_mfma_scale_f32_16x16x128_f8f6f4 v[88:91], v[146:151], v[60:65], v[88:91], v230, v50 op_sel_hi:[0,0,0] cbsz:2 blgp:2
	v_mfma_scale_f32_16x16x128_f8f6f4 v[84:87], v[152:157], v[60:65], v[84:87], v234, v50 op_sel_hi:[0,0,0] cbsz:2 blgp:2
	v_mfma_scale_f32_16x16x128_f8f6f4 v[72:75], v[146:151], v[158:163], v[72:75], v230, v176 op_sel_hi:[0,0,0] cbsz:2 blgp:2
	v_mfma_scale_f32_16x16x128_f8f6f4 v[64:67], v[152:157], v[158:163], v[186:189], v234, v176 op_sel_hi:[0,0,0] cbsz:2 blgp:2
	v_mfma_scale_f32_16x16x128_f8f6f4 v[60:63], v[146:151], v[164:169], v[220:223], v230, v180 op_sel_hi:[0,0,0] cbsz:2 blgp:2
	v_mfma_scale_f32_16x16x128_f8f6f4 v[48:51], v[152:157], v[164:169], v[190:193], v234, v180 op_sel_hi:[0,0,0] cbsz:2 blgp:2
	v_mfma_scale_f32_16x16x128_f8f6f4 v[40:43], v[146:151], v[170:175], v[202:205], v230, v184 op_sel_hi:[0,0,0] cbsz:2 blgp:2
	v_mfma_scale_f32_16x16x128_f8f6f4 v[36:39], v[152:157], v[170:175], v[216:219], v234, v184 op_sel_hi:[0,0,0] cbsz:2 blgp:2
	s_barrier
	s_cmp_gt_u32 s86, 13
	s_cbranch_scc0 .LBB0_991
	s_setprio 0
	s_and_b64 vcc, exec, s[36:37]
	s_cbranch_vccz .LBB0_994
	s_barrier
.LBB0_994:
	v_mul_f32_e32 v145, 0xbfb8aa3b, v128
	v_exp_f32_e32 v145, v145
	v_mul_f32_e32 v146, 0xbfb8aa3b, v129
	v_exp_f32_e32 v146, v146
	v_mov_b32_e32 v34, v0
	v_add_f32_e32 v145, 1.0, v145
	v_rcp_f32_e32 v145, v145
	v_add_f32_e32 v146, 1.0, v146
	v_rcp_f32_e32 v146, v146
	s_nop 0
	v_and_or_b32 v147, v34, 63, s51
	v_mul_f32_e32 v34, v128, v145
	v_mul_f32_e32 v128, 0xbfb8aa3b, v130
	v_mul_f32_e32 v2, v34, v2
	v_mul_f32_e32 v34, v129, v146
	v_exp_f32_e32 v128, v128
	v_mul_f32_e32 v129, 0xbfb8aa3b, v131
	v_exp_f32_e32 v129, v129
	v_mul_f32_e32 v3, v34, v3
	v_add_f32_e32 v34, 1.0, v128
	v_rcp_f32_e32 v34, v34
	v_add_f32_e32 v128, 1.0, v129
	v_mul_f32_e32 v129, 0xbfb8aa3b, v124
	v_rcp_f32_e32 v128, v128
	v_exp_f32_e32 v129, v129
	v_mul_f32_e32 v34, v130, v34
	v_mul_f32_e32 v4, v34, v4
	v_mul_f32_e32 v34, v131, v128
	v_add_f32_e32 v128, 1.0, v129
	v_rcp_f32_e32 v128, v128
	v_mul_f32_e32 v129, 0xbfb8aa3b, v125
	v_exp_f32_e32 v129, v129
	v_mul_f32_e32 v5, v34, v5
	v_mul_f32_e32 v34, v124, v128
	v_mul_f32_e32 v124, 0xbfb8aa3b, v126
	v_mul_f32_e32 v6, v34, v6
	v_add_f32_e32 v34, 1.0, v129
	v_exp_f32_e32 v124, v124
	v_mul_f32_e32 v128, 0xbfb8aa3b, v127
	v_rcp_f32_e32 v34, v34
	v_exp_f32_e32 v128, v128
	v_add_f32_e32 v124, 1.0, v124
	v_rcp_f32_e32 v124, v124
	v_mul_f32_e32 v34, v125, v34
	v_add_f32_e32 v125, 1.0, v128
	v_rcp_f32_e32 v125, v125
	v_mul_f32_e32 v7, v34, v7
	v_mul_f32_e32 v34, v126, v124
	v_mul_f32_e32 v8, v34, v8
	v_mul_f32_e32 v34, v127, v125
	v_mul_f32_e32 v124, 0xbfb8aa3b, v120
	v_mul_f32_e32 v125, 0xbfb8aa3b, v121
	v_exp_f32_e32 v124, v124
	v_exp_f32_e32 v125, v125
	v_mul_f32_e32 v9, v34, v9
	v_add_f32_e32 v34, 1.0, v124
	v_add_f32_e32 v124, 1.0, v125
	v_mul_f32_e32 v125, 0xbfb8aa3b, v122
	v_rcp_f32_e32 v34, v34
	v_exp_f32_e32 v125, v125
	v_rcp_f32_e32 v124, v124
	v_mul_f32_e32 v34, v120, v34
	v_add_f32_e32 v120, 1.0, v125
	v_mul_f32_e32 v10, v34, v10
	v_mul_f32_e32 v34, v121, v124
	v_rcp_f32_e32 v120, v120
	v_mul_f32_e32 v121, 0xbfb8aa3b, v123
	v_exp_f32_e32 v121, v121
	v_mul_f32_e32 v11, v34, v11
	v_mul_f32_e32 v34, v122, v120
	v_mul_f32_e32 v120, 0xbfb8aa3b, v116
	v_mul_f32_e32 v12, v34, v12
	v_add_f32_e32 v34, 1.0, v121
	v_exp_f32_e32 v120, v120
	v_mul_f32_e32 v121, 0xbfb8aa3b, v117
	v_exp_f32_e32 v121, v121
	v_rcp_f32_e32 v34, v34
	v_add_f32_e32 v120, 1.0, v120
	v_rcp_f32_e32 v120, v120
	v_add_f32_e32 v121, 1.0, v121
	v_rcp_f32_e32 v121, v121
	v_mul_f32_e32 v34, v123, v34
	v_mul_f32_e32 v13, v34, v13
	v_mul_f32_e32 v34, v116, v120
	v_mul_f32_e32 v116, 0xbfb8aa3b, v118
	v_mul_f32_e32 v14, v34, v14
	v_mul_f32_e32 v34, v117, v121
	v_exp_f32_e32 v116, v116
	v_mul_f32_e32 v117, 0xbfb8aa3b, v119
	v_exp_f32_e32 v117, v117
	v_mul_f32_e32 v15, v34, v15
	v_add_f32_e32 v34, 1.0, v116
	v_rcp_f32_e32 v34, v34
	v_add_f32_e32 v116, 1.0, v117
	v_mul_f32_e32 v117, 0xbfb8aa3b, v112
	v_rcp_f32_e32 v116, v116
	v_exp_f32_e32 v117, v117
	v_mul_f32_e32 v34, v118, v34
	v_mul_f32_e32 v16, v34, v16
	v_mul_f32_e32 v34, v119, v116
	v_add_f32_e32 v116, 1.0, v117
	v_rcp_f32_e32 v116, v116
	v_mul_f32_e32 v117, 0xbfb8aa3b, v113
	v_exp_f32_e32 v117, v117
	v_mul_f32_e32 v17, v34, v17
	v_mul_f32_e32 v34, v112, v116
	v_mul_f32_e32 v112, 0xbfb8aa3b, v114
	v_mul_f32_e32 v18, v34, v18
	v_add_f32_e32 v34, 1.0, v117
	v_exp_f32_e32 v112, v112
	v_mul_f32_e32 v116, 0xbfb8aa3b, v115
	v_rcp_f32_e32 v34, v34
	v_exp_f32_e32 v116, v116
	v_add_f32_e32 v112, 1.0, v112
	v_rcp_f32_e32 v112, v112
	v_mul_f32_e32 v34, v113, v34
	v_add_f32_e32 v113, 1.0, v116
	v_rcp_f32_e32 v113, v113
	v_mul_f32_e32 v19, v34, v19
	v_mul_f32_e32 v34, v114, v112
	v_mul_f32_e32 v20, v34, v20
	v_mul_f32_e32 v34, v115, v113
	v_mul_f32_e32 v112, 0xbfb8aa3b, v108
	v_mul_f32_e32 v113, 0xbfb8aa3b, v109
	v_exp_f32_e32 v112, v112
	v_exp_f32_e32 v113, v113
	v_mul_f32_e32 v21, v34, v21
	v_permlane32_swap_b32_e32 v2, v18
	v_add_f32_e32 v34, 1.0, v112
	v_add_f32_e32 v112, 1.0, v113
	v_mul_f32_e32 v113, 0xbfb8aa3b, v110
	v_rcp_f32_e32 v34, v34
	v_exp_f32_e32 v113, v113
	v_rcp_f32_e32 v112, v112
	v_permlane32_swap_b32_e32 v3, v19
	v_mul_f32_e32 v34, v108, v34
	v_add_f32_e32 v108, 1.0, v113
	v_mul_f32_e32 v22, v34, v22
	v_mul_f32_e32 v34, v109, v112
	v_rcp_f32_e32 v108, v108
	v_mul_f32_e32 v109, 0xbfb8aa3b, v111
	v_exp_f32_e32 v109, v109
	v_mul_f32_e32 v23, v34, v23
	v_mul_f32_e32 v34, v110, v108
	v_mul_f32_e32 v108, 0xbfb8aa3b, v104
	v_mul_f32_e32 v24, v34, v24
	v_add_f32_e32 v34, 1.0, v109
	v_exp_f32_e32 v108, v108
	v_mul_f32_e32 v109, 0xbfb8aa3b, v105
	v_exp_f32_e32 v109, v109
	v_rcp_f32_e32 v34, v34
	v_add_f32_e32 v108, 1.0, v108
	v_rcp_f32_e32 v108, v108
	v_add_f32_e32 v109, 1.0, v109
	v_rcp_f32_e32 v109, v109
	v_mul_f32_e32 v34, v111, v34
	v_mul_f32_e32 v25, v34, v25
	v_mul_f32_e32 v34, v104, v108
	v_mul_f32_e32 v104, 0xbfb8aa3b, v106
	v_mul_f32_e32 v26, v34, v26
	v_mul_f32_e32 v34, v105, v109
	v_exp_f32_e32 v104, v104
	v_mul_f32_e32 v105, 0xbfb8aa3b, v107
	v_exp_f32_e32 v105, v105
	v_mul_f32_e32 v27, v34, v27
	v_add_f32_e32 v34, 1.0, v104
	v_rcp_f32_e32 v34, v34
	v_add_f32_e32 v104, 1.0, v105
	v_mul_f32_e32 v105, 0xbfb8aa3b, v100
	v_rcp_f32_e32 v104, v104
	v_exp_f32_e32 v105, v105
	v_mul_f32_e32 v34, v106, v34
	v_mul_f32_e32 v28, v34, v28
	v_mul_f32_e32 v34, v107, v104
	v_add_f32_e32 v104, 1.0, v105
	v_rcp_f32_e32 v104, v104
	v_mul_f32_e32 v105, 0xbfb8aa3b, v101
	v_exp_f32_e32 v105, v105
	v_mul_f32_e32 v29, v34, v29
	v_mul_f32_e32 v34, v100, v104
	v_mul_f32_e32 v100, 0xbfb8aa3b, v102
	v_mul_f32_e32 v30, v34, v30
	v_add_f32_e32 v34, 1.0, v105
	v_exp_f32_e32 v100, v100
	v_mul_f32_e32 v104, 0xbfb8aa3b, v103
	v_rcp_f32_e32 v34, v34
	v_exp_f32_e32 v104, v104
	v_add_f32_e32 v100, 1.0, v100
	v_rcp_f32_e32 v100, v100
	v_mul_f32_e32 v34, v101, v34
	v_add_f32_e32 v101, 1.0, v104
	v_rcp_f32_e32 v101, v101
	v_mul_f32_e32 v31, v34, v31
	v_mul_f32_e32 v34, v102, v100
	v_permlane32_swap_b32_e32 v10, v26
	v_mul_f32_e32 v32, v34, v32
	v_mul_f32_e32 v34, v103, v101
	v_permlane32_swap_b32_e32 v11, v27
	v_permlane16_swap_b32_e32 v2, v10
	v_permlane16_swap_b32_e32 v18, v26
	v_mul_f32_e32 v33, v34, v33
	v_permlane16_swap_b32_e32 v3, v11
	v_permlane16_swap_b32_e32 v19, v27
	v_permlane32_swap_b32_e32 v4, v20
	v_permlane32_swap_b32_e32 v12, v28
	v_permlane32_swap_b32_e32 v5, v21
	v_permlane32_swap_b32_e32 v13, v29
	v_permlane16_swap_b32_e32 v4, v12
	v_permlane16_swap_b32_e32 v20, v28
	v_permlane16_swap_b32_e32 v5, v13
	v_permlane16_swap_b32_e32 v21, v29
	v_max_f32_e64 v34, |v2|, |v18|
	v_max3_f32 v34, v34, |v3|, |v19|
	v_permlane32_swap_b32_e32 v6, v22
	v_permlane32_swap_b32_e32 v14, v30
	v_permlane32_swap_b32_e32 v7, v23
	v_permlane32_swap_b32_e32 v15, v31
	v_permlane16_swap_b32_e32 v6, v14
	v_permlane16_swap_b32_e32 v22, v30
	v_permlane16_swap_b32_e32 v7, v15
	v_permlane16_swap_b32_e32 v23, v31
	v_max3_f32 v34, v34, |v4|, |v20|
	v_max3_f32 v34, v34, |v5|, |v21|
	v_permlane32_swap_b32_e32 v8, v24
	v_permlane32_swap_b32_e32 v16, v32
	v_permlane32_swap_b32_e32 v9, v25
	v_permlane32_swap_b32_e32 v17, v33
	v_permlane16_swap_b32_e32 v8, v16
	v_permlane16_swap_b32_e32 v24, v32
	v_permlane16_swap_b32_e32 v9, v17
	v_permlane16_swap_b32_e32 v25, v33
	v_max3_f32 v34, v34, |v6|, |v22|
	v_max3_f32 v34, v34, |v7|, |v23|
	v_max3_f32 v34, v34, |v8|, |v24|
	v_max3_f32 v34, v34, |v9|, |v25|
	v_max3_f32 v34, v34, |v10|, |v26|
	v_max3_f32 v34, v34, |v11|, |v27|
	v_max3_f32 v34, v34, |v12|, |v28|
	v_max3_f32 v34, v34, |v13|, |v29|
	v_max3_f32 v34, v34, |v14|, |v30|
	v_max3_f32 v34, v34, |v15|, |v31|
	v_max3_f32 v34, v34, |v16|, |v32|
	v_max3_f32 v34, v34, |v17|, |v33|
	v_bfe_u32 v100, v34, 23, 8
	v_and_b32_e32 v34, 0x7fffff, v34
	v_cmp_gt_u32_e32 vcc, s63, v34
	v_lshl_add_u32 v108, s52, 8, v147
	s_lshl_b32 s52, s53, 7
	v_cndmask_b32_e64 v34, -2, -3, vcc
	v_add3_u32 v34, v100, v34, s64
	v_max_i32_e32 v34, 0xffffff88, v34
	v_add_u32_e32 v34, 0x7f, v34
	v_lshlrev_b32_e32 v100, 23, v34
	v_cvt_scalef32_2xpk16_fp6_f32 v[102:107], v[2:17], v[18:33], v100
	v_mul_f32_e32 v4, 0xbfb8aa3b, v96
	v_exp_f32_e32 v4, v4
	v_mul_f32_e32 v5, 0xbfb8aa3b, v97
	v_exp_f32_e32 v5, v5
	v_mov_b64_e32 v[100:101], s[20:21]
	v_add_f32_e32 v4, 1.0, v4
	v_rcp_f32_e32 v4, v4
	v_add_f32_e32 v5, 1.0, v5
	v_mad_i64_i32 v[2:3], s[4:5], v108, s66, v[100:101]
	s_ashr_i32 s53, s52, 31
	v_rcp_f32_e32 v5, v5
	v_mul_f32_e32 v10, 0xbfb8aa3b, v80
	v_mul_f32_e32 v18, 0xbfb8aa3b, v68
	v_mul_f32_e32 v26, 0xbfb8aa3b, v52
	v_lshl_add_u64 v[2:3], v[2:3], 0, s[52:53]
	v_exp_f32_e32 v10, v10
	v_mul_f32_e32 v11, 0xbfb8aa3b, v81
	v_exp_f32_e32 v18, v18
	v_mul_f32_e32 v19, 0xbfb8aa3b, v69
	v_exp_f32_e32 v26, v26
	v_mul_f32_e32 v27, 0xbfb8aa3b, v53
	v_mul_lo_u32 v34, v34, s65
	v_lshl_add_u64 v[2:3], v[2:3], 0, s[18:19]
	v_mov_b32_e32 v32, v106
	v_mov_b32_e32 v33, v107
	v_exp_f32_e32 v11, v11
	v_exp_f32_e32 v19, v19
	v_exp_f32_e32 v27, v27
	global_store_dwordx4 v[2:3], v[102:105], off
	global_store_dwordx4 v[2:3], v[32:35], off offset:64
	v_mul_f32_e32 v2, v96, v4
	v_mul_f32_e32 v4, 0xbfb8aa3b, v98
	v_mul_f32_e32 v12, 0xbfb8aa3b, v82
	v_mul_f32_e32 v20, 0xbfb8aa3b, v70
	v_mul_f32_e32 v28, 0xbfb8aa3b, v54
	v_mul_f32_e32 v30, 0xbfb8aa3b, v44
	v_mul_f32_e32 v3, v97, v5
	v_exp_f32_e32 v4, v4
	v_mul_f32_e32 v5, 0xbfb8aa3b, v99
	v_exp_f32_e32 v12, v12
	v_mul_f32_e32 v13, 0xbfb8aa3b, v83
	v_exp_f32_e32 v20, v20
	v_mul_f32_e32 v21, 0xbfb8aa3b, v71
	v_exp_f32_e32 v28, v28
	v_mul_f32_e32 v29, 0xbfb8aa3b, v55
	v_exp_f32_e32 v30, v30
	v_mul_f32_e32 v31, 0xbfb8aa3b, v45
	v_exp_f32_e32 v5, v5
	v_add_f32_e32 v10, 1.0, v10
	v_exp_f32_e32 v13, v13
	v_add_f32_e32 v18, 1.0, v18
	v_exp_f32_e32 v21, v21
	v_add_f32_e32 v26, 1.0, v26
	v_exp_f32_e32 v29, v29
	v_exp_f32_e32 v31, v31
	v_mul_f32_e32 v6, 0xbfb8aa3b, v92
	v_rcp_f32_e32 v10, v10
	v_add_f32_e32 v11, 1.0, v11
	v_mul_f32_e32 v14, 0xbfb8aa3b, v76
	v_rcp_f32_e32 v18, v18
	v_add_f32_e32 v19, 1.0, v19
	v_mul_f32_e32 v22, 0xbfb8aa3b, v56
	v_rcp_f32_e32 v26, v26
	v_add_f32_e32 v27, 1.0, v27
	v_exp_f32_e32 v6, v6
	v_mul_f32_e32 v7, 0xbfb8aa3b, v93
	v_rcp_f32_e32 v11, v11
	v_exp_f32_e32 v14, v14
	v_mul_f32_e32 v15, 0xbfb8aa3b, v77
	v_rcp_f32_e32 v19, v19
	v_exp_f32_e32 v22, v22
	v_mul_f32_e32 v23, 0xbfb8aa3b, v57
	v_rcp_f32_e32 v27, v27
	v_mul_f32_e32 v32, 0xbfb8aa3b, v46
	v_add_f32_e32 v4, 1.0, v4
	v_exp_f32_e32 v7, v7
	v_add_f32_e32 v12, 1.0, v12
	v_exp_f32_e32 v15, v15
	v_add_f32_e32 v20, 1.0, v20
	v_exp_f32_e32 v23, v23
	v_add_f32_e32 v28, 1.0, v28
	v_add_f32_e32 v30, 1.0, v30
	v_exp_f32_e32 v32, v32
	v_rcp_f32_e32 v4, v4
	v_add_f32_e32 v5, 1.0, v5
	v_mul_f32_e32 v8, 0xbfb8aa3b, v94
	v_rcp_f32_e32 v12, v12
	v_add_f32_e32 v13, 1.0, v13
	v_mul_f32_e32 v16, 0xbfb8aa3b, v78
	v_rcp_f32_e32 v20, v20
	v_add_f32_e32 v21, 1.0, v21
	v_mul_f32_e32 v24, 0xbfb8aa3b, v58
	v_rcp_f32_e32 v28, v28
	v_add_f32_e32 v29, 1.0, v29
	v_rcp_f32_e32 v30, v30
	v_add_f32_e32 v31, 1.0, v31
	v_rcp_f32_e32 v5, v5
	v_exp_f32_e32 v8, v8
	v_mul_f32_e32 v9, 0xbfb8aa3b, v95
	v_mul_f32_e32 v10, v80, v10
	v_rcp_f32_e32 v13, v13
	v_exp_f32_e32 v16, v16
	v_mul_f32_e32 v17, 0xbfb8aa3b, v79
	v_mul_f32_e32 v18, v68, v18
	v_rcp_f32_e32 v21, v21
	v_exp_f32_e32 v24, v24
	v_mul_f32_e32 v25, 0xbfb8aa3b, v59
	v_mul_f32_e32 v26, v52, v26
	v_rcp_f32_e32 v29, v29
	v_rcp_f32_e32 v31, v31
	v_mul_f32_e32 v33, 0xbfb8aa3b, v47
	v_mul_f32_e32 v2, v2, v88
	v_add_f32_e32 v6, 1.0, v6
	v_exp_f32_e32 v9, v9
	v_mul_f32_e32 v10, v10, v72
	v_mul_f32_e32 v11, v81, v11
	v_add_f32_e32 v14, 1.0, v14
	v_exp_f32_e32 v17, v17
	v_mul_f32_e32 v18, v18, v60
	v_mul_f32_e32 v19, v69, v19
	v_add_f32_e32 v22, 1.0, v22
	v_exp_f32_e32 v25, v25
	v_mul_f32_e32 v26, v26, v40
	v_mul_f32_e32 v27, v53, v27
	v_exp_f32_e32 v33, v33
	v_mul_f32_e32 v3, v3, v89
	v_rcp_f32_e32 v6, v6
	v_add_f32_e32 v7, 1.0, v7
	v_mul_f32_e32 v11, v11, v73
	v_rcp_f32_e32 v14, v14
	v_add_f32_e32 v15, 1.0, v15
	v_mul_f32_e32 v19, v19, v61
	v_rcp_f32_e32 v22, v22
	v_add_f32_e32 v23, 1.0, v23
	v_mul_f32_e32 v27, v27, v41
	v_add_f32_e32 v32, 1.0, v32
	v_permlane32_swap_b32_e32 v2, v18
	v_permlane32_swap_b32_e32 v10, v26
	v_mul_f32_e32 v4, v98, v4
	v_rcp_f32_e32 v7, v7
	v_mul_f32_e32 v12, v82, v12
	v_rcp_f32_e32 v15, v15
	v_mul_f32_e32 v20, v70, v20
	v_rcp_f32_e32 v23, v23
	v_mul_f32_e32 v28, v54, v28
	v_mul_f32_e32 v30, v44, v30
	v_rcp_f32_e32 v32, v32
	v_permlane32_swap_b32_e32 v3, v19
	v_permlane32_swap_b32_e32 v11, v27
	v_permlane16_swap_b32_e32 v2, v10
	v_permlane16_swap_b32_e32 v18, v26
	v_mul_f32_e32 v4, v4, v90
	v_mul_f32_e32 v5, v99, v5
	v_add_f32_e32 v8, 1.0, v8
	v_mul_f32_e32 v12, v12, v74
	v_mul_f32_e32 v13, v83, v13
	v_add_f32_e32 v16, 1.0, v16
	v_mul_f32_e32 v20, v20, v62
	v_mul_f32_e32 v21, v71, v21
	v_add_f32_e32 v24, 1.0, v24
	v_mul_f32_e32 v28, v28, v42
	v_mul_f32_e32 v29, v55, v29
	v_mul_f32_e32 v30, v30, v36
	v_mul_f32_e32 v31, v45, v31
	v_permlane16_swap_b32_e32 v3, v11
	v_permlane16_swap_b32_e32 v19, v27
	v_mul_f32_e32 v5, v5, v91
	v_rcp_f32_e32 v8, v8
	v_add_f32_e32 v9, 1.0, v9
	v_mul_f32_e32 v13, v13, v75
	v_rcp_f32_e32 v16, v16
	v_add_f32_e32 v17, 1.0, v17
	v_mul_f32_e32 v21, v21, v63
	v_rcp_f32_e32 v24, v24
	v_add_f32_e32 v25, 1.0, v25
	v_mul_f32_e32 v29, v29, v43
	v_add_f32_e32 v33, 1.0, v33
	v_mul_f32_e32 v31, v31, v37
	v_permlane32_swap_b32_e32 v4, v20
	v_permlane32_swap_b32_e32 v12, v28
	v_mul_f32_e32 v6, v92, v6
	v_rcp_f32_e32 v9, v9
	v_mul_f32_e32 v14, v76, v14
	v_rcp_f32_e32 v17, v17
	v_mul_f32_e32 v22, v56, v22
	v_rcp_f32_e32 v25, v25
	v_rcp_f32_e32 v33, v33
	v_permlane32_swap_b32_e32 v5, v21
	v_permlane32_swap_b32_e32 v13, v29
	v_permlane16_swap_b32_e32 v4, v12
	v_permlane16_swap_b32_e32 v20, v28
	v_mul_f32_e32 v6, v6, v84
	v_mul_f32_e32 v7, v93, v7
	v_mul_f32_e32 v14, v14, v64
	v_mul_f32_e32 v15, v77, v15
	v_mul_f32_e32 v22, v22, v48
	v_mul_f32_e32 v23, v57, v23
	v_mul_f32_e32 v32, v46, v32
	v_permlane16_swap_b32_e32 v5, v13
	v_permlane16_swap_b32_e32 v21, v29
	v_max_f32_e64 v34, |v2|, |v18|
	v_max3_f32 v34, v34, |v3|, |v19|
	v_mul_f32_e32 v7, v7, v85
	v_mul_f32_e32 v15, v15, v65
	v_mul_f32_e32 v23, v23, v49
	v_mul_f32_e32 v32, v32, v38
	v_permlane32_swap_b32_e32 v6, v22
	v_permlane32_swap_b32_e32 v14, v30
	v_mul_f32_e32 v8, v94, v8
	v_mul_f32_e32 v16, v78, v16
	v_mul_f32_e32 v24, v58, v24
	v_permlane32_swap_b32_e32 v7, v23
	v_permlane32_swap_b32_e32 v15, v31
	v_permlane16_swap_b32_e32 v6, v14
	v_permlane16_swap_b32_e32 v22, v30
	v_mul_f32_e32 v8, v8, v86
	v_mul_f32_e32 v9, v95, v9
	v_mul_f32_e32 v16, v16, v66
	v_mul_f32_e32 v17, v79, v17
	v_mul_f32_e32 v24, v24, v50
	v_mul_f32_e32 v25, v59, v25
	v_mul_f32_e32 v33, v47, v33
	v_permlane16_swap_b32_e32 v7, v15
	v_permlane16_swap_b32_e32 v23, v31
	v_max3_f32 v34, v34, |v4|, |v20|
	v_max3_f32 v34, v34, |v5|, |v21|
	v_mul_f32_e32 v9, v9, v87
	v_mul_f32_e32 v17, v17, v67
	v_mul_f32_e32 v25, v25, v51
	v_mul_f32_e32 v33, v33, v39
	v_permlane32_swap_b32_e32 v8, v24
	v_permlane32_swap_b32_e32 v16, v32
	v_permlane32_swap_b32_e32 v9, v25
	v_permlane32_swap_b32_e32 v17, v33
	v_permlane16_swap_b32_e32 v8, v16
	v_permlane16_swap_b32_e32 v24, v32
	v_permlane16_swap_b32_e32 v9, v17
	v_permlane16_swap_b32_e32 v25, v33
	v_max3_f32 v34, v34, |v6|, |v22|
	v_max3_f32 v34, v34, |v7|, |v23|
	v_max3_f32 v34, v34, |v8|, |v24|
	v_max3_f32 v34, v34, |v9|, |v25|
	v_max3_f32 v34, v34, |v10|, |v26|
	v_max3_f32 v34, v34, |v11|, |v27|
	v_max3_f32 v34, v34, |v12|, |v28|
	v_max3_f32 v34, v34, |v13|, |v29|
	v_max3_f32 v34, v34, |v14|, |v30|
	v_max3_f32 v34, v34, |v15|, |v31|
	v_max3_f32 v34, v34, |v16|, |v32|
	v_max3_f32 v34, v34, |v17|, |v33|
	v_bfe_u32 v36, v34, 23, 8
	v_and_b32_e32 v34, 0x7fffff, v34
	v_cmp_gt_u32_e32 vcc, s63, v34
	s_nop 1
	v_cndmask_b32_e64 v34, -2, -3, vcc
	v_add3_u32 v34, v36, v34, s64
	v_max_i32_e32 v34, 0xffffff88, v34
	v_add_u32_e32 v34, 0x7f, v34
	v_lshlrev_b32_e32 v42, 23, v34
	v_cvt_scalef32_2xpk16_fp6_f32 v[36:41], v[2:17], v[18:33], v42
	v_add_u32_e32 v2, 0x80, v108
	v_mad_i64_i32 v[2:3], s[4:5], v2, s66, v[100:101]
	v_lshl_add_u64 v[2:3], v[2:3], 0, s[52:53]
	v_mul_lo_u32 v34, v34, s65
	v_lshl_add_u64 v[2:3], v[2:3], 0, s[18:19]
	v_mov_b32_e32 v32, v40
	v_mov_b32_e32 v33, v41
	s_andn2_b64 vcc, exec, s[6:7]
	s_mov_b64 s[4:5], -1
	global_store_dwordx4 v[2:3], v[36:39], off
	global_store_dwordx4 v[2:3], v[32:35], off offset:64
	s_cbranch_vccnz .LBB0_987
	s_andn2_b64 vcc, exec, s[16:17]
	s_cbranch_vccnz .LBB0_986
	s_barrier
	s_branch .LBB0_986

.LBB0_1077:
	v_mov_b32_e32 v116, v0
	s_lshl_b32 s5, s62, 8
	v_lshrrev_b32_e32 v114, 1, v116
	s_lshl_b32 s4, s61, 8
	v_and_or_b32 v114, v114, 24, s5
	s_add_i32 s4, s4, s84
	v_or_b32_e32 v114, s85, v114
	v_ashrrev_i32_e32 v115, 31, v114
	v_and_or_b32 v174, v116, 15, s4
	v_lshlrev_b64 v[172:173], 2, v[114:115]
	v_ashrrev_i32_e32 v175, 31, v174
	v_lshlrev_b32_e32 v114, 1, v174
	v_ashrrev_i32_e32 v115, 31, v114
	v_lshlrev_b64 v[116:117], 13, v[174:175]
	v_lshl_add_u64 v[114:115], v[114:115], 2, s[22:23]
	v_lshl_add_u64 v[116:117], s[20:21], 0, v[116:117]
	v_readlane_b32 s48, v254, 30
	v_lshl_add_u64 v[196:197], v[116:117], 0, v[172:173]
	global_load_dwordx2 v[198:199], v[114:115], off
	global_load_dwordx4 v[180:183], v[196:197], off
	global_load_dwordx4 v[184:187], v[196:197], off offset:16
	global_load_dwordx4 v[188:191], v[196:197], off offset:512
	global_load_dwordx4 v[192:195], v[196:197], off offset:528
	v_readlane_b32 s52, v254, 34
	v_readlane_b32 s53, v254, 35
	v_readlane_b32 s54, v254, 36
	v_readlane_b32 s55, v254, 37
	v_lshl_add_u64 v[122:123], s[52:53], 0, v[172:173]
	v_or_b32_e32 v200, 16, v174
	v_lshl_add_u64 v[142:143], s[54:55], 0, v[172:173]
	global_load_dwordx4 v[118:121], v[142:143], off
	global_load_dwordx4 v[130:133], v[122:123], off
	global_load_dwordx4 v[114:117], v[122:123], off offset:16
	global_load_dwordx4 v[134:137], v[142:143], off offset:16
	global_load_dwordx4 v[126:129], v[142:143], off offset:512
	global_load_dwordx4 v[138:141], v[122:123], off offset:512
	s_nop 0
	global_load_dwordx4 v[122:125], v[122:123], off offset:528
	s_nop 0
	global_load_dwordx4 v[142:145], v[142:143], off offset:528
	v_ashrrev_i32_e32 v201, 31, v200
	v_lshlrev_b32_e32 v202, 1, v200
	v_ashrrev_i32_e32 v203, 31, v202
	v_lshlrev_b64 v[200:201], 13, v[200:201]
	v_lshl_add_u64 v[202:203], v[202:203], 2, s[22:23]
	v_lshl_add_u64 v[200:201], s[20:21], 0, v[200:201]
	v_lshl_add_u64 v[200:201], v[200:201], 0, v[172:173]
	s_and_b64 vcc, exec, s[6:7]
	s_mov_b64 s[4:5], -1
	v_readlane_b32 s49, v254, 31
	v_readlane_b32 s50, v254, 32
	v_readlane_b32 s51, v254, 33
	v_readlane_b32 s56, v254, 38
	v_readlane_b32 s57, v254, 39
	v_readlane_b32 s58, v254, 40
	v_readlane_b32 s59, v254, 41
	v_readlane_b32 s60, v254, 42
	v_readlane_b32 s61, v254, 43
	v_readlane_b32 s62, v254, 44
	v_readlane_b32 s63, v254, 45
	s_waitcnt vmcnt(0)
	v_sub_f32_e32 v183, v183, v198
	v_sub_f32_e32 v182, v182, v198
	v_sub_f32_e32 v181, v181, v198
	v_sub_f32_e32 v180, v180, v198
	v_sub_f32_e32 v187, v187, v198
	v_sub_f32_e32 v186, v186, v198
	v_sub_f32_e32 v185, v185, v198
	v_sub_f32_e32 v184, v184, v198
	v_sub_f32_e32 v191, v191, v198
	v_sub_f32_e32 v190, v190, v198
	v_sub_f32_e32 v189, v189, v198
	v_sub_f32_e32 v188, v188, v198
	v_sub_f32_e32 v195, v195, v198
	v_sub_f32_e32 v194, v194, v198
	v_sub_f32_e32 v193, v193, v198
	v_sub_f32_e32 v192, v192, v198
	v_pk_mul_f32 v[180:181], v[198:199], v[180:181] op_sel:[1,0]
	v_pk_mul_f32 v[182:183], v[198:199], v[182:183] op_sel:[1,0]
	v_pk_mul_f32 v[184:185], v[198:199], v[184:185] op_sel:[1,0]
	v_pk_mul_f32 v[186:187], v[198:199], v[186:187] op_sel:[1,0]
	v_pk_mul_f32 v[188:189], v[198:199], v[188:189] op_sel:[1,0]
	v_pk_mul_f32 v[190:191], v[198:199], v[190:191] op_sel:[1,0]
	v_pk_mul_f32 v[192:193], v[198:199], v[192:193] op_sel:[1,0]
	v_pk_mul_f32 v[194:195], v[198:199], v[194:195] op_sel:[1,0]
	v_pk_fma_f32 v[182:183], v[132:133], v[182:183], v[120:121]
	v_pk_fma_f32 v[180:181], v[130:131], v[180:181], v[118:119]
	v_pk_fma_f32 v[186:187], v[116:117], v[186:187], v[136:137]
	v_pk_fma_f32 v[184:185], v[114:115], v[184:185], v[134:135]
	v_pk_fma_f32 v[190:191], v[140:141], v[190:191], v[128:129]
	v_pk_fma_f32 v[188:189], v[138:139], v[188:189], v[126:127]
	v_pk_fma_f32 v[194:195], v[124:125], v[194:195], v[144:145]
	v_pk_fma_f32 v[192:193], v[122:123], v[192:193], v[142:143]
	v_pk_fma_f32 v[160:161], v[182:183], s[44:45], v[160:161] op_sel_hi:[1,0,1]
	v_pk_fma_f32 v[158:159], v[180:181], s[44:45], v[158:159] op_sel_hi:[1,0,1]
	v_pk_fma_f32 v[156:157], v[186:187], s[44:45], v[156:157] op_sel_hi:[1,0,1]
	v_pk_fma_f32 v[154:155], v[184:185], s[44:45], v[154:155] op_sel_hi:[1,0,1]
	v_pk_fma_f32 v[152:153], v[190:191], s[44:45], v[152:153] op_sel_hi:[1,0,1]
	v_pk_fma_f32 v[150:151], v[188:189], s[44:45], v[150:151] op_sel_hi:[1,0,1]
	v_pk_fma_f32 v[148:149], v[194:195], s[44:45], v[148:149] op_sel_hi:[1,0,1]
	v_pk_fma_f32 v[146:147], v[192:193], s[44:45], v[146:147] op_sel_hi:[1,0,1]
	global_store_dwordx4 v[196:197], v[158:161], off
	global_store_dwordx4 v[196:197], v[154:157], off offset:16
	global_store_dwordx4 v[196:197], v[150:153], off offset:512
	global_store_dwordx4 v[196:197], v[146:149], off offset:528
	global_load_dwordx2 v[180:181], v[202:203], off
	global_load_dwordx4 v[146:149], v[200:201], off
	global_load_dwordx4 v[150:153], v[200:201], off offset:16
	global_load_dwordx4 v[154:157], v[200:201], off offset:512
	global_load_dwordx4 v[158:161], v[200:201], off offset:528
	v_or_b32_e32 v182, 32, v174
	v_ashrrev_i32_e32 v183, 31, v182
	v_lshlrev_b32_e32 v184, 1, v182
	v_ashrrev_i32_e32 v185, 31, v184
	v_lshlrev_b64 v[182:183], 13, v[182:183]
	v_lshl_add_u64 v[184:185], v[184:185], 2, s[22:23]
	v_lshl_add_u64 v[182:183], s[20:21], 0, v[182:183]
	v_lshl_add_u64 v[182:183], v[182:183], 0, v[172:173]
	s_waitcnt vmcnt(3)
	v_sub_f32_e32 v149, v149, v180
	v_sub_f32_e32 v148, v148, v180
	v_sub_f32_e32 v147, v147, v180
	v_sub_f32_e32 v146, v146, v180
	s_waitcnt vmcnt(2)
	v_sub_f32_e32 v153, v153, v180
	v_sub_f32_e32 v152, v152, v180
	v_sub_f32_e32 v151, v151, v180
	v_sub_f32_e32 v150, v150, v180
	s_waitcnt vmcnt(1)
	v_sub_f32_e32 v157, v157, v180
	v_sub_f32_e32 v156, v156, v180
	v_sub_f32_e32 v155, v155, v180
	v_sub_f32_e32 v154, v154, v180
	s_waitcnt vmcnt(0)
	v_sub_f32_e32 v161, v161, v180
	v_sub_f32_e32 v160, v160, v180
	v_sub_f32_e32 v159, v159, v180
	v_sub_f32_e32 v158, v158, v180
	v_pk_mul_f32 v[146:147], v[180:181], v[146:147] op_sel:[1,0]
	v_pk_mul_f32 v[148:149], v[180:181], v[148:149] op_sel:[1,0]
	v_pk_mul_f32 v[150:151], v[180:181], v[150:151] op_sel:[1,0]
	v_pk_mul_f32 v[152:153], v[180:181], v[152:153] op_sel:[1,0]
	v_pk_mul_f32 v[154:155], v[180:181], v[154:155] op_sel:[1,0]
	v_pk_mul_f32 v[156:157], v[180:181], v[156:157] op_sel:[1,0]
	v_pk_mul_f32 v[158:159], v[180:181], v[158:159] op_sel:[1,0]
	v_pk_mul_f32 v[160:161], v[180:181], v[160:161] op_sel:[1,0]
	v_pk_fma_f32 v[148:149], v[132:133], v[148:149], v[120:121]
	v_pk_fma_f32 v[146:147], v[130:131], v[146:147], v[118:119]
	v_pk_fma_f32 v[152:153], v[116:117], v[152:153], v[136:137]
	v_pk_fma_f32 v[150:151], v[114:115], v[150:151], v[134:135]
	v_pk_fma_f32 v[156:157], v[140:141], v[156:157], v[128:129]
	v_pk_fma_f32 v[154:155], v[138:139], v[154:155], v[126:127]
	v_pk_fma_f32 v[160:161], v[124:125], v[160:161], v[144:145]
	v_pk_fma_f32 v[158:159], v[122:123], v[158:159], v[142:143]
	v_pk_fma_f32 v[112:113], v[148:149], s[44:45], v[112:113] op_sel_hi:[1,0,1]
	v_pk_fma_f32 v[110:111], v[146:147], s[44:45], v[110:111] op_sel_hi:[1,0,1]
	v_pk_fma_f32 v[108:109], v[152:153], s[44:45], v[108:109] op_sel_hi:[1,0,1]
	v_pk_fma_f32 v[106:107], v[150:151], s[44:45], v[106:107] op_sel_hi:[1,0,1]
	v_pk_fma_f32 v[104:105], v[156:157], s[44:45], v[104:105] op_sel_hi:[1,0,1]
	v_pk_fma_f32 v[102:103], v[154:155], s[44:45], v[102:103] op_sel_hi:[1,0,1]
	v_pk_fma_f32 v[100:101], v[160:161], s[44:45], v[100:101] op_sel_hi:[1,0,1]
	v_pk_fma_f32 v[98:99], v[158:159], s[44:45], v[98:99] op_sel_hi:[1,0,1]
	global_store_dwordx4 v[200:201], v[110:113], off
	global_store_dwordx4 v[200:201], v[106:109], off offset:16
	global_store_dwordx4 v[200:201], v[102:105], off offset:512
	global_store_dwordx4 v[200:201], v[98:101], off offset:528
	global_load_dwordx2 v[146:147], v[184:185], off
	global_load_dwordx4 v[98:101], v[182:183], off
	global_load_dwordx4 v[102:105], v[182:183], off offset:16
	global_load_dwordx4 v[106:109], v[182:183], off offset:512
	global_load_dwordx4 v[110:113], v[182:183], off offset:528
	v_or_b32_e32 v148, 48, v174
	v_ashrrev_i32_e32 v149, 31, v148
	v_lshlrev_b32_e32 v150, 1, v148
	v_ashrrev_i32_e32 v151, 31, v150
	v_lshlrev_b64 v[148:149], 13, v[148:149]
	v_lshl_add_u64 v[150:151], v[150:151], 2, s[22:23]
	v_lshl_add_u64 v[148:149], s[20:21], 0, v[148:149]
	v_lshl_add_u64 v[148:149], v[148:149], 0, v[172:173]
	s_waitcnt vmcnt(3)
	v_sub_f32_e32 v101, v101, v146
	v_sub_f32_e32 v100, v100, v146
	v_sub_f32_e32 v99, v99, v146
	v_sub_f32_e32 v98, v98, v146
	s_waitcnt vmcnt(2)
	v_sub_f32_e32 v105, v105, v146
	v_sub_f32_e32 v104, v104, v146
	v_sub_f32_e32 v103, v103, v146
	v_sub_f32_e32 v102, v102, v146
	s_waitcnt vmcnt(1)
	v_sub_f32_e32 v109, v109, v146
	v_sub_f32_e32 v108, v108, v146
	v_sub_f32_e32 v107, v107, v146
	v_sub_f32_e32 v106, v106, v146
	s_waitcnt vmcnt(0)
	v_sub_f32_e32 v113, v113, v146
	v_sub_f32_e32 v112, v112, v146
	v_sub_f32_e32 v111, v111, v146
	v_sub_f32_e32 v110, v110, v146
	v_pk_mul_f32 v[98:99], v[146:147], v[98:99] op_sel:[1,0]
	v_pk_mul_f32 v[100:101], v[146:147], v[100:101] op_sel:[1,0]
	v_pk_mul_f32 v[102:103], v[146:147], v[102:103] op_sel:[1,0]
	v_pk_mul_f32 v[104:105], v[146:147], v[104:105] op_sel:[1,0]
	v_pk_mul_f32 v[106:107], v[146:147], v[106:107] op_sel:[1,0]
	v_pk_mul_f32 v[108:109], v[146:147], v[108:109] op_sel:[1,0]
	v_pk_mul_f32 v[110:111], v[146:147], v[110:111] op_sel:[1,0]
	v_pk_mul_f32 v[112:113], v[146:147], v[112:113] op_sel:[1,0]
	v_pk_fma_f32 v[100:101], v[132:133], v[100:101], v[120:121]
	v_pk_fma_f32 v[98:99], v[130:131], v[98:99], v[118:119]
	v_pk_fma_f32 v[104:105], v[116:117], v[104:105], v[136:137]
	v_pk_fma_f32 v[102:103], v[114:115], v[102:103], v[134:135]
	v_pk_fma_f32 v[108:109], v[140:141], v[108:109], v[128:129]
	v_pk_fma_f32 v[106:107], v[138:139], v[106:107], v[126:127]
	v_pk_fma_f32 v[112:113], v[124:125], v[112:113], v[144:145]
	v_pk_fma_f32 v[110:111], v[122:123], v[110:111], v[142:143]
	v_pk_fma_f32 v[96:97], v[100:101], s[44:45], v[96:97] op_sel_hi:[1,0,1]
	v_pk_fma_f32 v[94:95], v[98:99], s[44:45], v[94:95] op_sel_hi:[1,0,1]
	v_pk_fma_f32 v[92:93], v[104:105], s[44:45], v[92:93] op_sel_hi:[1,0,1]
	v_pk_fma_f32 v[90:91], v[102:103], s[44:45], v[90:91] op_sel_hi:[1,0,1]
	v_pk_fma_f32 v[88:89], v[108:109], s[44:45], v[88:89] op_sel_hi:[1,0,1]
	v_pk_fma_f32 v[86:87], v[106:107], s[44:45], v[86:87] op_sel_hi:[1,0,1]
	v_pk_fma_f32 v[84:85], v[112:113], s[44:45], v[84:85] op_sel_hi:[1,0,1]
	v_pk_fma_f32 v[82:83], v[110:111], s[44:45], v[82:83] op_sel_hi:[1,0,1]
	global_store_dwordx4 v[182:183], v[94:97], off
	global_store_dwordx4 v[182:183], v[90:93], off offset:16
	global_store_dwordx4 v[182:183], v[86:89], off offset:512
	global_store_dwordx4 v[182:183], v[82:85], off offset:528
	global_load_dwordx2 v[98:99], v[150:151], off
	global_load_dwordx4 v[82:85], v[148:149], off
	global_load_dwordx4 v[86:89], v[148:149], off offset:16
	global_load_dwordx4 v[90:93], v[148:149], off offset:512
	global_load_dwordx4 v[94:97], v[148:149], off offset:528
	v_add_u32_e32 v100, 0x80, v174
	v_ashrrev_i32_e32 v101, 31, v100
	v_lshlrev_b32_e32 v102, 1, v100
	v_ashrrev_i32_e32 v103, 31, v102
	v_lshlrev_b64 v[100:101], 13, v[100:101]
	v_lshl_add_u64 v[102:103], v[102:103], 2, s[22:23]
	v_lshl_add_u64 v[100:101], s[20:21], 0, v[100:101]
	v_lshl_add_u64 v[100:101], v[100:101], 0, v[172:173]
	s_waitcnt vmcnt(3)
	v_sub_f32_e32 v85, v85, v98
	v_sub_f32_e32 v84, v84, v98
	v_sub_f32_e32 v83, v83, v98
	v_sub_f32_e32 v82, v82, v98
	s_waitcnt vmcnt(2)
	v_sub_f32_e32 v89, v89, v98
	v_sub_f32_e32 v88, v88, v98
	v_sub_f32_e32 v87, v87, v98
	v_sub_f32_e32 v86, v86, v98
	s_waitcnt vmcnt(1)
	v_sub_f32_e32 v93, v93, v98
	v_sub_f32_e32 v92, v92, v98
	v_sub_f32_e32 v91, v91, v98
	v_sub_f32_e32 v90, v90, v98
	s_waitcnt vmcnt(0)
	v_sub_f32_e32 v97, v97, v98
	v_sub_f32_e32 v96, v96, v98
	v_sub_f32_e32 v95, v95, v98
	v_sub_f32_e32 v94, v94, v98
	v_pk_mul_f32 v[82:83], v[98:99], v[82:83] op_sel:[1,0]
	v_pk_mul_f32 v[84:85], v[98:99], v[84:85] op_sel:[1,0]
	v_pk_mul_f32 v[86:87], v[98:99], v[86:87] op_sel:[1,0]
	v_pk_mul_f32 v[88:89], v[98:99], v[88:89] op_sel:[1,0]
	v_pk_mul_f32 v[90:91], v[98:99], v[90:91] op_sel:[1,0]
	v_pk_mul_f32 v[92:93], v[98:99], v[92:93] op_sel:[1,0]
	v_pk_mul_f32 v[94:95], v[98:99], v[94:95] op_sel:[1,0]
	v_pk_mul_f32 v[96:97], v[98:99], v[96:97] op_sel:[1,0]
	v_pk_fma_f32 v[84:85], v[132:133], v[84:85], v[120:121]
	v_pk_fma_f32 v[82:83], v[130:131], v[82:83], v[118:119]
	v_pk_fma_f32 v[88:89], v[116:117], v[88:89], v[136:137]
	v_pk_fma_f32 v[86:87], v[114:115], v[86:87], v[134:135]
	v_pk_fma_f32 v[92:93], v[140:141], v[92:93], v[128:129]
	v_pk_fma_f32 v[90:91], v[138:139], v[90:91], v[126:127]
	v_pk_fma_f32 v[96:97], v[124:125], v[96:97], v[144:145]
	v_pk_fma_f32 v[94:95], v[122:123], v[94:95], v[142:143]
	v_pk_fma_f32 v[80:81], v[84:85], s[44:45], v[80:81] op_sel_hi:[1,0,1]
	v_pk_fma_f32 v[78:79], v[82:83], s[44:45], v[78:79] op_sel_hi:[1,0,1]
	v_pk_fma_f32 v[76:77], v[88:89], s[44:45], v[76:77] op_sel_hi:[1,0,1]
	v_pk_fma_f32 v[74:75], v[86:87], s[44:45], v[74:75] op_sel_hi:[1,0,1]
	v_pk_fma_f32 v[72:73], v[92:93], s[44:45], v[72:73] op_sel_hi:[1,0,1]
	v_pk_fma_f32 v[70:71], v[90:91], s[44:45], v[70:71] op_sel_hi:[1,0,1]
	v_pk_fma_f32 v[68:69], v[96:97], s[44:45], v[68:69] op_sel_hi:[1,0,1]
	v_pk_fma_f32 v[66:67], v[94:95], s[44:45], v[66:67] op_sel_hi:[1,0,1]
	global_store_dwordx4 v[148:149], v[78:81], off
	global_store_dwordx4 v[148:149], v[74:77], off offset:16
	global_store_dwordx4 v[148:149], v[70:73], off offset:512
	global_store_dwordx4 v[148:149], v[66:69], off offset:528
	global_load_dwordx2 v[82:83], v[102:103], off
	global_load_dwordx4 v[66:69], v[100:101], off
	global_load_dwordx4 v[70:73], v[100:101], off offset:16
	global_load_dwordx4 v[74:77], v[100:101], off offset:512
	global_load_dwordx4 v[78:81], v[100:101], off offset:528
	v_add_u32_e32 v84, 0x90, v174
	v_ashrrev_i32_e32 v85, 31, v84
	v_lshlrev_b32_e32 v86, 1, v84
	v_ashrrev_i32_e32 v87, 31, v86
	v_lshlrev_b64 v[84:85], 13, v[84:85]
	v_lshl_add_u64 v[86:87], v[86:87], 2, s[22:23]
	v_lshl_add_u64 v[84:85], s[20:21], 0, v[84:85]
	v_lshl_add_u64 v[84:85], v[84:85], 0, v[172:173]
	s_waitcnt vmcnt(3)
	v_sub_f32_e32 v69, v69, v82
	v_sub_f32_e32 v68, v68, v82
	v_sub_f32_e32 v67, v67, v82
	v_sub_f32_e32 v66, v66, v82
	s_waitcnt vmcnt(2)
	v_sub_f32_e32 v73, v73, v82
	v_sub_f32_e32 v72, v72, v82
	v_sub_f32_e32 v71, v71, v82
	v_sub_f32_e32 v70, v70, v82
	s_waitcnt vmcnt(1)
	v_sub_f32_e32 v77, v77, v82
	v_sub_f32_e32 v76, v76, v82
	v_sub_f32_e32 v75, v75, v82
	v_sub_f32_e32 v74, v74, v82
	s_waitcnt vmcnt(0)
	v_sub_f32_e32 v81, v81, v82
	v_sub_f32_e32 v80, v80, v82
	v_sub_f32_e32 v79, v79, v82
	v_sub_f32_e32 v78, v78, v82
	v_pk_mul_f32 v[66:67], v[82:83], v[66:67] op_sel:[1,0]
	v_pk_mul_f32 v[68:69], v[82:83], v[68:69] op_sel:[1,0]
	v_pk_mul_f32 v[70:71], v[82:83], v[70:71] op_sel:[1,0]
	v_pk_mul_f32 v[72:73], v[82:83], v[72:73] op_sel:[1,0]
	v_pk_mul_f32 v[74:75], v[82:83], v[74:75] op_sel:[1,0]
	v_pk_mul_f32 v[76:77], v[82:83], v[76:77] op_sel:[1,0]
	v_pk_mul_f32 v[78:79], v[82:83], v[78:79] op_sel:[1,0]
	v_pk_mul_f32 v[80:81], v[82:83], v[80:81] op_sel:[1,0]
	v_pk_fma_f32 v[68:69], v[132:133], v[68:69], v[120:121]
	v_pk_fma_f32 v[66:67], v[130:131], v[66:67], v[118:119]
	v_pk_fma_f32 v[72:73], v[116:117], v[72:73], v[136:137]
	v_pk_fma_f32 v[70:71], v[114:115], v[70:71], v[134:135]
	v_pk_fma_f32 v[76:77], v[140:141], v[76:77], v[128:129]
	v_pk_fma_f32 v[74:75], v[138:139], v[74:75], v[126:127]
	v_pk_fma_f32 v[80:81], v[124:125], v[80:81], v[144:145]
	v_pk_fma_f32 v[78:79], v[122:123], v[78:79], v[142:143]
	v_pk_fma_f32 v[64:65], v[68:69], s[44:45], v[64:65] op_sel_hi:[1,0,1]
	v_pk_fma_f32 v[62:63], v[66:67], s[44:45], v[62:63] op_sel_hi:[1,0,1]
	v_pk_fma_f32 v[60:61], v[72:73], s[44:45], v[60:61] op_sel_hi:[1,0,1]
	v_pk_fma_f32 v[58:59], v[70:71], s[44:45], v[58:59] op_sel_hi:[1,0,1]
	v_pk_fma_f32 v[56:57], v[76:77], s[44:45], v[56:57] op_sel_hi:[1,0,1]
	v_pk_fma_f32 v[54:55], v[74:75], s[44:45], v[54:55] op_sel_hi:[1,0,1]
	v_pk_fma_f32 v[52:53], v[80:81], s[44:45], v[52:53] op_sel_hi:[1,0,1]
	v_pk_fma_f32 v[50:51], v[78:79], s[44:45], v[50:51] op_sel_hi:[1,0,1]
	global_store_dwordx4 v[100:101], v[62:65], off
	global_store_dwordx4 v[100:101], v[58:61], off offset:16
	global_store_dwordx4 v[100:101], v[54:57], off offset:512
	global_store_dwordx4 v[100:101], v[50:53], off offset:528
	global_load_dwordx2 v[66:67], v[86:87], off
	global_load_dwordx4 v[50:53], v[84:85], off
	global_load_dwordx4 v[54:57], v[84:85], off offset:16
	global_load_dwordx4 v[58:61], v[84:85], off offset:512
	global_load_dwordx4 v[62:65], v[84:85], off offset:528
	v_add_u32_e32 v68, 0xa0, v174
	v_ashrrev_i32_e32 v69, 31, v68
	v_lshlrev_b32_e32 v70, 1, v68
	v_ashrrev_i32_e32 v71, 31, v70
	v_lshlrev_b64 v[68:69], 13, v[68:69]
	v_lshl_add_u64 v[70:71], v[70:71], 2, s[22:23]
	v_lshl_add_u64 v[68:69], s[20:21], 0, v[68:69]
	v_lshl_add_u64 v[68:69], v[68:69], 0, v[172:173]
	s_waitcnt vmcnt(3)
	v_sub_f32_e32 v53, v53, v66
	v_sub_f32_e32 v52, v52, v66
	v_sub_f32_e32 v51, v51, v66
	v_sub_f32_e32 v50, v50, v66
	s_waitcnt vmcnt(2)
	v_sub_f32_e32 v57, v57, v66
	v_sub_f32_e32 v56, v56, v66
	v_sub_f32_e32 v55, v55, v66
	v_sub_f32_e32 v54, v54, v66
	s_waitcnt vmcnt(1)
	v_sub_f32_e32 v61, v61, v66
	v_sub_f32_e32 v60, v60, v66
	v_sub_f32_e32 v59, v59, v66
	v_sub_f32_e32 v58, v58, v66
	s_waitcnt vmcnt(0)
	v_sub_f32_e32 v65, v65, v66
	v_sub_f32_e32 v64, v64, v66
	v_sub_f32_e32 v63, v63, v66
	v_sub_f32_e32 v62, v62, v66
	v_pk_mul_f32 v[50:51], v[66:67], v[50:51] op_sel:[1,0]
	v_pk_mul_f32 v[52:53], v[66:67], v[52:53] op_sel:[1,0]
	v_pk_mul_f32 v[54:55], v[66:67], v[54:55] op_sel:[1,0]
	v_pk_mul_f32 v[56:57], v[66:67], v[56:57] op_sel:[1,0]
	v_pk_mul_f32 v[58:59], v[66:67], v[58:59] op_sel:[1,0]
	v_pk_mul_f32 v[60:61], v[66:67], v[60:61] op_sel:[1,0]
	v_pk_mul_f32 v[62:63], v[66:67], v[62:63] op_sel:[1,0]
	v_pk_mul_f32 v[64:65], v[66:67], v[64:65] op_sel:[1,0]
	v_pk_fma_f32 v[52:53], v[132:133], v[52:53], v[120:121]
	v_pk_fma_f32 v[50:51], v[130:131], v[50:51], v[118:119]
	v_pk_fma_f32 v[56:57], v[116:117], v[56:57], v[136:137]
	v_pk_fma_f32 v[54:55], v[114:115], v[54:55], v[134:135]
	v_pk_fma_f32 v[60:61], v[140:141], v[60:61], v[128:129]
	v_pk_fma_f32 v[58:59], v[138:139], v[58:59], v[126:127]
	v_pk_fma_f32 v[64:65], v[124:125], v[64:65], v[144:145]
	v_pk_fma_f32 v[62:63], v[122:123], v[62:63], v[142:143]
	v_pk_fma_f32 v[48:49], v[52:53], s[44:45], v[48:49] op_sel_hi:[1,0,1]
	v_pk_fma_f32 v[46:47], v[50:51], s[44:45], v[46:47] op_sel_hi:[1,0,1]
	v_pk_fma_f32 v[44:45], v[56:57], s[44:45], v[44:45] op_sel_hi:[1,0,1]
	v_pk_fma_f32 v[42:43], v[54:55], s[44:45], v[42:43] op_sel_hi:[1,0,1]
	v_pk_fma_f32 v[40:41], v[60:61], s[44:45], v[40:41] op_sel_hi:[1,0,1]
	v_pk_fma_f32 v[38:39], v[58:59], s[44:45], v[38:39] op_sel_hi:[1,0,1]
	v_pk_fma_f32 v[36:37], v[64:65], s[44:45], v[36:37] op_sel_hi:[1,0,1]
	v_pk_fma_f32 v[34:35], v[62:63], s[44:45], v[34:35] op_sel_hi:[1,0,1]
	global_store_dwordx4 v[84:85], v[46:49], off
	global_store_dwordx4 v[84:85], v[42:45], off offset:16
	global_store_dwordx4 v[84:85], v[38:41], off offset:512
	global_store_dwordx4 v[84:85], v[34:37], off offset:528
	global_load_dwordx2 v[50:51], v[70:71], off
	global_load_dwordx4 v[34:37], v[68:69], off
	global_load_dwordx4 v[38:41], v[68:69], off offset:16
	global_load_dwordx4 v[42:45], v[68:69], off offset:512
	global_load_dwordx4 v[46:49], v[68:69], off offset:528
	v_add_u32_e32 v52, 0xb0, v174
	v_ashrrev_i32_e32 v53, 31, v52
	v_lshlrev_b32_e32 v54, 1, v52
	v_ashrrev_i32_e32 v55, 31, v54
	v_lshlrev_b64 v[52:53], 13, v[52:53]
	v_lshl_add_u64 v[54:55], v[54:55], 2, s[22:23]
	v_lshl_add_u64 v[52:53], s[20:21], 0, v[52:53]
	v_lshl_add_u64 v[52:53], v[52:53], 0, v[172:173]
	s_waitcnt vmcnt(3)
	v_sub_f32_e32 v37, v37, v50
	v_sub_f32_e32 v36, v36, v50
	v_sub_f32_e32 v35, v35, v50
	v_sub_f32_e32 v34, v34, v50
	s_waitcnt vmcnt(2)
	v_sub_f32_e32 v41, v41, v50
	v_sub_f32_e32 v40, v40, v50
	v_sub_f32_e32 v39, v39, v50
	v_sub_f32_e32 v38, v38, v50
	s_waitcnt vmcnt(1)
	v_sub_f32_e32 v45, v45, v50
	v_sub_f32_e32 v44, v44, v50
	v_sub_f32_e32 v43, v43, v50
	v_sub_f32_e32 v42, v42, v50
	s_waitcnt vmcnt(0)
	v_sub_f32_e32 v49, v49, v50
	v_sub_f32_e32 v48, v48, v50
	v_sub_f32_e32 v47, v47, v50
	v_sub_f32_e32 v46, v46, v50
	v_pk_mul_f32 v[34:35], v[50:51], v[34:35] op_sel:[1,0]
	v_pk_mul_f32 v[36:37], v[50:51], v[36:37] op_sel:[1,0]
	v_pk_mul_f32 v[38:39], v[50:51], v[38:39] op_sel:[1,0]
	v_pk_mul_f32 v[40:41], v[50:51], v[40:41] op_sel:[1,0]
	v_pk_mul_f32 v[42:43], v[50:51], v[42:43] op_sel:[1,0]
	v_pk_mul_f32 v[44:45], v[50:51], v[44:45] op_sel:[1,0]
	v_pk_mul_f32 v[46:47], v[50:51], v[46:47] op_sel:[1,0]
	v_pk_mul_f32 v[48:49], v[50:51], v[48:49] op_sel:[1,0]
	v_pk_fma_f32 v[36:37], v[132:133], v[36:37], v[120:121]
	v_pk_fma_f32 v[34:35], v[130:131], v[34:35], v[118:119]
	v_pk_fma_f32 v[40:41], v[116:117], v[40:41], v[136:137]
	v_pk_fma_f32 v[38:39], v[114:115], v[38:39], v[134:135]
	v_pk_fma_f32 v[44:45], v[140:141], v[44:45], v[128:129]
	v_pk_fma_f32 v[42:43], v[138:139], v[42:43], v[126:127]
	v_pk_fma_f32 v[48:49], v[124:125], v[48:49], v[144:145]
	v_pk_fma_f32 v[46:47], v[122:123], v[46:47], v[142:143]
	v_pk_fma_f32 v[32:33], v[36:37], s[44:45], v[32:33] op_sel_hi:[1,0,1]
	v_pk_fma_f32 v[30:31], v[34:35], s[44:45], v[30:31] op_sel_hi:[1,0,1]
	v_pk_fma_f32 v[28:29], v[40:41], s[44:45], v[28:29] op_sel_hi:[1,0,1]
	v_pk_fma_f32 v[26:27], v[38:39], s[44:45], v[26:27] op_sel_hi:[1,0,1]
	v_pk_fma_f32 v[24:25], v[44:45], s[44:45], v[24:25] op_sel_hi:[1,0,1]
	v_pk_fma_f32 v[22:23], v[42:43], s[44:45], v[22:23] op_sel_hi:[1,0,1]
	v_pk_fma_f32 v[20:21], v[48:49], s[44:45], v[20:21] op_sel_hi:[1,0,1]
	v_pk_fma_f32 v[18:19], v[46:47], s[44:45], v[18:19] op_sel_hi:[1,0,1]
	global_store_dwordx4 v[68:69], v[30:33], off
	global_store_dwordx4 v[68:69], v[26:29], off offset:16
	global_store_dwordx4 v[68:69], v[22:25], off offset:512
	global_store_dwordx4 v[68:69], v[18:21], off offset:528
	global_load_dwordx2 v[34:35], v[54:55], off
	global_load_dwordx4 v[18:21], v[52:53], off
	global_load_dwordx4 v[22:25], v[52:53], off offset:16
	global_load_dwordx4 v[26:29], v[52:53], off offset:512
	global_load_dwordx4 v[30:33], v[52:53], off offset:528
	s_waitcnt vmcnt(3)
	v_sub_f32_e32 v21, v21, v34
	v_sub_f32_e32 v20, v20, v34
	v_sub_f32_e32 v19, v19, v34
	v_sub_f32_e32 v18, v18, v34
	s_waitcnt vmcnt(2)
	v_sub_f32_e32 v25, v25, v34
	v_sub_f32_e32 v24, v24, v34
	v_sub_f32_e32 v23, v23, v34
	v_sub_f32_e32 v22, v22, v34
	s_waitcnt vmcnt(1)
	v_sub_f32_e32 v29, v29, v34
	v_sub_f32_e32 v28, v28, v34
	v_sub_f32_e32 v27, v27, v34
	v_sub_f32_e32 v26, v26, v34
	s_waitcnt vmcnt(0)
	v_sub_f32_e32 v33, v33, v34
	v_sub_f32_e32 v32, v32, v34
	v_sub_f32_e32 v31, v31, v34
	v_sub_f32_e32 v30, v30, v34
	v_pk_mul_f32 v[18:19], v[34:35], v[18:19] op_sel:[1,0]
	v_pk_mul_f32 v[20:21], v[34:35], v[20:21] op_sel:[1,0]
	v_pk_mul_f32 v[22:23], v[34:35], v[22:23] op_sel:[1,0]
	v_pk_mul_f32 v[24:25], v[34:35], v[24:25] op_sel:[1,0]
	v_pk_mul_f32 v[26:27], v[34:35], v[26:27] op_sel:[1,0]
	v_pk_mul_f32 v[28:29], v[34:35], v[28:29] op_sel:[1,0]
	v_pk_mul_f32 v[30:31], v[34:35], v[30:31] op_sel:[1,0]
	v_pk_mul_f32 v[32:33], v[34:35], v[32:33] op_sel:[1,0]
	v_pk_fma_f32 v[20:21], v[132:133], v[20:21], v[120:121]
	v_pk_fma_f32 v[18:19], v[130:131], v[18:19], v[118:119]
	v_pk_fma_f32 v[24:25], v[116:117], v[24:25], v[136:137]
	v_pk_fma_f32 v[22:23], v[114:115], v[22:23], v[134:135]
	v_pk_fma_f32 v[28:29], v[140:141], v[28:29], v[128:129]
	v_pk_fma_f32 v[26:27], v[138:139], v[26:27], v[126:127]
	v_pk_fma_f32 v[32:33], v[124:125], v[32:33], v[144:145]
	v_pk_fma_f32 v[30:31], v[122:123], v[30:31], v[142:143]
	v_pk_fma_f32 v[16:17], v[20:21], s[44:45], v[16:17] op_sel_hi:[1,0,1]
	v_pk_fma_f32 v[14:15], v[18:19], s[44:45], v[14:15] op_sel_hi:[1,0,1]
	v_pk_fma_f32 v[12:13], v[24:25], s[44:45], v[12:13] op_sel_hi:[1,0,1]
	v_pk_fma_f32 v[10:11], v[22:23], s[44:45], v[10:11] op_sel_hi:[1,0,1]
	v_pk_fma_f32 v[8:9], v[28:29], s[44:45], v[8:9] op_sel_hi:[1,0,1]
	v_pk_fma_f32 v[6:7], v[26:27], s[44:45], v[6:7] op_sel_hi:[1,0,1]
	v_pk_fma_f32 v[4:5], v[32:33], s[44:45], v[4:5] op_sel_hi:[1,0,1]
	v_pk_fma_f32 v[2:3], v[30:31], s[44:45], v[2:3] op_sel_hi:[1,0,1]
	global_store_dwordx4 v[52:53], v[14:17], off
	global_store_dwordx4 v[52:53], v[10:13], off offset:16
	global_store_dwordx4 v[52:53], v[6:9], off offset:512
	global_store_dwordx4 v[52:53], v[2:5], off offset:528
	s_cbranch_vccnz .LBB0_1062
	s_andn2_b64 vcc, exec, s[18:19]
	s_cbranch_vccnz .LBB0_1061
	s_barrier
	s_branch .LBB0_1061

.LBB0_1943:
	s_cmp_lt_i32 s74, 17
	s_cselect_b64 s[26:27], -1, 0
	s_and_b64 s[0:1], s[26:27], s[6:7]
	s_andn2_b64 vcc, exec, s[0:1]
	s_cbranch_vccnz .LBB0_1969
	v_readlane_b32 s0, v254, 0
	v_mov_b32_e32 v102, v0
	v_readlane_b32 s1, v254, 1
	s_load_dword s1, s[0:1], 0xc0
	s_movk_i32 s4, 0x4000
	v_cmp_gt_i32_e32 vcc, s4, v102
	s_waitcnt lgkmcnt(0)
	s_abs_i32 s0, s1
	v_cvt_f32_u32_e32 v1, s0
	s_sub_i32 s3, 0, s0
	s_add_i32 s14, s1, 0x3fff
	s_abs_i32 s2, s14
	v_rcp_iflag_f32_e32 v1, v1
	s_nop 0
	v_mul_f32_e32 v1, 0x4f7ffffe, v1
	v_cvt_u32_f32_e32 v1, v1
	s_nop 0
	v_readfirstlane_b32 s5, v1
	s_mul_i32 s3, s3, s5
	s_mul_hi_u32 s3, s5, s3
	s_add_i32 s5, s5, s3
	s_mul_hi_u32 s3, s2, s5
	s_and_saveexec_b64 s[6:7], vcc
	s_cbranch_execz .LBB0_1957
	v_max_i32_e32 v1, 0x3e00, v102
	v_sub_u32_e32 v1, v1, v102
	s_movk_i32 s4, 0x1ff
	v_add_u32_e32 v1, 0x1ff, v1
	v_cmp_lt_u32_e32 vcc, s4, v1
	s_mov_b64 s[4:5], -1
	v_mov_b32_e32 v2, v102
	s_and_saveexec_b64 s[8:9], vcc
	s_cbranch_execz .LBB0_1954
	v_lshrrev_b32_e32 v1, 9, v1
	v_add_u32_e32 v2, -1, v1
	v_add_u32_e32 v103, 0x200, v102
	v_lshrrev_b32_e32 v3, 1, v2
	v_add_u32_e32 v4, 1, v3
	v_cmp_lt_u32_e32 vcc, 13, v2
	v_mov_b32_e32 v7, 0
	v_mov_b64_e32 v[2:3], v[102:103]
	s_and_saveexec_b64 s[10:11], vcc
	s_cbranch_execz .LBB0_1950
	v_readlane_b32 s36, v254, 30
	v_readlane_b32 s50, v254, 44
	v_readlane_b32 s51, v254, 45
	v_and_b32_e32 v5, -8, v4
	s_mov_b32 s4, 0
	v_lshrrev_b32_e32 v6, 5, v102
	v_mul_u32_u24_e32 v6, 0x90, v6
	v_and_b32_e32 v8, 31, v102
	v_lshl_add_u32 v6, v8, 2, v6
	s_mov_b64 s[12:13], 0
	v_mov_b64_e32 v[2:3], v[102:103]
	s_mov_b64 s[30:31], s[50:51]
	v_readlane_b32 s37, v254, 31
	v_readlane_b32 s38, v254, 32
	v_readlane_b32 s39, v254, 33
	v_readlane_b32 s40, v254, 34
	v_readlane_b32 s41, v254, 35
	v_readlane_b32 s42, v254, 36
	v_readlane_b32 s43, v254, 37
	v_readlane_b32 s44, v254, 38
	v_readlane_b32 s45, v254, 39
	v_readlane_b32 s46, v254, 40
	v_readlane_b32 s47, v254, 41
	v_readlane_b32 s48, v254, 42
	v_readlane_b32 s49, v254, 43
.LBB0_1948:
	v_ashrrev_i32_e32 v9, 31, v3
	v_mov_b32_e32 v8, v3
	v_ashrrev_i32_e32 v11, 31, v2
	v_mov_b32_e32 v10, v2
	v_add_u32_e32 v12, 0x400, v2
	v_add_u32_e32 v14, 0x400, v3
	v_add_u32_e32 v16, 0x800, v2
	v_add_u32_e32 v18, 0x800, v3
	v_add_u32_e32 v20, 0xc00, v2
	v_add_u32_e32 v22, 0xc00, v3
	v_add_u32_e32 v24, 0x1000, v2
	v_add_u32_e32 v26, 0x1000, v3
	v_add_u32_e32 v28, 0x1400, v2
	v_add_u32_e32 v30, 0x1400, v3
	v_add_u32_e32 v32, 0x1800, v2
	v_add_u32_e32 v34, 0x1800, v3
	v_add_u32_e32 v36, 0x1c00, v2
	v_add_u32_e32 v38, 0x1c00, v3
	v_lshl_add_u64 v[10:11], v[10:11], 2, s[30:31]
	v_lshl_add_u64 v[8:9], v[8:9], 2, s[30:31]
	v_ashrrev_i32_e32 v15, 31, v14
	v_ashrrev_i32_e32 v13, 31, v12
	v_ashrrev_i32_e32 v19, 31, v18
	v_ashrrev_i32_e32 v17, 31, v16
	v_ashrrev_i32_e32 v23, 31, v22
	v_ashrrev_i32_e32 v21, 31, v20
	v_ashrrev_i32_e32 v27, 31, v26
	v_ashrrev_i32_e32 v25, 31, v24
	v_ashrrev_i32_e32 v31, 31, v30
	v_ashrrev_i32_e32 v29, 31, v28
	v_ashrrev_i32_e32 v35, 31, v34
	v_ashrrev_i32_e32 v33, 31, v32
	v_ashrrev_i32_e32 v39, 31, v38
	v_ashrrev_i32_e32 v37, 31, v36
	v_lshl_add_u64 v[12:13], v[12:13], 2, s[30:31]
	v_lshl_add_u64 v[14:15], v[14:15], 2, s[30:31]
	v_lshl_add_u64 v[16:17], v[16:17], 2, s[30:31]
	v_lshl_add_u64 v[18:19], v[18:19], 2, s[30:31]
	v_lshl_add_u64 v[20:21], v[20:21], 2, s[30:31]
	v_lshl_add_u64 v[22:23], v[22:23], 2, s[30:31]
	v_lshl_add_u64 v[24:25], v[24:25], 2, s[30:31]
	v_lshl_add_u64 v[26:27], v[26:27], 2, s[30:31]
	v_lshl_add_u64 v[28:29], v[28:29], 2, s[30:31]
	v_lshl_add_u64 v[30:31], v[30:31], 2, s[30:31]
	v_lshl_add_u64 v[32:33], v[32:33], 2, s[30:31]
	v_lshl_add_u64 v[34:35], v[34:35], 2, s[30:31]
	v_lshl_add_u64 v[36:37], v[36:37], 2, s[30:31]
	v_lshl_add_u64 v[38:39], v[38:39], 2, s[30:31]
	global_load_dword v40, v[10:11], off
	global_load_dword v41, v[8:9], off
	global_load_dword v42, v[12:13], off
	global_load_dword v43, v[14:15], off
	global_load_dword v44, v[16:17], off
	global_load_dword v45, v[18:19], off
	global_load_dword v46, v[20:21], off
	global_load_dword v47, v[22:23], off
	global_load_dword v48, v[24:25], off
	global_load_dword v49, v[26:27], off
	global_load_dword v50, v[28:29], off
	global_load_dword v51, v[30:31], off
	global_load_dword v52, v[32:33], off
	global_load_dword v53, v[34:35], off
	global_load_dword v54, v[36:37], off
	global_load_dword v8, v[38:39], off
	v_add_u32_e32 v5, -8, v5
	s_add_i32 s4, s4, 16
	v_cmp_eq_u32_e32 vcc, 0, v5
	v_add_u32_e32 v3, 0x2000, v3
	v_add_u32_e32 v2, 0x2000, v2
	v_mov_b32_e32 v7, s4
	s_or_b64 s[12:13], vcc, s[12:13]
	s_waitcnt vmcnt(0)
	ds_write2st64_b32 v6, v40, v41 offset1:9
	ds_write2st64_b32 v6, v42, v43 offset0:18 offset1:27
	ds_write2st64_b32 v6, v44, v45 offset0:36 offset1:45
	ds_write2st64_b32 v6, v46, v47 offset0:54 offset1:63
	ds_write2st64_b32 v6, v48, v49 offset0:72 offset1:81
	ds_write2st64_b32 v6, v50, v51 offset0:90 offset1:99
	ds_write2st64_b32 v6, v52, v53 offset0:108 offset1:117
	ds_write2st64_b32 v6, v54, v8 offset0:126 offset1:135
	v_add_u32_e32 v6, 0x9000, v6
	s_andn2_b64 exec, exec, s[12:13]
	s_cbranch_execnz .LBB0_1948
	s_or_b64 exec, exec, s[12:13]
.LBB0_1950:
	s_or_b64 exec, exec, s[10:11]
	v_and_b32_e32 v4, 7, v4
	v_cmp_ne_u32_e32 vcc, 0, v4
	s_and_saveexec_b64 s[10:11], vcc
	v_readlane_b32 s36, v254, 30
	v_readlane_b32 s50, v254, 44
	v_readlane_b32 s51, v254, 45
	v_readlane_b32 s37, v254, 31
	v_readlane_b32 s38, v254, 32
	v_readlane_b32 s39, v254, 33
	v_readlane_b32 s40, v254, 34
	v_readlane_b32 s41, v254, 35
	v_readlane_b32 s42, v254, 36
	v_readlane_b32 s43, v254, 37
	v_readlane_b32 s44, v254, 38
	v_readlane_b32 s45, v254, 39
	v_readlane_b32 s46, v254, 40
	v_readlane_b32 s47, v254, 41
	v_readlane_b32 s48, v254, 42
	v_readlane_b32 s49, v254, 43
	s_cbranch_execz .LBB0_1953
	v_mul_u32_u24_e32 v5, 0x900, v7
	v_lshrrev_b32_e32 v6, 5, v102
	v_mul_u32_u24_e32 v6, 0x90, v6
	v_and_b32_e32 v8, 31, v102
	v_lshl_add_u32 v6, v8, 2, v6
	s_mov_b64 s[30:31], s[50:51]
	v_add3_u32 v5, v5, v6, 0
	s_mov_b64 s[12:13], 0
.LBB0_1952:
	v_ashrrev_i32_e32 v9, 31, v2
	v_mov_b32_e32 v8, v2
	v_ashrrev_i32_e32 v7, 31, v3
	v_mov_b32_e32 v6, v3
	v_lshl_add_u64 v[8:9], v[8:9], 2, s[30:31]
	v_lshl_add_u64 v[6:7], v[6:7], 2, s[30:31]
	global_load_dword v10, v[8:9], off
	global_load_dword v11, v[6:7], off
	v_add_u32_e32 v4, -1, v4
	v_cmp_eq_u32_e32 vcc, 0, v4
	v_add_u32_e32 v3, 0x400, v3
	v_add_u32_e32 v2, 0x400, v2
	s_or_b64 s[12:13], vcc, s[12:13]
	s_waitcnt vmcnt(0)
	ds_write2st64_b32 v5, v10, v11 offset1:9
	v_add_u32_e32 v5, 0x1200, v5
	s_andn2_b64 exec, exec, s[12:13]
	s_cbranch_execnz .LBB0_1952

.LBB0_1954:
	s_or_b64 exec, exec, s[8:9]
	s_and_b64 exec, exec, s[4:5]
	s_cbranch_execz .LBB0_1957
	v_readlane_b32 s36, v254, 30
	v_ashrrev_i32_e32 v3, 31, v2
	v_readlane_b32 s50, v254, 44
	v_readlane_b32 s51, v254, 45
	v_add_u32_e32 v1, 0xfffffe00, v2
	v_lshrrev_b32_e32 v4, 5, v2
	v_mul_u32_u24_e32 v4, 0x90, v4
	v_and_b32_e32 v5, 31, v2
	v_lshl_add_u32 v4, v5, 2, v4
	v_lshl_add_u64 v[2:3], v[2:3], 2, s[50:51]
	s_mov_b64 s[8:9], 0
	s_mov_b64 s[10:11], 0x800
	s_movk_i32 s4, 0x3dff
	v_readlane_b32 s37, v254, 31
	v_readlane_b32 s38, v254, 32
	v_readlane_b32 s39, v254, 33
	v_readlane_b32 s40, v254, 34
	v_readlane_b32 s41, v254, 35
	v_readlane_b32 s42, v254, 36
	v_readlane_b32 s43, v254, 37
	v_readlane_b32 s44, v254, 38
	v_readlane_b32 s45, v254, 39
	v_readlane_b32 s46, v254, 40
	v_readlane_b32 s47, v254, 41
	v_readlane_b32 s48, v254, 42
	v_readlane_b32 s49, v254, 43
.LBB0_1956:
	global_load_dword v5, v[2:3], off
	v_add_u32_e32 v1, 0x200, v1
	v_cmp_lt_i32_e32 vcc, s4, v1
	v_lshl_add_u64 v[2:3], v[2:3], 0, s[10:11]
	s_or_b64 s[8:9], vcc, s[8:9]
	s_waitcnt vmcnt(0)
	ds_write_b32 v4, v5
	v_add_u32_e32 v4, 0x900, v4
	s_andn2_b64 exec, exec, s[8:9]
	s_cbranch_execnz .LBB0_1956
.LBB0_1957:
	s_or_b64 exec, exec, s[6:7]
	s_ashr_i32 s8, s14, 31
	s_ashr_i32 s1, s1, 31
	v_cmp_gt_i32_e64 s[6:7], 8, v102
	v_lshl_add_u32 v1, v102, 2, 0
	s_and_saveexec_b64 s[4:5], s[6:7]
	v_add_u32_e32 v2, 0x14000, v1
	v_mov_b32_e32 v3, 0
	ds_write_b32 v2, v3
	s_or_b64 exec, exec, s[4:5]
	s_mul_i32 s4, s3, s0
	s_sub_i32 s2, s2, s4
	s_xor_b32 s1, s8, s1
	s_add_i32 s4, s3, 1
	s_sub_i32 s5, s2, s0
	s_cmp_ge_u32 s2, s0
	s_cselect_b32 s3, s4, s3
	s_cselect_b32 s2, s5, s2
	s_add_i32 s4, s3, 1
	s_cmp_ge_u32 s2, s0
	s_cselect_b32 s0, s4, s3
	s_xor_b32 s0, s0, s1
	s_sub_i32 s0, s0, s1
	s_mul_i32 s1, s0, s96
	v_ashrrev_i32_e32 v2, 6, v102
	s_add_i32 s0, s1, s0
	s_min_i32 s0, s0, 0x4000
	v_add_u32_e32 v104, s1, v2
	v_cmp_gt_i32_e32 vcc, s0, v104
	s_waitcnt vmcnt(0) lgkmcnt(0)
	s_barrier
	s_and_saveexec_b64 s[30:31], vcc
	s_cbranch_execz .LBB0_1966
	v_mbcnt_lo_u32_b32 v4, -1, 0
	v_mbcnt_hi_u32_b32 v4, -1, v4
	v_and_b32_e32 v5, 64, v4
	v_add_u32_e32 v5, 64, v5
	v_xor_b32_e32 v6, 1, v4
	v_cmp_lt_i32_e32 vcc, v6, v5
	v_readlane_b32 s8, v254, 30
	v_readlane_b32 s9, v254, 31
	v_cndmask_b32_e32 v6, v4, v6, vcc
	v_lshlrev_b32_e32 v103, 2, v6
	v_xor_b32_e32 v6, 2, v4
	v_cmp_lt_i32_e32 vcc, v6, v5
	v_readlane_b32 s10, v254, 32
	v_readlane_b32 s11, v254, 33
	v_cndmask_b32_e32 v6, v4, v6, vcc
	v_lshlrev_b32_e32 v134, 2, v6
	v_xor_b32_e32 v6, 4, v4
	v_cmp_lt_i32_e32 vcc, v6, v5
	v_readlane_b32 s12, v254, 34
	v_readlane_b32 s13, v254, 35
	v_cndmask_b32_e32 v6, v4, v6, vcc
	v_lshlrev_b32_e32 v135, 2, v6
	v_xor_b32_e32 v6, 8, v4
	v_cmp_lt_i32_e32 vcc, v6, v5
	v_and_b32_e32 v3, 63, v102
	v_readlane_b32 s14, v254, 36
	v_cndmask_b32_e32 v6, v4, v6, vcc
	v_lshlrev_b32_e32 v136, 2, v6
	v_xor_b32_e32 v6, 16, v4
	v_cmp_lt_i32_e32 vcc, v6, v5
	v_readlane_b32 s15, v254, 37
	s_mov_b64 s[8:9], s[12:13]
	v_cndmask_b32_e32 v6, v4, v6, vcc
	v_lshlrev_b32_e32 v137, 2, v6
	v_xor_b32_e32 v6, 32, v4
	v_cmp_lt_i32_e32 vcc, v6, v5
	v_lshlrev_b32_e32 v40, 4, v3
	v_mov_b32_e32 v41, 0
	v_cndmask_b32_e32 v4, v4, v6, vcc
	s_mov_b64 s[10:11], s[14:15]
	v_lshlrev_b32_e32 v138, 2, v4
	v_lshl_add_u64 v[4:5], s[8:9], 0, v[40:41]
	s_mov_b64 s[2:3], 0x2000
	v_lshl_add_u64 v[6:7], s[10:11], 0, v[40:41]
	v_lshl_add_u64 v[106:107], v[4:5], 0, s[2:3]
	v_lshl_add_u64 v[108:109], v[6:7], 0, s[2:3]
	s_mov_b64 s[2:3], 0x3000
	v_lshl_add_u64 v[110:111], v[4:5], 0, s[2:3]
	v_lshl_add_u64 v[112:113], v[6:7], 0, s[2:3]
	s_mov_b64 s[2:3], 0x3400
	s_add_u32 s34, s72, 0x1069000
	v_lshl_add_u64 v[114:115], v[4:5], 0, s[2:3]
	v_lshl_add_u64 v[116:117], v[6:7], 0, s[2:3]
	s_mov_b64 s[2:3], 0x3800
	s_addc_u32 s35, s73, 0
	v_lshl_add_u64 v[118:119], v[4:5], 0, s[2:3]
	v_lshl_add_u64 v[120:121], v[6:7], 0, s[2:3]
	s_mov_b64 s[2:3], 0x3c00
	s_add_u32 s36, s72, 0x1000000
	v_lshl_add_u64 v[122:123], v[4:5], 0, s[2:3]
	v_lshlrev_b32_e32 v4, 5, v102
	v_lshlrev_b32_e32 v5, 4, v102
	s_addc_u32 s37, s73, 0
	v_ashrrev_i32_e32 v105, 31, v104
	v_and_b32_e32 v4, 0x780, v4
	v_and_b32_e32 v5, 48, v5
	s_add_u32 s38, s72, 0x1020000
	v_lshlrev_b32_e32 v2, 1, v2
	v_lshlrev_b64 v[128:129], 13, v[104:105]
	v_lshlrev_b64 v[130:131], 11, v[104:105]
	v_lshl_add_u64 v[124:125], v[6:7], 0, s[2:3]
	v_cmp_eq_u32_e64 s[8:9], 0, v3
	v_mul_u32_u24_e32 v139, 0x90, v3
	s_addc_u32 s39, s73, 0
	v_lshl_add_u32 v126, s1, 1, v2
	v_or_b32_e32 v128, v128, v40
	v_or3_b32 v130, v130, v4, v5
	s_mov_b64 s[44:45], 0
	v_mov_b32_e32 v105, 0x3727c5ac
	s_mov_b32 s1, 0xf800000
	v_mov_b32_e32 v140, 0x260
	s_mov_b32 s2, 0x700001
	s_movk_i32 s3, 0xff82
	s_mov_b32 s28, 0x1010101
	s_mov_b32 s29, 0x26b00000
	v_mov_b32_e32 v141, 1
	s_mov_b32 s33, 0xff61b1e6
	s_add_i32 s40, 0, 0x14000
	s_mov_b64 s[46:47], 0x10000
	s_mov_b64 s[48:49], 0x4000
	v_mov_b32_e32 v142, 0xff61b1e6
	v_readlane_b32 s16, v254, 38
	v_readlane_b32 s17, v254, 39
	v_readlane_b32 s18, v254, 40
	v_readlane_b32 s19, v254, 41
	v_readlane_b32 s20, v254, 42
	v_readlane_b32 s21, v254, 43
	v_readlane_b32 s22, v254, 44
	v_readlane_b32 s23, v254, 45
	s_branch .LBB0_1962

.LBB0_1964:
	s_or_b64 exec, exec, s[4:5]
	v_mov_b32_e32 v19, v20
	v_mov_b32_e32 v23, v21
	v_mov_b32_e32 v20, v132
	v_mov_b32_e32 v21, v38
	v_pk_mul_f32 v[18:19], v[18:19], v[40:41] op_sel_hi:[1,0]
	v_pk_mul_f32 v[2:3], v[2:3], v[40:41] op_sel_hi:[1,0]
	v_pk_mul_f32 v[20:21], v[20:21], v[40:41] op_sel_hi:[1,0]
	s_waitcnt vmcnt(13)
	v_pk_fma_f32 v[18:19], v[94:95], v[18:19], v[98:99]
	v_pk_mul_f32 v[4:5], v[4:5], v[40:41] op_sel_hi:[1,0]
	s_waitcnt vmcnt(6)
	v_pk_fma_f32 v[2:3], v[62:63], v[2:3], v[66:67]
	v_pk_mul_f32 v[14:15], v[14:15], v[40:41] op_sel_hi:[1,0]
	v_pk_fma_f32 v[20:21], v[96:97], v[20:21], v[100:101]
	v_mov_b32_e32 v38, v133
	v_pk_mul_f32 v[22:23], v[22:23], v[40:41] op_sel_hi:[1,0]
	v_pk_fma_f32 v[4:5], v[64:65], v[4:5], v[68:69]
	v_pk_mul_f32 v[6:7], v[6:7], v[40:41] op_sel_hi:[1,0]
	v_pk_mul_f32 v[16:17], v[16:17], v[40:41] op_sel_hi:[1,0]
	s_waitcnt vmcnt(0)
	v_pk_fma_f32 v[14:15], v[34:35], v[14:15], v[42:43]
	v_max_f32_e64 v34, |v18|, |v2|
	v_max_f32_e64 v35, |v19|, |v3|
	v_pk_mul_f32 v[24:25], v[38:39], v[40:41] op_sel_hi:[1,0]
	v_pk_fma_f32 v[22:23], v[86:87], v[22:23], v[90:91]
	v_pk_mul_f32 v[8:9], v[8:9], v[40:41] op_sel_hi:[1,0]
	v_pk_fma_f32 v[6:7], v[54:55], v[6:7], v[58:59]
	v_pk_mul_f32 v[12:13], v[12:13], v[40:41] op_sel_hi:[1,0]
	v_pk_mul_f32 v[10:11], v[10:11], v[40:41] op_sel_hi:[1,0]
	v_pk_fma_f32 v[16:17], v[36:37], v[16:17], v[44:45]
	v_max3_f32 v34, v34, 0, v35
	v_max_f32_e64 v35, |v20|, |v4|
	v_max_f32_e64 v36, |v21|, |v5|
	v_pk_fma_f32 v[24:25], v[88:89], v[24:25], v[92:93]
	v_pk_mul_f32 v[26:27], v[26:27], v[40:41] op_sel_hi:[1,0]
	v_pk_fma_f32 v[8:9], v[56:57], v[8:9], v[60:61]
	v_pk_fma_f32 v[12:13], v[48:49], v[12:13], v[52:53]
	v_pk_fma_f32 v[10:11], v[46:47], v[10:11], v[50:51]
	v_max3_f32 v34, v34, v35, v36
	v_max_f32_e64 v35, |v22|, |v6|
	v_max_f32_e64 v36, |v23|, |v7|
	ds_read_b128 v[50:53], v139
	v_pk_mul_f32 v[28:29], v[28:29], v[40:41] op_sel_hi:[1,0]
	v_pk_fma_f32 v[26:27], v[78:79], v[26:27], v[82:83]
	v_max3_f32 v34, v34, v35, v36
	v_max_f32_e64 v35, |v24|, |v8|
	v_max_f32_e64 v36, |v25|, |v9|
	ds_read_b128 v[54:57], v139 offset:16
	ds_read_b128 v[58:61], v139 offset:32
	ds_read_b128 v[62:65], v139 offset:48
	v_pk_fma_f32 v[28:29], v[80:81], v[28:29], v[84:85]
	v_pk_mul_f32 v[30:31], v[30:31], v[40:41] op_sel_hi:[1,0]
	v_max3_f32 v34, v34, v35, v36
	v_max_f32_e64 v35, |v26|, |v10|
	v_max_f32_e64 v36, |v27|, |v11|
	v_pk_mul_f32 v[32:33], v[32:33], v[40:41] op_sel_hi:[1,0]
	v_pk_fma_f32 v[30:31], v[70:71], v[30:31], v[74:75]
	v_max3_f32 v34, v34, v35, v36
	v_max_f32_e64 v35, |v28|, |v12|
	v_max_f32_e64 v36, |v29|, |v13|
	v_pk_fma_f32 v[32:33], v[72:73], v[32:33], v[76:77]
	v_max3_f32 v34, v34, v35, v36
	v_max_f32_e64 v35, |v30|, |v14|
	v_max_f32_e64 v36, |v31|, |v15|
	v_max3_f32 v34, v34, v35, v36
	v_max_f32_e64 v35, |v32|, |v16|
	v_max_f32_e64 v36, |v33|, |v17|
	s_waitcnt lgkmcnt(3)
	v_fma_f32 v49, v18, v52, 0
	v_fma_f32 v48, v18, v53, 0
	s_waitcnt lgkmcnt(2)
	v_fma_f32 v47, v18, v54, 0
	v_fma_f32 v46, v18, v55, 0
	v_max3_f32 v34, v34, v35, v36
	s_waitcnt lgkmcnt(1)
	v_fmac_f32_e32 v49, v19, v60
	v_fmac_f32_e32 v48, v19, v61
	s_waitcnt lgkmcnt(0)
	v_fmac_f32_e32 v47, v19, v62
	ds_read_b128 v[52:55], v139 offset:64
	v_fmac_f32_e32 v46, v19, v63
	ds_read_b128 v[60:63], v139 offset:80
	v_bfe_u32 v35, v34, 23, 8
	v_and_b32_e32 v34, 0x7fffff, v34
	v_cmp_gt_u32_e32 vcc, s2, v34
	v_fma_f32 v45, v18, v56, 0
	v_fma_f32 v44, v18, v57, 0
	v_cndmask_b32_e64 v34, -2, -3, vcc
	v_add3_u32 v34, v35, v34, s3
	v_fmac_f32_e32 v45, v19, v64
	v_fmac_f32_e32 v44, v19, v65
	v_max_i32_e32 v34, 0xffffff88, v34
	s_waitcnt lgkmcnt(1)
	v_fmac_f32_e32 v49, v20, v54
	v_fmac_f32_e32 v48, v20, v55
	s_waitcnt lgkmcnt(0)
	v_fmac_f32_e32 v47, v20, v60
	v_fmac_f32_e32 v46, v20, v61
	v_fmac_f32_e32 v45, v20, v62
	v_fmac_f32_e32 v44, v20, v63
	ds_read_b128 v[54:57], v139 offset:96
	ds_read_b128 v[60:63], v139 offset:112
	v_add_u32_e32 v34, 0x7f, v34
	v_pk_fma_f32 v[50:51], v[18:19], v[50:51], 0 op_sel_hi:[0,1,0]
	v_lshlrev_b32_e32 v42, 23, v34
	v_mul_lo_u32 v40, v34, s28
	v_cvt_scalef32_2xpk16_fp6_f32 v[34:39], v[18:33], v[2:17], v42
	v_pk_fma_f32 v[18:19], v[18:19], v[58:59], v[50:51] op_sel:[1,0,0]
	s_waitcnt lgkmcnt(1)
	v_fmac_f32_e32 v49, v21, v56
	v_pk_fma_f32 v[18:19], v[20:21], v[52:53], v[18:19] op_sel_hi:[0,1,1]
	v_pk_fma_f32 v[84:85], v[20:21], v[54:55], v[18:19] op_sel:[1,0,0]
	v_fmac_f32_e32 v48, v21, v57
	ds_read_b128 v[50:53], v139 offset:9216
	ds_read_b128 v[54:57], v139 offset:9232
	s_waitcnt lgkmcnt(2)
	v_fmac_f32_e32 v47, v21, v60
	v_fmac_f32_e32 v46, v21, v61
	v_fmac_f32_e32 v45, v21, v62
	v_fmac_f32_e32 v44, v21, v63
	s_waitcnt lgkmcnt(1)
	v_fmac_f32_e32 v49, v22, v52
	v_fmac_f32_e32 v48, v22, v53
	s_waitcnt lgkmcnt(0)
	v_fmac_f32_e32 v47, v22, v54
	ds_read_b128 v[18:21], v139 offset:9248
	v_fmac_f32_e32 v46, v22, v55
	ds_read_b128 v[52:55], v139 offset:9264
	v_fmac_f32_e32 v45, v22, v56
	v_fmac_f32_e32 v44, v22, v57
	ds_read_b128 v[56:59], v139 offset:9280
	ds_read_b128 v[60:63], v139 offset:9296
	s_waitcnt lgkmcnt(3)
	v_fmac_f32_e32 v49, v23, v20
	v_fmac_f32_e32 v48, v23, v21
	s_waitcnt lgkmcnt(2)
	v_fmac_f32_e32 v47, v23, v52
	v_fmac_f32_e32 v46, v23, v53
	v_fmac_f32_e32 v45, v23, v54
	v_fmac_f32_e32 v44, v23, v55
	s_waitcnt lgkmcnt(1)
	v_fmac_f32_e32 v49, v24, v58
	v_fmac_f32_e32 v48, v24, v59
	s_waitcnt lgkmcnt(0)
	v_fmac_f32_e32 v47, v24, v60
	ds_read_b128 v[52:55], v139 offset:9312
	v_fmac_f32_e32 v46, v24, v61
	ds_read_b128 v[58:61], v139 offset:9328
	v_fmac_f32_e32 v45, v24, v62
	v_fmac_f32_e32 v44, v24, v63
	ds_read_b128 v[62:65], v139 offset:18432
	ds_read_b128 v[66:69], v139 offset:18448
	s_waitcnt lgkmcnt(3)
	v_fmac_f32_e32 v49, v25, v54
	v_fmac_f32_e32 v48, v25, v55
	s_waitcnt lgkmcnt(2)
	v_fmac_f32_e32 v47, v25, v58
	v_fmac_f32_e32 v46, v25, v59
	v_fmac_f32_e32 v45, v25, v60
	v_fmac_f32_e32 v44, v25, v61
	s_waitcnt lgkmcnt(1)
	v_fmac_f32_e32 v49, v26, v64
	v_fmac_f32_e32 v48, v26, v65
	s_waitcnt lgkmcnt(0)
	v_fmac_f32_e32 v47, v26, v66
	ds_read_b128 v[58:61], v139 offset:18464
	v_fmac_f32_e32 v46, v26, v67
	ds_read_b128 v[64:67], v139 offset:18480
	v_fmac_f32_e32 v45, v26, v68
	v_fmac_f32_e32 v44, v26, v69
	ds_read_b128 v[68:71], v139 offset:18496
	ds_read_b128 v[72:75], v139 offset:18512
	s_waitcnt lgkmcnt(3)
	v_fmac_f32_e32 v49, v27, v60
	v_fmac_f32_e32 v48, v27, v61
	s_waitcnt lgkmcnt(2)
	v_fmac_f32_e32 v47, v27, v64
	v_fmac_f32_e32 v46, v27, v65
	v_fmac_f32_e32 v45, v27, v66
	v_fmac_f32_e32 v44, v27, v67
	s_waitcnt lgkmcnt(1)
	v_fmac_f32_e32 v49, v28, v70
	v_fmac_f32_e32 v48, v28, v71
	s_waitcnt lgkmcnt(0)
	v_fmac_f32_e32 v47, v28, v72
	ds_read_b128 v[64:67], v139 offset:18528
	v_fmac_f32_e32 v46, v28, v73
	ds_read_b128 v[70:73], v139 offset:18544
	v_fmac_f32_e32 v45, v28, v74
	v_fmac_f32_e32 v44, v28, v75
	ds_read_b128 v[74:77], v139 offset:27648
	ds_read_b128 v[78:81], v139 offset:27664
	s_waitcnt lgkmcnt(3)
	v_fmac_f32_e32 v49, v29, v66
	v_fmac_f32_e32 v48, v29, v67
	s_waitcnt lgkmcnt(2)
	v_fmac_f32_e32 v47, v29, v70
	v_fmac_f32_e32 v46, v29, v71
	v_pk_fma_f32 v[20:21], v[22:23], v[50:51], v[84:85] op_sel_hi:[0,1,1]
	v_fmac_f32_e32 v45, v29, v72
	v_fmac_f32_e32 v44, v29, v73
	s_waitcnt lgkmcnt(1)
	v_fmac_f32_e32 v49, v30, v76
	v_fmac_f32_e32 v48, v30, v77
	s_waitcnt lgkmcnt(0)
	v_fmac_f32_e32 v47, v30, v78
	ds_read_b128 v[70:73], v139 offset:27680
	v_fmac_f32_e32 v46, v30, v79
	ds_read_b128 v[76:79], v139 offset:27696
	v_pk_fma_f32 v[18:19], v[22:23], v[18:19], v[20:21] op_sel:[1,0,0]
	v_fmac_f32_e32 v45, v30, v80
	v_pk_fma_f32 v[18:19], v[24:25], v[56:57], v[18:19] op_sel_hi:[0,1,1]
	v_pk_fma_f32 v[18:19], v[24:25], v[52:53], v[18:19] op_sel:[1,0,0]
	v_fmac_f32_e32 v44, v30, v81
	v_pk_fma_f32 v[18:19], v[26:27], v[62:63], v[18:19] op_sel_hi:[0,1,1]
	v_pk_fma_f32 v[18:19], v[26:27], v[58:59], v[18:19] op_sel:[1,0,0]
	s_waitcnt lgkmcnt(0)
	v_fmac_f32_e32 v47, v31, v76
	v_fmac_f32_e32 v46, v31, v77
	v_fmac_f32_e32 v45, v31, v78
	v_fmac_f32_e32 v44, v31, v79
	ds_read_b128 v[76:79], v139 offset:27712
	ds_read_b128 v[80:83], v139 offset:27728
	v_pk_fma_f32 v[18:19], v[28:29], v[68:69], v[18:19] op_sel_hi:[0,1,1]
	v_pk_fma_f32 v[18:19], v[28:29], v[64:65], v[18:19] op_sel:[1,0,0]
	ds_read_b128 v[22:25], v139 offset:27760
	v_pk_fma_f32 v[18:19], v[30:31], v[74:75], v[18:19] op_sel_hi:[0,1,1]
	v_pk_fma_f32 v[18:19], v[30:31], v[70:71], v[18:19] op_sel:[1,0,0]
	v_fmac_f32_e32 v49, v31, v72
	s_waitcnt lgkmcnt(2)
	v_pk_fma_f32 v[74:75], v[32:33], v[76:77], v[18:19] op_sel_hi:[0,1,1]
	ds_read_b128 v[18:21], v139 offset:27744
	v_fmac_f32_e32 v48, v31, v73
	v_fmac_f32_e32 v49, v32, v78
	v_fmac_f32_e32 v48, v32, v79
	s_waitcnt lgkmcnt(2)
	v_fmac_f32_e32 v47, v32, v80
	v_fmac_f32_e32 v46, v32, v81
	ds_read_b128 v[26:29], v139 offset:36864
	s_waitcnt lgkmcnt(1)
	v_fmac_f32_e32 v49, v33, v20
	v_fmac_f32_e32 v48, v33, v21
	v_fmac_f32_e32 v47, v33, v22
	v_fmac_f32_e32 v46, v33, v23
	ds_read_b128 v[20:23], v139 offset:36880
	v_fmac_f32_e32 v45, v32, v82
	v_fmac_f32_e32 v44, v32, v83
	v_fmac_f32_e32 v45, v33, v24
	v_fmac_f32_e32 v44, v33, v25
	s_waitcnt lgkmcnt(1)
	v_fmac_f32_e32 v49, v2, v28
	v_fmac_f32_e32 v48, v2, v29
	ds_read_b128 v[28:31], v139 offset:36896
	ds_read_b128 v[50:53], v139 offset:36912
	s_waitcnt lgkmcnt(2)
	v_fmac_f32_e32 v47, v2, v20
	v_fmac_f32_e32 v46, v2, v21
	v_fmac_f32_e32 v45, v2, v22
	v_fmac_f32_e32 v44, v2, v23
	ds_read_b128 v[20:23], v139 offset:36928
	ds_read_b128 v[54:57], v139 offset:36944
	s_waitcnt lgkmcnt(3)
	v_fmac_f32_e32 v49, v3, v30
	v_fmac_f32_e32 v48, v3, v31
	s_waitcnt lgkmcnt(2)
	v_fmac_f32_e32 v47, v3, v50
	v_fmac_f32_e32 v46, v3, v51
	v_fmac_f32_e32 v45, v3, v52
	v_fmac_f32_e32 v44, v3, v53
	s_waitcnt lgkmcnt(1)
	v_fmac_f32_e32 v49, v4, v22
	v_fmac_f32_e32 v48, v4, v23
	ds_read_b128 v[22:25], v139 offset:36960
	ds_read_b128 v[50:53], v139 offset:36976
	s_waitcnt lgkmcnt(2)
	v_fmac_f32_e32 v47, v4, v54
	v_fmac_f32_e32 v46, v4, v55
	v_fmac_f32_e32 v45, v4, v56
	v_fmac_f32_e32 v44, v4, v57
	ds_read_b128 v[54:57], v139 offset:46080
	ds_read_b128 v[58:61], v139 offset:46096
	s_waitcnt lgkmcnt(3)
	v_fmac_f32_e32 v49, v5, v24
	v_fmac_f32_e32 v48, v5, v25
	s_waitcnt lgkmcnt(2)
	v_fmac_f32_e32 v47, v5, v50
	v_fmac_f32_e32 v46, v5, v51
	v_fmac_f32_e32 v45, v5, v52
	v_fmac_f32_e32 v44, v5, v53
	s_waitcnt lgkmcnt(1)
	v_fmac_f32_e32 v49, v6, v56
	v_fmac_f32_e32 v48, v6, v57
	s_waitcnt lgkmcnt(0)
	v_fmac_f32_e32 v47, v6, v58
	ds_read_b128 v[50:53], v139 offset:46112
	v_fmac_f32_e32 v46, v6, v59
	ds_read_b128 v[56:59], v139 offset:46128
	v_fmac_f32_e32 v45, v6, v60
	v_fmac_f32_e32 v44, v6, v61
	ds_read_b128 v[60:63], v139 offset:46144
	ds_read_b128 v[64:67], v139 offset:46160
	s_waitcnt lgkmcnt(3)
	v_fmac_f32_e32 v49, v7, v52
	v_fmac_f32_e32 v48, v7, v53
	s_waitcnt lgkmcnt(2)
	v_fmac_f32_e32 v47, v7, v56
	v_fmac_f32_e32 v46, v7, v57
	v_fmac_f32_e32 v45, v7, v58
	v_fmac_f32_e32 v44, v7, v59
	s_waitcnt lgkmcnt(1)
	v_fmac_f32_e32 v49, v8, v62
	v_fmac_f32_e32 v48, v8, v63
	s_waitcnt lgkmcnt(0)
	v_fmac_f32_e32 v47, v8, v64
	ds_read_b128 v[56:59], v139 offset:46176
	v_fmac_f32_e32 v46, v8, v65
	ds_read_b128 v[62:65], v139 offset:46192
	v_pk_fma_f32 v[18:19], v[32:33], v[18:19], v[74:75] op_sel:[1,0,0]
	v_fmac_f32_e32 v45, v8, v66
	v_fmac_f32_e32 v44, v8, v67
	ds_read_b128 v[66:69], v139 offset:55296
	ds_read_b128 v[70:73], v139 offset:55312
	v_pk_fma_f32 v[18:19], v[2:3], v[26:27], v[18:19] op_sel_hi:[0,1,1]
	v_pk_fma_f32 v[2:3], v[2:3], v[28:29], v[18:19] op_sel:[1,0,0]
	s_waitcnt lgkmcnt(3)
	v_fmac_f32_e32 v49, v9, v58
	v_pk_fma_f32 v[2:3], v[4:5], v[20:21], v[2:3] op_sel_hi:[0,1,1]
	v_pk_fma_f32 v[2:3], v[4:5], v[22:23], v[2:3] op_sel:[1,0,0]
	v_fmac_f32_e32 v48, v9, v59
	s_waitcnt lgkmcnt(2)
	v_fmac_f32_e32 v47, v9, v62
	v_fmac_f32_e32 v46, v9, v63
	v_pk_fma_f32 v[2:3], v[6:7], v[54:55], v[2:3] op_sel_hi:[0,1,1]
	v_fmac_f32_e32 v45, v9, v64
	v_fmac_f32_e32 v44, v9, v65
	s_waitcnt lgkmcnt(1)
	v_fmac_f32_e32 v49, v10, v68
	v_fmac_f32_e32 v48, v10, v69
	s_waitcnt lgkmcnt(0)
	v_fmac_f32_e32 v47, v10, v70
	v_fmac_f32_e32 v46, v10, v71
	ds_read_b128 v[62:65], v139 offset:55328
	ds_read_b128 v[68:71], v139 offset:55344
	v_pk_fma_f32 v[2:3], v[6:7], v[50:51], v[2:3] op_sel:[1,0,0]
	ds_read_b128 v[18:21], v139 offset:55392
	v_pk_fma_f32 v[2:3], v[8:9], v[60:61], v[2:3] op_sel_hi:[0,1,1]
	v_pk_fma_f32 v[2:3], v[8:9], v[56:57], v[2:3] op_sel:[1,0,0]
	ds_read_b128 v[6:9], v139 offset:55376
	v_pk_fma_f32 v[2:3], v[10:11], v[66:67], v[2:3] op_sel_hi:[0,1,1]
	s_waitcnt lgkmcnt(3)
	v_pk_fma_f32 v[32:33], v[10:11], v[62:63], v[2:3] op_sel:[1,0,0]
	ds_read_b128 v[2:5], v139 offset:55360
	v_fmac_f32_e32 v49, v11, v64
	v_fmac_f32_e32 v48, v11, v65
	s_waitcnt lgkmcnt(3)
	v_fmac_f32_e32 v47, v11, v68
	v_fmac_f32_e32 v46, v11, v69
	s_waitcnt lgkmcnt(0)
	v_fmac_f32_e32 v49, v12, v4
	v_fmac_f32_e32 v48, v12, v5
	v_fmac_f32_e32 v47, v12, v6
	v_fmac_f32_e32 v46, v12, v7
	ds_read_b128 v[4:7], v139 offset:55408
	v_fmac_f32_e32 v45, v10, v72
	v_fmac_f32_e32 v44, v10, v73
	v_fmac_f32_e32 v45, v11, v70
	v_fmac_f32_e32 v44, v11, v71
	v_fmac_f32_e32 v45, v12, v8
	v_fmac_f32_e32 v44, v12, v9
	v_fmac_f32_e32 v49, v13, v20
	v_fmac_f32_e32 v48, v13, v21
	ds_read_b128 v[8:11], v139 offset:64512
	ds_read_b128 v[20:23], v139 offset:64528
	s_waitcnt lgkmcnt(2)
	v_fmac_f32_e32 v47, v13, v4
	v_fmac_f32_e32 v46, v13, v5
	v_fmac_f32_e32 v45, v13, v6
	v_fmac_f32_e32 v44, v13, v7
	ds_read_b128 v[4:7], v139 offset:64544
	ds_read_b128 v[24:27], v139 offset:64560
	v_pk_fma_f32 v[2:3], v[12:13], v[2:3], v[32:33] op_sel_hi:[0,1,1]
	s_waitcnt lgkmcnt(2)
	v_fmac_f32_e32 v47, v14, v20
	v_fmac_f32_e32 v46, v14, v21
	v_fmac_f32_e32 v45, v14, v22
	v_fmac_f32_e32 v44, v14, v23
	ds_read_b128 v[20:23], v139 offset:64576
	ds_read_b128 v[28:31], v139 offset:64592
	ds_read_b128 v[50:53], v139 offset:64608
	ds_read_b128 v[54:57], v139 offset:64624
	v_pk_fma_f32 v[2:3], v[12:13], v[18:19], v[2:3] op_sel:[1,0,0]
	v_fmac_f32_e32 v49, v14, v10
	v_pk_fma_f32 v[2:3], v[14:15], v[8:9], v[2:3] op_sel_hi:[0,1,1]
	s_waitcnt lgkmcnt(5)
	v_pk_fma_f32 v[2:3], v[14:15], v[4:5], v[2:3] op_sel:[1,0,0]
	v_fmac_f32_e32 v49, v15, v6
	s_waitcnt lgkmcnt(3)
	v_pk_fma_f32 v[2:3], v[16:17], v[20:21], v[2:3] op_sel_hi:[0,1,1]
	s_waitcnt lgkmcnt(1)
	v_pk_fma_f32 v[2:3], v[16:17], v[50:51], v[2:3] op_sel:[1,0,0]
	ds_bpermute_b32 v4, v103, v2
	ds_bpermute_b32 v5, v103, v3
	v_fmac_f32_e32 v49, v16, v22
	v_fmac_f32_e32 v49, v17, v52
	ds_bpermute_b32 v6, v103, v49
	v_fmac_f32_e32 v48, v14, v11
	s_waitcnt lgkmcnt(1)
	v_pk_add_f32 v[2:3], v[2:3], v[4:5]
	ds_bpermute_b32 v4, v134, v2
	ds_bpermute_b32 v5, v134, v3
	s_waitcnt lgkmcnt(2)
	v_add_f32_e32 v6, v49, v6
	v_fmac_f32_e32 v48, v15, v7
	ds_bpermute_b32 v7, v134, v6
	v_fmac_f32_e32 v47, v15, v24
	s_waitcnt lgkmcnt(1)
	v_pk_add_f32 v[2:3], v[2:3], v[4:5]
	ds_bpermute_b32 v4, v135, v2
	ds_bpermute_b32 v5, v135, v3
	v_fmac_f32_e32 v48, v16, v23
	v_fmac_f32_e32 v47, v16, v28
	v_fmac_f32_e32 v48, v17, v53
	v_fmac_f32_e32 v47, v17, v54
	s_waitcnt lgkmcnt(0)
	v_pk_add_f32 v[2:3], v[2:3], v[4:5]
	ds_bpermute_b32 v4, v136, v2
	ds_bpermute_b32 v5, v136, v3
	v_add_f32_e32 v6, v6, v7
	ds_bpermute_b32 v8, v103, v48
	ds_bpermute_b32 v7, v135, v6
	ds_bpermute_b32 v9, v103, v47
	s_waitcnt lgkmcnt(3)
	v_pk_add_f32 v[2:3], v[2:3], v[4:5]
	ds_bpermute_b32 v4, v137, v2
	ds_bpermute_b32 v5, v137, v3
	s_waitcnt lgkmcnt(3)
	v_add_f32_e32 v6, v6, v7
	s_waitcnt lgkmcnt(2)
	v_add_f32_e32 v7, v47, v9
	ds_bpermute_b32 v9, v136, v6
	v_fmac_f32_e32 v46, v15, v25
	s_waitcnt lgkmcnt(1)
	v_pk_add_f32 v[2:3], v[2:3], v[4:5]
	v_add_f32_e32 v4, v48, v8
	ds_bpermute_b32 v5, v134, v4
	ds_bpermute_b32 v8, v134, v7
	s_waitcnt lgkmcnt(2)
	v_add_f32_e32 v6, v6, v9
	ds_bpermute_b32 v11, v137, v6
	v_fmac_f32_e32 v45, v15, v26
	s_waitcnt lgkmcnt(2)
	v_add_f32_e32 v5, v4, v5
	s_waitcnt lgkmcnt(1)
	v_add_f32_e32 v7, v7, v8
	ds_bpermute_b32 v10, v135, v5
	ds_bpermute_b32 v8, v135, v7
	s_waitcnt lgkmcnt(2)
	v_add_f32_e32 v6, v6, v11
	v_fmac_f32_e32 v44, v15, v27
	v_fmac_f32_e32 v46, v16, v29
	s_waitcnt lgkmcnt(1)
	v_add_f32_e32 v9, v5, v10
	s_waitcnt lgkmcnt(0)
	v_add_f32_e32 v7, v7, v8
	ds_bpermute_b32 v10, v136, v9
	ds_bpermute_b32 v8, v136, v7
	v_fmac_f32_e32 v45, v16, v30
	v_fmac_f32_e32 v44, v16, v31
	v_fmac_f32_e32 v46, v17, v55
	s_waitcnt lgkmcnt(1)
	v_add_f32_e32 v9, v9, v10
	s_waitcnt lgkmcnt(0)
	v_add_f32_e32 v11, v7, v8
	ds_bpermute_b32 v10, v137, v9
	ds_bpermute_b32 v12, v137, v11
	v_fmac_f32_e32 v45, v17, v56
	v_fmac_f32_e32 v44, v17, v57
	ds_bpermute_b32 v13, v103, v46
	s_waitcnt lgkmcnt(2)
	v_add_f32_e32 v8, v9, v10
	s_waitcnt lgkmcnt(1)
	v_add_f32_e32 v10, v11, v12
	ds_bpermute_b32 v12, v103, v45
	ds_bpermute_b32 v14, v103, v44
	s_waitcnt lgkmcnt(2)
	v_add_f32_e32 v13, v46, v13
	ds_bpermute_b32 v15, v134, v13
	ds_bpermute_b32 v4, v138, v2
	s_waitcnt lgkmcnt(3)
	v_add_f32_e32 v12, v45, v12
	s_waitcnt lgkmcnt(2)
	v_add_f32_e32 v14, v44, v14
	ds_bpermute_b32 v16, v134, v12
	ds_bpermute_b32 v17, v134, v14
	s_waitcnt lgkmcnt(3)
	v_add_f32_e32 v13, v13, v15
	ds_bpermute_b32 v15, v135, v13
	ds_bpermute_b32 v5, v138, v3
	s_waitcnt lgkmcnt(3)
	v_add_f32_e32 v12, v12, v16
	s_waitcnt lgkmcnt(2)
	v_add_f32_e32 v14, v14, v17
	ds_bpermute_b32 v16, v135, v12
	ds_bpermute_b32 v17, v135, v14
	s_waitcnt lgkmcnt(3)
	v_add_f32_e32 v13, v13, v15
	ds_bpermute_b32 v15, v136, v13
	ds_bpermute_b32 v7, v138, v6
	s_waitcnt lgkmcnt(3)
	v_add_f32_e32 v12, v12, v16
	s_waitcnt lgkmcnt(2)
	v_add_f32_e32 v14, v14, v17
	ds_bpermute_b32 v16, v136, v12
	ds_bpermute_b32 v17, v136, v14
	s_waitcnt lgkmcnt(3)
	v_add_f32_e32 v13, v13, v15
	ds_bpermute_b32 v15, v137, v13
	ds_bpermute_b32 v9, v138, v8
	s_waitcnt lgkmcnt(3)
	v_add_f32_e32 v16, v12, v16
	s_waitcnt lgkmcnt(2)
	v_add_f32_e32 v17, v14, v17
	ds_bpermute_b32 v18, v137, v16
	ds_bpermute_b32 v19, v137, v17
	s_waitcnt lgkmcnt(3)
	v_add_f32_e32 v12, v13, v15
	ds_bpermute_b32 v11, v138, v10
	ds_bpermute_b32 v13, v138, v12
	s_waitcnt lgkmcnt(3)
	v_add_f32_e32 v14, v16, v18
	s_waitcnt lgkmcnt(2)
	v_add_f32_e32 v16, v17, v19
	ds_bpermute_b32 v15, v138, v14
	ds_bpermute_b32 v17, v138, v16
	v_lshl_add_u64 v[42:43], s[72:73], 0, v[130:131]
	v_add_co_u32_e32 v42, vcc, s29, v42
	s_nop 1
	v_addc_co_u32_e32 v43, vcc, 0, v43, vcc
	global_store_dwordx4 v[42:43], v[34:37], off
	global_store_dwordx4 v[42:43], v[38:41], off offset:64
	s_and_saveexec_b64 s[50:51], s[8:9]
	s_cbranch_execz .LBB0_1961
	v_pk_add_f32 v[2:3], v[2:3], v[4:5]
	v_add_f32_e32 v6, v6, v7
	v_cmp_gt_f32_e32 vcc, v3, v2
	v_add_f32_e32 v8, v8, v9
	s_waitcnt lgkmcnt(3)
	v_add_f32_e32 v10, v10, v11
	v_cndmask_b32_e32 v4, v2, v3, vcc
	v_cmp_gt_f32_e64 s[10:11], v6, v4
	s_waitcnt lgkmcnt(2)
	v_add_f32_e32 v12, v12, v13
	s_waitcnt lgkmcnt(1)
	v_add_f32_e32 v14, v14, v15
	v_cndmask_b32_e64 v4, v4, v6, s[10:11]
	v_cmp_gt_f32_e64 s[12:13], v8, v4
	s_waitcnt lgkmcnt(0)
	v_add_f32_e32 v16, v16, v17
	v_cmp_nlt_f32_e64 s[24:25], s33, v2
	v_cndmask_b32_e64 v4, v4, v8, s[12:13]
	v_cmp_gt_f32_e64 s[14:15], v10, v4
	s_nop 1
	v_cndmask_b32_e64 v4, v4, v10, s[14:15]
	v_cmp_gt_f32_e64 s[16:17], v12, v4
	s_nop 1
	v_cndmask_b32_e64 v4, v4, v12, s[16:17]
	v_cmp_gt_f32_e64 s[18:19], v14, v4
	s_nop 1
	v_cndmask_b32_e64 v5, v4, v14, s[18:19]
	v_cndmask_b32_e64 v4, 0, 1, vcc
	v_cndmask_b32_e64 v4, v4, 2, s[10:11]
	v_cndmask_b32_e64 v4, v4, 3, s[12:13]
	v_cndmask_b32_e64 v4, v4, 4, s[14:15]
	v_cndmask_b32_e64 v4, v4, 5, s[16:17]
	v_cndmask_b32_e64 v4, v4, 6, s[18:19]
	v_cmp_ngt_f32_e32 vcc, v16, v5
	s_nop 1
	v_cndmask_b32_e32 v4, 7, v4, vcc
	v_cmp_eq_u32_e64 s[22:23], 0, v4
	s_or_b64 s[22:23], s[24:25], s[22:23]
	v_cmp_ne_u32_e64 s[20:21], 1, v4
	v_cndmask_b32_e64 v2, v2, v142, s[22:23]
	v_cmp_gt_f32_e64 s[24:25], v3, v2
	s_and_b64 s[20:21], s[20:21], s[24:25]
	v_cndmask_b32_e64 v2, v2, v3, s[20:21]
	v_cmp_ne_u32_e64 s[18:19], 2, v4
	v_cmp_gt_f32_e64 s[24:25], v6, v2
	s_and_b64 s[18:19], s[18:19], s[24:25]
	v_cndmask_b32_e64 v2, v2, v6, s[18:19]
	v_cmp_ne_u32_e64 s[16:17], 3, v4
	v_cmp_gt_f32_e64 s[24:25], v8, v2
	s_and_b64 s[16:17], s[16:17], s[24:25]
	v_cndmask_b32_e64 v2, v2, v8, s[16:17]
	v_cmp_ne_u32_e64 s[14:15], 4, v4
	v_cmp_gt_f32_e64 s[24:25], v10, v2
	s_and_b64 s[14:15], s[14:15], s[24:25]
	v_cndmask_b32_e64 v2, v2, v10, s[14:15]
	v_cmp_ne_u32_e64 s[12:13], 5, v4
	v_cmp_gt_f32_e64 s[24:25], v12, v2
	s_and_b64 s[12:13], s[12:13], s[24:25]
	v_cndmask_b32_e64 v2, v2, v12, s[12:13]
	v_cmp_ne_u32_e64 s[10:11], 6, v4
	v_cmp_gt_f32_e64 s[24:25], v14, v2
	s_and_b64 s[10:11], s[10:11], s[24:25]
	v_cndmask_b32_e64 v2, v2, v14, s[10:11]
	v_cmp_gt_f32_e64 s[24:25], v16, v2
	s_and_b64 s[24:25], vcc, s[24:25]
	v_cndmask_b32_e32 v3, v16, v5, vcc
	v_cndmask_b32_e64 v2, v2, v16, s[24:25]
	v_sub_f32_e32 v2, v2, v3
	v_mul_f32_e32 v2, 0x3fb8aa3b, v2
	v_exp_f32_e32 v2, v2
	v_cndmask_b32_e64 v3, 0, -1, s[22:23]
	v_cndmask_b32_e64 v3, v3, 1, s[20:21]
	v_cndmask_b32_e64 v3, v3, 2, s[18:19]
	v_add_f32_e32 v6, 1.0, v2
	v_div_scale_f32 v7, s[4:5], v6, v6, v2
	v_cndmask_b32_e64 v3, v3, 3, s[16:17]
	v_rcp_f32_e32 v8, v7
	v_cndmask_b32_e64 v3, v3, 4, s[14:15]
	v_cndmask_b32_e64 v3, v3, 5, s[12:13]
	v_cndmask_b32_e64 v3, v3, 6, s[10:11]
	v_cndmask_b32_e64 v5, v3, 7, s[24:25]
	v_fma_f32 v3, -v7, v8, 1.0
	v_fmac_f32_e32 v8, v3, v8
	v_div_scale_f32 v3, vcc, v2, v6, v2
	v_mul_f32_e32 v9, v3, v8
	v_fma_f32 v10, -v7, v9, v3
	v_fmac_f32_e32 v9, v10, v8
	v_fma_f32 v3, -v7, v9, v3
	v_div_scale_f32 v7, s[4:5], v6, v6, 1.0
	v_rcp_f32_e32 v10, v7
	v_div_fmas_f32 v3, v3, v8, v9
	v_div_fixup_f32 v11, v3, v6, v2
	v_fma_f32 v2, -v7, v10, 1.0
	v_fmac_f32_e32 v10, v2, v10
	v_div_scale_f32 v2, vcc, 1.0, v6, 1.0
	v_mul_f32_e32 v3, v2, v10
	v_fma_f32 v8, -v7, v3, v2
	v_fmac_f32_e32 v3, v8, v10
	v_fma_f32 v2, -v7, v3, v2
	v_div_fmas_f32 v2, v2, v10, v3
	v_div_fixup_f32 v10, v2, v6, 1.0
	v_lshlrev_b64 v[2:3], 2, v[126:127]
	v_add_u32_e32 v8, 1, v126
	v_lshl_add_u64 v[6:7], s[36:37], 0, v[2:3]
	v_ashrrev_i32_e32 v9, 31, v8
	v_lshl_add_u64 v[2:3], s[38:39], 0, v[2:3]
	global_store_dword v[2:3], v10, off
	v_lshl_add_u64 v[2:3], v[8:9], 2, s[38:39]
	global_store_dwordx2 v[6:7], v[4:5], off
	global_store_dword v[2:3], v11, off
	v_lshl_add_u32 v2, v4, 2, s40
	ds_add_u32 v2, v141
	v_lshl_add_u32 v2, v5, 2, s40
	ds_add_u32 v2, v141
	s_branch .LBB0_1961
.LBB0_1966:
	s_or_b64 exec, exec, s[30:31]
	s_waitcnt lgkmcnt(0)
	s_barrier
	s_and_saveexec_b64 s[4:5], s[6:7]
	s_cbranch_execz .LBB0_1968
	v_add_u32_e32 v1, 0x14000, v1
	v_lshl_add_u32 v2, s96, 3, v102
	ds_read_b32 v1, v1
	v_ashrrev_i32_e32 v3, 31, v2
	v_lshl_add_u64 v[2:3], v[2:3], 2, s[72:73]
	v_add_co_u32_e32 v2, vcc, 0x1060000, v2
	s_nop 1
	v_addc_co_u32_e32 v3, vcc, 0, v3, vcc
	s_waitcnt lgkmcnt(0)
	global_store_dword v[2:3], v1, off

.LBB0_2111:
	v_ashrrev_i32_e32 v1, 6, v10
	v_cmp_gt_i32_e32 vcc, s1, v1
	s_and_saveexec_b64 s[6:7], vcc
	s_cbranch_execz .LBB0_2114
	v_and_b32_e32 v2, 63, v10
	v_lshlrev_b32_e32 v2, 4, v2
	v_mov_b32_e32 v3, 0
	v_lshl_add_u64 v[4:5], s[72:73], 0, v[2:3]
	s_mov_b64 s[2:3], 0x26b00000
	v_lshl_add_u64 v[2:3], v[4:5], 0, s[2:3]
	s_mov_b64 s[2:3], 0x28b00000
	v_lshl_add_u32 v6, v1, 2, 0
	v_lshl_add_u64 v[4:5], v[4:5], 0, s[2:3]
	v_add_u32_e32 v6, 0x8900, v6
	s_mov_b64 s[8:9], 0
	s_cmpk_lg_i32 s1, 0x80
	s_cbranch_scc1 .LBB0_2113
	v_ashrrev_i32_e32 v7, 1, v1
	v_add_u32_e32 v8, s0, v7
	v_ashrrev_i32_e32 v9, 31, v8
	v_lshlrev_b64 v[8:9], 11, v[8:9]
	v_lshl_add_u64 v[16:17], v[2:3], 0, v[8:9]
	s_mov_b64 s[2:3], 0x2000
	global_load_dwordx4 v[20:23], v[16:17], off
	global_load_dwordx4 v[24:27], v[16:17], off offset:1024
	ds_read_b32 v150, v6
	v_lshl_add_u64 v[16:17], v[16:17], 0, s[2:3]
	global_load_dwordx4 v[28:31], v[16:17], off
	global_load_dwordx4 v[32:35], v[16:17], off offset:1024
	ds_read_b32 v151, v6 offset:32
	v_lshl_add_u64 v[16:17], v[16:17], 0, s[2:3]
	global_load_dwordx4 v[36:39], v[16:17], off
	global_load_dwordx4 v[40:43], v[16:17], off offset:1024
	ds_read_b32 v152, v6 offset:64
	v_lshl_add_u64 v[16:17], v[16:17], 0, s[2:3]
	global_load_dwordx4 v[44:47], v[16:17], off
	global_load_dwordx4 v[48:51], v[16:17], off offset:1024
	ds_read_b32 v153, v6 offset:96
	v_lshl_add_u64 v[16:17], v[16:17], 0, s[2:3]
	global_load_dwordx4 v[52:55], v[16:17], off
	global_load_dwordx4 v[56:59], v[16:17], off offset:1024
	ds_read_b32 v154, v6 offset:128
	v_lshl_add_u64 v[16:17], v[16:17], 0, s[2:3]
	global_load_dwordx4 v[60:63], v[16:17], off
	global_load_dwordx4 v[64:67], v[16:17], off offset:1024
	ds_read_b32 v155, v6 offset:160
	v_lshl_add_u64 v[16:17], v[16:17], 0, s[2:3]
	global_load_dwordx4 v[68:71], v[16:17], off
	global_load_dwordx4 v[72:75], v[16:17], off offset:1024
	ds_read_b32 v156, v6 offset:192
	v_lshl_add_u64 v[16:17], v[16:17], 0, s[2:3]
	global_load_dwordx4 v[76:79], v[16:17], off
	global_load_dwordx4 v[80:83], v[16:17], off offset:1024
	ds_read_b32 v157, v6 offset:224
	v_lshl_add_u64 v[16:17], v[16:17], 0, s[2:3]
	global_load_dwordx4 v[84:87], v[16:17], off
	global_load_dwordx4 v[88:91], v[16:17], off offset:1024
	ds_read_b32 v158, v6 offset:256
	v_lshl_add_u64 v[16:17], v[16:17], 0, s[2:3]
	global_load_dwordx4 v[92:95], v[16:17], off
	global_load_dwordx4 v[96:99], v[16:17], off offset:1024
	ds_read_b32 v159, v6 offset:288
	v_lshl_add_u64 v[16:17], v[16:17], 0, s[2:3]
	global_load_dwordx4 v[100:103], v[16:17], off
	global_load_dwordx4 v[104:107], v[16:17], off offset:1024
	ds_read_b32 v160, v6 offset:320
	v_lshl_add_u64 v[16:17], v[16:17], 0, s[2:3]
	global_load_dwordx4 v[108:111], v[16:17], off
	global_load_dwordx4 v[112:115], v[16:17], off offset:1024
	ds_read_b32 v161, v6 offset:352
	v_lshl_add_u64 v[16:17], v[16:17], 0, s[2:3]
	global_load_dwordx4 v[116:119], v[16:17], off
	global_load_dwordx4 v[120:123], v[16:17], off offset:1024
	ds_read_b32 v162, v6 offset:384
	v_lshl_add_u64 v[16:17], v[16:17], 0, s[2:3]
	global_load_dwordx4 v[124:127], v[16:17], off
	global_load_dwordx4 v[128:131], v[16:17], off offset:1024
	ds_read_b32 v163, v6 offset:416
	v_lshl_add_u64 v[16:17], v[16:17], 0, s[2:3]
	global_load_dwordx4 v[132:135], v[16:17], off
	global_load_dwordx4 v[136:139], v[16:17], off offset:1024
	ds_read_b32 v164, v6 offset:448
	v_lshl_add_u64 v[16:17], v[16:17], 0, s[2:3]
	global_load_dwordx4 v[140:143], v[16:17], off
	global_load_dwordx4 v[144:147], v[16:17], off offset:1024
	ds_read_b32 v165, v6 offset:480
	s_waitcnt lgkmcnt(0)
	v_ashrrev_i32_e32 v19, 31, v150
	v_mov_b32_e32 v18, v150
	v_lshlrev_b64 v[18:19], 11, v[18:19]
	v_lshl_add_u64 v[18:19], v[4:5], 0, v[18:19]
	s_waitcnt vmcnt(30)
	global_store_dwordx4 v[18:19], v[20:23], off
	global_store_dwordx4 v[18:19], v[24:27], off offset:1024
	v_ashrrev_i32_e32 v19, 31, v151
	v_mov_b32_e32 v18, v151
	v_lshlrev_b64 v[18:19], 11, v[18:19]
	v_lshl_add_u64 v[18:19], v[4:5], 0, v[18:19]
	s_waitcnt vmcnt(30)
	global_store_dwordx4 v[18:19], v[28:31], off
	global_store_dwordx4 v[18:19], v[32:35], off offset:1024
	v_ashrrev_i32_e32 v19, 31, v152
	v_mov_b32_e32 v18, v152
	v_lshlrev_b64 v[18:19], 11, v[18:19]
	v_lshl_add_u64 v[18:19], v[4:5], 0, v[18:19]
	s_waitcnt vmcnt(30)
	global_store_dwordx4 v[18:19], v[36:39], off
	global_store_dwordx4 v[18:19], v[40:43], off offset:1024
	v_ashrrev_i32_e32 v19, 31, v153
	v_mov_b32_e32 v18, v153
	v_lshlrev_b64 v[18:19], 11, v[18:19]
	v_lshl_add_u64 v[18:19], v[4:5], 0, v[18:19]
	s_waitcnt vmcnt(30)
	global_store_dwordx4 v[18:19], v[44:47], off
	global_store_dwordx4 v[18:19], v[48:51], off offset:1024
	v_ashrrev_i32_e32 v19, 31, v154
	v_mov_b32_e32 v18, v154
	v_lshlrev_b64 v[18:19], 11, v[18:19]
	v_lshl_add_u64 v[18:19], v[4:5], 0, v[18:19]
	s_waitcnt vmcnt(30)
	global_store_dwordx4 v[18:19], v[52:55], off
	global_store_dwordx4 v[18:19], v[56:59], off offset:1024
	v_ashrrev_i32_e32 v19, 31, v155
	v_mov_b32_e32 v18, v155
	v_lshlrev_b64 v[18:19], 11, v[18:19]
	v_lshl_add_u64 v[18:19], v[4:5], 0, v[18:19]
	s_waitcnt vmcnt(30)
	global_store_dwordx4 v[18:19], v[60:63], off
	global_store_dwordx4 v[18:19], v[64:67], off offset:1024
	v_ashrrev_i32_e32 v19, 31, v156
	v_mov_b32_e32 v18, v156
	v_lshlrev_b64 v[18:19], 11, v[18:19]
	v_lshl_add_u64 v[18:19], v[4:5], 0, v[18:19]
	s_waitcnt vmcnt(30)
	global_store_dwordx4 v[18:19], v[68:71], off
	global_store_dwordx4 v[18:19], v[72:75], off offset:1024
	v_ashrrev_i32_e32 v19, 31, v157
	v_mov_b32_e32 v18, v157
	v_lshlrev_b64 v[18:19], 11, v[18:19]
	v_lshl_add_u64 v[18:19], v[4:5], 0, v[18:19]
	s_waitcnt vmcnt(30)
	global_store_dwordx4 v[18:19], v[76:79], off
	global_store_dwordx4 v[18:19], v[80:83], off offset:1024
	v_ashrrev_i32_e32 v19, 31, v158
	v_mov_b32_e32 v18, v158
	v_lshlrev_b64 v[18:19], 11, v[18:19]
	v_lshl_add_u64 v[18:19], v[4:5], 0, v[18:19]
	s_waitcnt vmcnt(30)
	global_store_dwordx4 v[18:19], v[84:87], off
	global_store_dwordx4 v[18:19], v[88:91], off offset:1024
	v_ashrrev_i32_e32 v19, 31, v159
	v_mov_b32_e32 v18, v159
	v_lshlrev_b64 v[18:19], 11, v[18:19]
	v_lshl_add_u64 v[18:19], v[4:5], 0, v[18:19]
	s_waitcnt vmcnt(30)
	global_store_dwordx4 v[18:19], v[92:95], off
	global_store_dwordx4 v[18:19], v[96:99], off offset:1024
	v_ashrrev_i32_e32 v19, 31, v160
	v_mov_b32_e32 v18, v160
	v_lshlrev_b64 v[18:19], 11, v[18:19]
	v_lshl_add_u64 v[18:19], v[4:5], 0, v[18:19]
	s_waitcnt vmcnt(30)
	global_store_dwordx4 v[18:19], v[100:103], off
	global_store_dwordx4 v[18:19], v[104:107], off offset:1024
	v_ashrrev_i32_e32 v19, 31, v161
	v_mov_b32_e32 v18, v161
	v_lshlrev_b64 v[18:19], 11, v[18:19]
	v_lshl_add_u64 v[18:19], v[4:5], 0, v[18:19]
	s_waitcnt vmcnt(30)
	global_store_dwordx4 v[18:19], v[108:111], off
	global_store_dwordx4 v[18:19], v[112:115], off offset:1024
	v_ashrrev_i32_e32 v19, 31, v162
	v_mov_b32_e32 v18, v162
	v_lshlrev_b64 v[18:19], 11, v[18:19]
	v_lshl_add_u64 v[18:19], v[4:5], 0, v[18:19]
	s_waitcnt vmcnt(30)
	global_store_dwordx4 v[18:19], v[116:119], off
	global_store_dwordx4 v[18:19], v[120:123], off offset:1024
	v_ashrrev_i32_e32 v19, 31, v163
	v_mov_b32_e32 v18, v163
	v_lshlrev_b64 v[18:19], 11, v[18:19]
	v_lshl_add_u64 v[18:19], v[4:5], 0, v[18:19]
	s_waitcnt vmcnt(30)
	global_store_dwordx4 v[18:19], v[124:127], off
	global_store_dwordx4 v[18:19], v[128:131], off offset:1024
	v_ashrrev_i32_e32 v19, 31, v164
	v_mov_b32_e32 v18, v164
	v_lshlrev_b64 v[18:19], 11, v[18:19]
	v_lshl_add_u64 v[18:19], v[4:5], 0, v[18:19]
	s_waitcnt vmcnt(30)
	global_store_dwordx4 v[18:19], v[132:135], off
	global_store_dwordx4 v[18:19], v[136:139], off offset:1024
	v_ashrrev_i32_e32 v19, 31, v165
	v_mov_b32_e32 v18, v165
	v_lshlrev_b64 v[18:19], 11, v[18:19]
	v_lshl_add_u64 v[18:19], v[4:5], 0, v[18:19]
	s_waitcnt vmcnt(30)
	global_store_dwordx4 v[18:19], v[140:143], off
	global_store_dwordx4 v[18:19], v[144:147], off offset:1024
	s_branch .LBB0_2114

.LBB0_2187:
	ds_read_b128 v[142:145], v138
	ds_read_b128 v[188:191], v138 offset:1024
	ds_read_b128 v[148:151], v138 offset:2048
	ds_read_b128 v[192:195], v138 offset:3072
	ds_read_b128 v[154:157], v139
	ds_read_b128 v[196:199], v139 offset:1024
	ds_read_b128 v[160:163], v139 offset:2048
	ds_read_b128 v[200:203], v139 offset:3072
	v_lshl_add_u64 v[146:147], s[48:49], 0, v[136:137]
	s_add_i32 m0, s33, 0xc000
	ds_read_b128 v[166:169], v140
	ds_read_b128 v[204:207], v140 offset:1024
	ds_read_b128 v[172:175], v140 offset:2048
	ds_read_b128 v[208:211], v140 offset:3072
	ds_read_b128 v[178:181], v140 offset:4096
	ds_read_b128 v[212:215], v140 offset:5120
	ds_read_b128 v[184:187], v140 offset:6144
	ds_read_b128 v[216:219], v140 offset:7168
	global_load_lds_dwordx4 v[146:147], off
	s_add_i32 m0, s33, 0xe000
	v_lshl_add_u64 v[146:147], v[146:147], 0, s[6:7]
	global_load_lds_dwordx4 v[146:147], off
	s_waitcnt vmcnt(8)
	s_waitcnt lgkmcnt(0)
	s_barrier
	s_waitcnt lgkmcnt(0)
	v_mov_b32_e32 v146, v188
	v_mov_b32_e32 v147, v189
	v_mov_b32_e32 v152, v192
	v_mov_b32_e32 v153, v193
	v_mov_b32_e32 v170, v204
	v_mov_b32_e32 v171, v205
	v_mov_b32_e32 v176, v208
	v_mov_b32_e32 v177, v209
	v_mov_b32_e32 v182, v212
	v_mov_b32_e32 v183, v213
	v_mov_b32_e32 v188, v216
	v_mov_b32_e32 v189, v217
	v_mfma_scale_f32_16x16x128_f8f6f4 v[128:131], v[142:147], v[166:171], v[128:131], v190, v206 op_sel_hi:[0,0,0] cbsz:2 blgp:2
	v_mfma_scale_f32_16x16x128_f8f6f4 v[124:127], v[148:153], v[166:171], v[124:127], v194, v206 op_sel_hi:[0,0,0] cbsz:2 blgp:2
	v_mfma_scale_f32_16x16x128_f8f6f4 v[120:123], v[142:147], v[172:177], v[120:123], v190, v210 op_sel_hi:[0,0,0] cbsz:2 blgp:2
	v_mfma_scale_f32_16x16x128_f8f6f4 v[116:119], v[148:153], v[172:177], v[116:119], v194, v210 op_sel_hi:[0,0,0] cbsz:2 blgp:2
	s_add_u32 s50, s48, 0xfffc0080
	s_addc_u32 s51, s49, -1
	s_cmp_eq_u32 s76, 12
	s_cselect_b32 s51, s35, s51
	s_cselect_b32 s50, s47, s50
	s_cselect_b32 s53, s37, s67
	s_cselect_b32 s52, s65, s66
	s_add_i32 s100, s57, s29
	s_add_i32 s101, s58, s29
	v_lshl_add_u64 v[232:233], s[52:53], 0, v[132:133]
	v_lshl_add_u64 v[234:235], s[50:51], 0, v[134:135]
	v_lshl_add_u64 v[240:241], v[232:233], 0, s[6:7]
	v_lshl_add_u64 v[242:243], v[232:233], 0, s[8:9]
	v_lshl_add_u64 v[244:245], v[232:233], 0, s[10:11]
	v_lshl_add_u64 v[246:247], v[234:235], 0, s[6:7]
	v_mfma_scale_f32_16x16x128_f8f6f4 v[112:115], v[142:147], v[178:183], v[112:115], v190, v214 op_sel_hi:[0,0,0] cbsz:2 blgp:2
	v_mfma_scale_f32_16x16x128_f8f6f4 v[108:111], v[148:153], v[178:183], v[108:111], v194, v214 op_sel_hi:[0,0,0] cbsz:2 blgp:2
	v_mfma_scale_f32_16x16x128_f8f6f4 v[104:107], v[142:147], v[184:189], v[104:107], v190, v218 op_sel_hi:[0,0,0] cbsz:2 blgp:2
	v_mfma_scale_f32_16x16x128_f8f6f4 v[100:103], v[148:153], v[184:189], v[100:103], v194, v218 op_sel_hi:[0,0,0] cbsz:2 blgp:2
	v_mov_b32_e32 v164, v200
	v_mov_b32_e32 v165, v201
	v_mov_b32_e32 v158, v196
	v_mov_b32_e32 v159, v197
	v_mfma_scale_f32_16x16x128_f8f6f4 v[30:33], v[160:165], v[184:189], v[30:33], v202, v218 op_sel_hi:[0,0,0] cbsz:2 blgp:2
	s_nop 0
	v_mfma_scale_f32_16x16x128_f8f6f4 v[220:223], v[154:159], v[166:171], v[2:5], v198, v206 op_sel_hi:[0,0,0] cbsz:2 blgp:2
	v_mfma_scale_f32_16x16x128_f8f6f4 v[166:169], v[160:165], v[166:171], v[6:9], v202, v206 op_sel_hi:[0,0,0] cbsz:2 blgp:2
	v_mfma_scale_f32_16x16x128_f8f6f4 v[204:207], v[154:159], v[172:177], v[10:13], v198, v210 op_sel_hi:[0,0,0] cbsz:2 blgp:2
	v_mfma_scale_f32_16x16x128_f8f6f4 v[170:173], v[160:165], v[172:177], v[14:17], v202, v210 op_sel_hi:[0,0,0] cbsz:2 blgp:2
	v_mfma_scale_f32_16x16x128_f8f6f4 v[174:177], v[154:159], v[178:183], v[18:21], v198, v214 op_sel_hi:[0,0,0] cbsz:2 blgp:2
	v_mfma_scale_f32_16x16x128_f8f6f4 v[178:181], v[160:165], v[178:183], v[22:25], v202, v214 op_sel_hi:[0,0,0] cbsz:2 blgp:2
	v_mfma_scale_f32_16x16x128_f8f6f4 v[208:211], v[154:159], v[184:189], v[26:29], v198, v218 op_sel_hi:[0,0,0] cbsz:2 blgp:2
	s_barrier
	s_mov_b32 m0, s100
	ds_read_b128 v[2:5], v140 offset:16384
	ds_read_b128 v[24:27], v140 offset:17408
	ds_read_b128 v[8:11], v140 offset:18432
	global_load_lds_dwordx4 v[232:233], off
	s_add_i32 m0, s100, 0x2000
	ds_read_b128 v[182:185], v140 offset:19456
	global_load_lds_dwordx4 v[240:241], off
	s_mov_b32 m0, s101
	ds_read_b128 v[14:17], v140 offset:20480
	global_load_lds_dwordx4 v[242:243], off
	s_add_i32 m0, s101, 0x2000
	ds_read_b128 v[186:189], v140 offset:21504
	global_load_lds_dwordx4 v[244:245], off
	s_mov_b32 m0, s33
	ds_read_b128 v[20:23], v140 offset:22528
	global_load_lds_dwordx4 v[234:235], off
	s_mov_b32 m0, s40
	ds_read_b128 v[212:215], v140 offset:23552
	global_load_lds_dwordx4 v[246:247], off
	s_waitcnt vmcnt(8)
	s_waitcnt lgkmcnt(0)
	s_barrier
	s_waitcnt lgkmcnt(0)
	v_mov_b32_e32 v6, v24
	v_mov_b32_e32 v7, v25
	v_mov_b32_e32 v12, v182
	v_mov_b32_e32 v13, v183
	v_mov_b32_e32 v18, v186
	v_mov_b32_e32 v19, v187
	v_mfma_scale_f32_16x16x128_f8f6f4 v[96:99], v[142:147], v[2:7], v[96:99], v190, v26 op_sel_hi:[0,0,0] cbsz:2 blgp:2
	v_mov_b32_e32 v24, v212
	v_mov_b32_e32 v25, v213
	v_mfma_scale_f32_16x16x128_f8f6f4 v[92:95], v[148:153], v[2:7], v[92:95], v194, v26 op_sel_hi:[0,0,0] cbsz:2 blgp:2
	v_mfma_scale_f32_16x16x128_f8f6f4 v[80:83], v[142:147], v[8:13], v[80:83], v190, v184 op_sel_hi:[0,0,0] cbsz:2 blgp:2
	v_mfma_scale_f32_16x16x128_f8f6f4 v[76:79], v[148:153], v[8:13], v[76:79], v194, v184 op_sel_hi:[0,0,0] cbsz:2 blgp:2
	s_add_i32 s50, 0, 0x18000
	s_add_i32 s51, 0, 0x1c000
	v_add_u32_e32 v252, 0x18000, v1
	v_add_u32_e32 v253, 0x1c000, v1
	v_lshl_add_u64 v[248:249], v[234:235], 0, s[8:9]
	v_lshl_add_u64 v[250:251], v[234:235], 0, s[10:11]
	v_mfma_scale_f32_16x16x128_f8f6f4 v[68:71], v[142:147], v[14:19], v[68:71], v190, v188 op_sel_hi:[0,0,0] cbsz:2 blgp:2
	v_mfma_scale_f32_16x16x128_f8f6f4 v[56:59], v[148:153], v[14:19], v[56:59], v194, v188 op_sel_hi:[0,0,0] cbsz:2 blgp:2
	v_mfma_scale_f32_16x16x128_f8f6f4 v[190:193], v[142:147], v[20:25], v[52:55], v190, v214 op_sel_hi:[0,0,0] cbsz:2 blgp:2
	v_mfma_scale_f32_16x16x128_f8f6f4 v[194:197], v[148:153], v[20:25], v[44:47], v194, v214 op_sel_hi:[0,0,0] cbsz:2 blgp:2
	v_mfma_scale_f32_16x16x128_f8f6f4 v[88:91], v[154:159], v[2:7], v[88:91], v198, v26 op_sel_hi:[0,0,0] cbsz:2 blgp:2
	v_mfma_scale_f32_16x16x128_f8f6f4 v[84:87], v[160:165], v[2:7], v[84:87], v202, v26 op_sel_hi:[0,0,0] cbsz:2 blgp:2
	v_mfma_scale_f32_16x16x128_f8f6f4 v[72:75], v[154:159], v[8:13], v[72:75], v198, v184 op_sel_hi:[0,0,0] cbsz:2 blgp:2
	v_mfma_scale_f32_16x16x128_f8f6f4 v[182:185], v[160:165], v[8:13], v[64:67], v202, v184 op_sel_hi:[0,0,0] cbsz:2 blgp:2
	v_mfma_scale_f32_16x16x128_f8f6f4 v[216:219], v[154:159], v[14:19], v[60:63], v198, v188 op_sel_hi:[0,0,0] cbsz:2 blgp:2
	v_mfma_scale_f32_16x16x128_f8f6f4 v[186:189], v[160:165], v[14:19], v[48:51], v202, v188 op_sel_hi:[0,0,0] cbsz:2 blgp:2
	v_mfma_scale_f32_16x16x128_f8f6f4 v[198:201], v[154:159], v[20:25], v[40:43], v198, v214 op_sel_hi:[0,0,0] cbsz:2 blgp:2
	v_mfma_scale_f32_16x16x128_f8f6f4 v[212:215], v[160:165], v[20:25], v[36:39], v202, v214 op_sel_hi:[0,0,0] cbsz:2 blgp:2
	s_barrier
	s_mov_b32 m0, s41
	ds_read_b128 v[36:39], v252
	ds_read_b128 v[52:55], v252 offset:1024
	ds_read_b128 v[42:45], v252 offset:2048
	ds_read_b128 v[64:67], v252 offset:3072
	ds_read_b128 v[142:145], v253
	ds_read_b128 v[224:227], v253 offset:1024
	ds_read_b128 v[148:151], v253 offset:2048
	ds_read_b128 v[228:231], v253 offset:3072
	ds_read_b128 v[6:9], v140 offset:32768
	ds_read_b128 v[10:13], v140 offset:33792
	ds_read_b128 v[14:17], v140 offset:34816
	ds_read_b128 v[18:21], v140 offset:35840
	ds_read_b128 v[22:25], v140 offset:36864
	ds_read_b128 v[26:29], v140 offset:37888
	global_load_lds_dwordx4 v[248:249], off
	s_mov_b32 m0, s42
	ds_read_b128 v[48:51], v140 offset:38912
	ds_read_b128 v[60:63], v140 offset:39936
	global_load_lds_dwordx4 v[250:251], off
	s_waitcnt vmcnt(8)
	s_waitcnt lgkmcnt(0)
	s_barrier
	s_waitcnt lgkmcnt(0)
	v_mov_b32_e32 v40, v52
	v_mov_b32_e32 v41, v53
	v_mov_b32_e32 v46, v64
	v_mov_b32_e32 v47, v65
	v_mov_b32_e32 v52, v60
	v_mov_b32_e32 v53, v61
	v_mfma_scale_f32_16x16x128_f8f6f4 v[128:131], v[36:41], v[6:11], v[128:131], v54, v12 op_sel_hi:[0,0,0] cbsz:2 blgp:2
	v_mfma_scale_f32_16x16x128_f8f6f4 v[124:127], v[42:47], v[6:11], v[124:127], v66, v12 op_sel_hi:[0,0,0] cbsz:2 blgp:2
	v_mfma_scale_f32_16x16x128_f8f6f4 v[120:123], v[36:41], v[14:19], v[120:123], v54, v20 op_sel_hi:[0,0,0] cbsz:2 blgp:2
	v_mfma_scale_f32_16x16x128_f8f6f4 v[116:119], v[42:47], v[14:19], v[116:119], v66, v20 op_sel_hi:[0,0,0] cbsz:2 blgp:2
	s_add_i32 s100, s50, s29
	s_add_i32 s101, s51, s29
	s_add_i32 s50, s51, s29
	v_lshl_add_u64 v[240:241], v[232:233], 0, s[20:21]
	v_lshl_add_u64 v[242:243], v[232:233], 0, s[22:23]
	v_lshl_add_u64 v[244:245], v[232:233], 0, s[24:25]
	v_lshl_add_u64 v[246:247], v[232:233], 0, s[26:27]
	v_lshl_add_u64 v[248:249], v[234:235], 0, s[20:21]
	v_lshl_add_u64 v[250:251], v[234:235], 0, s[22:23]
	v_mfma_scale_f32_16x16x128_f8f6f4 v[112:115], v[36:41], v[22:27], v[112:115], v54, v28 op_sel_hi:[0,0,0] cbsz:2 blgp:2
	v_mfma_scale_f32_16x16x128_f8f6f4 v[108:111], v[42:47], v[22:27], v[108:111], v66, v28 op_sel_hi:[0,0,0] cbsz:2 blgp:2
	v_mfma_scale_f32_16x16x128_f8f6f4 v[104:107], v[36:41], v[48:53], v[104:107], v54, v62 op_sel_hi:[0,0,0] cbsz:2 blgp:2
	v_mfma_scale_f32_16x16x128_f8f6f4 v[100:103], v[42:47], v[48:53], v[100:103], v66, v62 op_sel_hi:[0,0,0] cbsz:2 blgp:2
	v_mov_b32_e32 v146, v224
	v_mov_b32_e32 v147, v225
	v_mov_b32_e32 v152, v228
	v_mov_b32_e32 v153, v229
	v_mfma_scale_f32_16x16x128_f8f6f4 v[2:5], v[142:147], v[6:11], v[220:223], v226, v12 op_sel_hi:[0,0,0] cbsz:2 blgp:2
	s_nop 0
	v_mfma_scale_f32_16x16x128_f8f6f4 v[6:9], v[148:153], v[6:11], v[166:169], v230, v12 op_sel_hi:[0,0,0] cbsz:2 blgp:2
	v_mfma_scale_f32_16x16x128_f8f6f4 v[10:13], v[142:147], v[14:19], v[204:207], v226, v20 op_sel_hi:[0,0,0] cbsz:2 blgp:2
	v_mfma_scale_f32_16x16x128_f8f6f4 v[14:17], v[148:153], v[14:19], v[170:173], v230, v20 op_sel_hi:[0,0,0] cbsz:2 blgp:2
	v_mfma_scale_f32_16x16x128_f8f6f4 v[18:21], v[142:147], v[22:27], v[174:177], v226, v28 op_sel_hi:[0,0,0] cbsz:2 blgp:2
	v_mfma_scale_f32_16x16x128_f8f6f4 v[22:25], v[148:153], v[22:27], v[178:181], v230, v28 op_sel_hi:[0,0,0] cbsz:2 blgp:2
	v_mfma_scale_f32_16x16x128_f8f6f4 v[26:29], v[142:147], v[48:53], v[208:211], v226, v62 op_sel_hi:[0,0,0] cbsz:2 blgp:2
	v_mfma_scale_f32_16x16x128_f8f6f4 v[30:33], v[148:153], v[48:53], v[30:33], v230, v62 op_sel_hi:[0,0,0] cbsz:2 blgp:2
	s_barrier
	s_mov_b32 m0, s100
	ds_read_b128 v[60:63], v140 offset:49152
	ds_read_b128 v[48:51], v140 offset:50176
	ds_read_b128 v[154:157], v140 offset:51200
	global_load_lds_dwordx4 v[240:241], off
	s_add_i32 m0, s100, 0x2000
	ds_read_b128 v[170:173], v140 offset:52224
	global_load_lds_dwordx4 v[242:243], off
	s_mov_b32 m0, s101
	ds_read_b128 v[160:163], v140 offset:53248
	global_load_lds_dwordx4 v[244:245], off
	s_add_i32 m0, s101, 0x2000
	ds_read_b128 v[174:177], v140 offset:54272
	global_load_lds_dwordx4 v[246:247], off
	s_mov_b32 m0, s43
	ds_read_b128 v[166:169], v140 offset:55296
	global_load_lds_dwordx4 v[248:249], off
	s_mov_b32 m0, s54
	ds_read_b128 v[178:181], v140 offset:56320
	global_load_lds_dwordx4 v[250:251], off
	s_waitcnt vmcnt(8)
	s_waitcnt lgkmcnt(0)
	s_barrier
	s_waitcnt lgkmcnt(0)
	v_mov_b32_e32 v64, v48
	v_mov_b32_e32 v65, v49
	v_mov_b32_e32 v158, v170
	v_mov_b32_e32 v159, v171
	v_mov_b32_e32 v164, v174
	v_mov_b32_e32 v165, v175
	v_mov_b32_e32 v170, v178
	v_mov_b32_e32 v171, v179
	v_mfma_scale_f32_16x16x128_f8f6f4 v[96:99], v[36:41], v[60:65], v[96:99], v54, v50 op_sel_hi:[0,0,0] cbsz:2 blgp:2
	v_mfma_scale_f32_16x16x128_f8f6f4 v[92:95], v[42:47], v[60:65], v[92:95], v66, v50 op_sel_hi:[0,0,0] cbsz:2 blgp:2
	v_mfma_scale_f32_16x16x128_f8f6f4 v[80:83], v[36:41], v[154:159], v[80:83], v54, v172 op_sel_hi:[0,0,0] cbsz:2 blgp:2
	v_mfma_scale_f32_16x16x128_f8f6f4 v[76:79], v[42:47], v[154:159], v[76:79], v66, v172 op_sel_hi:[0,0,0] cbsz:2 blgp:2
	s_add_i32 s76, s76, 2
	s_add_u32 s48, s48, 0x100
	s_addc_u32 s49, s49, 0
	s_add_u32 s66, s66, 0x100
	s_addc_u32 s67, s67, 0
	v_mfma_scale_f32_16x16x128_f8f6f4 v[68:71], v[36:41], v[160:165], v[68:71], v54, v176 op_sel_hi:[0,0,0] cbsz:2 blgp:2
	v_mfma_scale_f32_16x16x128_f8f6f4 v[56:59], v[42:47], v[160:165], v[56:59], v66, v176 op_sel_hi:[0,0,0] cbsz:2 blgp:2
	v_mfma_scale_f32_16x16x128_f8f6f4 v[52:55], v[36:41], v[166:171], v[190:193], v54, v180 op_sel_hi:[0,0,0] cbsz:2 blgp:2
	v_mfma_scale_f32_16x16x128_f8f6f4 v[44:47], v[42:47], v[166:171], v[194:197], v66, v180 op_sel_hi:[0,0,0] cbsz:2 blgp:2
	v_mfma_scale_f32_16x16x128_f8f6f4 v[88:91], v[142:147], v[60:65], v[88:91], v226, v50 op_sel_hi:[0,0,0] cbsz:2 blgp:2
	v_mfma_scale_f32_16x16x128_f8f6f4 v[84:87], v[148:153], v[60:65], v[84:87], v230, v50 op_sel_hi:[0,0,0] cbsz:2 blgp:2
	v_mfma_scale_f32_16x16x128_f8f6f4 v[72:75], v[142:147], v[154:159], v[72:75], v226, v172 op_sel_hi:[0,0,0] cbsz:2 blgp:2
	v_mfma_scale_f32_16x16x128_f8f6f4 v[64:67], v[148:153], v[154:159], v[182:185], v230, v172 op_sel_hi:[0,0,0] cbsz:2 blgp:2
	v_mfma_scale_f32_16x16x128_f8f6f4 v[60:63], v[142:147], v[160:165], v[216:219], v226, v176 op_sel_hi:[0,0,0] cbsz:2 blgp:2
	v_mfma_scale_f32_16x16x128_f8f6f4 v[48:51], v[148:153], v[160:165], v[186:189], v230, v176 op_sel_hi:[0,0,0] cbsz:2 blgp:2
	v_mfma_scale_f32_16x16x128_f8f6f4 v[40:43], v[142:147], v[166:171], v[198:201], v226, v180 op_sel_hi:[0,0,0] cbsz:2 blgp:2
	v_mfma_scale_f32_16x16x128_f8f6f4 v[36:39], v[148:153], v[166:171], v[212:215], v230, v180 op_sel_hi:[0,0,0] cbsz:2 blgp:2
	s_barrier
	s_cmp_gt_u32 s76, 13
	s_cbranch_scc0 .LBB0_2187
	s_setprio 0
	s_and_b64 vcc, exec, s[30:31]
	s_cbranch_vccz .LBB0_2190
	s_barrier
.LBB0_2190:
	v_mul_f32_e32 v141, 0xbfb8aa3b, v128
	v_exp_f32_e32 v141, v141
	v_mul_f32_e32 v142, 0xbfb8aa3b, v129
	v_exp_f32_e32 v142, v142
	v_mov_b32_e32 v34, v0
	v_add_f32_e32 v141, 1.0, v141
	v_rcp_f32_e32 v141, v141
	v_add_f32_e32 v142, 1.0, v142
	v_rcp_f32_e32 v142, v142
	v_readlane_b32 s76, v254, 6
	v_and_or_b32 v143, v34, 63, s55
	v_mul_f32_e32 v34, v128, v141
	v_mul_f32_e32 v128, 0xbfb8aa3b, v130
	v_mul_f32_e32 v2, v34, v2
	v_mul_f32_e32 v34, v129, v142
	v_exp_f32_e32 v128, v128
	v_mul_f32_e32 v129, 0xbfb8aa3b, v131
	v_exp_f32_e32 v129, v129
	v_mul_f32_e32 v3, v34, v3
	v_add_f32_e32 v34, 1.0, v128
	v_rcp_f32_e32 v34, v34
	v_add_f32_e32 v128, 1.0, v129
	v_mul_f32_e32 v129, 0xbfb8aa3b, v124
	v_rcp_f32_e32 v128, v128
	v_exp_f32_e32 v129, v129
	v_mul_f32_e32 v34, v130, v34
	v_mul_f32_e32 v4, v34, v4
	v_mul_f32_e32 v34, v131, v128
	v_add_f32_e32 v128, 1.0, v129
	v_rcp_f32_e32 v128, v128
	v_mul_f32_e32 v129, 0xbfb8aa3b, v125
	v_exp_f32_e32 v129, v129
	v_mul_f32_e32 v5, v34, v5
	v_mul_f32_e32 v34, v124, v128
	v_mul_f32_e32 v124, 0xbfb8aa3b, v126
	v_mul_f32_e32 v6, v34, v6
	v_add_f32_e32 v34, 1.0, v129
	v_exp_f32_e32 v124, v124
	v_mul_f32_e32 v128, 0xbfb8aa3b, v127
	v_rcp_f32_e32 v34, v34
	v_exp_f32_e32 v128, v128
	v_add_f32_e32 v124, 1.0, v124
	v_rcp_f32_e32 v124, v124
	v_mul_f32_e32 v34, v125, v34
	v_add_f32_e32 v125, 1.0, v128
	v_rcp_f32_e32 v125, v125
	v_mul_f32_e32 v7, v34, v7
	v_mul_f32_e32 v34, v126, v124
	v_mul_f32_e32 v8, v34, v8
	v_mul_f32_e32 v34, v127, v125
	v_mul_f32_e32 v124, 0xbfb8aa3b, v120
	v_mul_f32_e32 v125, 0xbfb8aa3b, v121
	v_exp_f32_e32 v124, v124
	v_exp_f32_e32 v125, v125
	v_mul_f32_e32 v9, v34, v9
	v_readlane_b32 s82, v254, 12
	v_add_f32_e32 v34, 1.0, v124
	v_add_f32_e32 v124, 1.0, v125
	v_mul_f32_e32 v125, 0xbfb8aa3b, v122
	v_rcp_f32_e32 v34, v34
	v_exp_f32_e32 v125, v125
	v_rcp_f32_e32 v124, v124
	v_readlane_b32 s83, v254, 13
	v_mul_f32_e32 v34, v120, v34
	v_add_f32_e32 v120, 1.0, v125
	v_mul_f32_e32 v10, v34, v10
	v_mul_f32_e32 v34, v121, v124
	v_rcp_f32_e32 v120, v120
	v_mul_f32_e32 v121, 0xbfb8aa3b, v123
	v_exp_f32_e32 v121, v121
	v_mul_f32_e32 v11, v34, v11
	v_mul_f32_e32 v34, v122, v120
	v_mul_f32_e32 v120, 0xbfb8aa3b, v116
	v_mul_f32_e32 v12, v34, v12
	v_add_f32_e32 v34, 1.0, v121
	v_exp_f32_e32 v120, v120
	v_mul_f32_e32 v121, 0xbfb8aa3b, v117
	v_exp_f32_e32 v121, v121
	v_rcp_f32_e32 v34, v34
	v_add_f32_e32 v120, 1.0, v120
	v_rcp_f32_e32 v120, v120
	v_add_f32_e32 v121, 1.0, v121
	v_rcp_f32_e32 v121, v121
	v_mul_f32_e32 v34, v123, v34
	v_mul_f32_e32 v13, v34, v13
	v_mul_f32_e32 v34, v116, v120
	v_mul_f32_e32 v116, 0xbfb8aa3b, v118
	v_mul_f32_e32 v14, v34, v14
	v_mul_f32_e32 v34, v117, v121
	v_exp_f32_e32 v116, v116
	v_mul_f32_e32 v117, 0xbfb8aa3b, v119
	v_exp_f32_e32 v117, v117
	v_mul_f32_e32 v15, v34, v15
	v_add_f32_e32 v34, 1.0, v116
	v_rcp_f32_e32 v34, v34
	v_add_f32_e32 v116, 1.0, v117
	v_mul_f32_e32 v117, 0xbfb8aa3b, v112
	v_rcp_f32_e32 v116, v116
	v_exp_f32_e32 v117, v117
	v_mul_f32_e32 v34, v118, v34
	v_mul_f32_e32 v16, v34, v16
	v_mul_f32_e32 v34, v119, v116
	v_add_f32_e32 v116, 1.0, v117
	v_rcp_f32_e32 v116, v116
	v_mul_f32_e32 v117, 0xbfb8aa3b, v113
	v_exp_f32_e32 v117, v117
	v_mul_f32_e32 v17, v34, v17
	v_mul_f32_e32 v34, v112, v116
	v_mul_f32_e32 v112, 0xbfb8aa3b, v114
	v_mul_f32_e32 v18, v34, v18
	v_add_f32_e32 v34, 1.0, v117
	v_exp_f32_e32 v112, v112
	v_mul_f32_e32 v116, 0xbfb8aa3b, v115
	v_rcp_f32_e32 v34, v34
	v_exp_f32_e32 v116, v116
	v_add_f32_e32 v112, 1.0, v112
	v_rcp_f32_e32 v112, v112
	v_mul_f32_e32 v34, v113, v34
	v_add_f32_e32 v113, 1.0, v116
	v_rcp_f32_e32 v113, v113
	v_mul_f32_e32 v19, v34, v19
	v_mul_f32_e32 v34, v114, v112
	v_mul_f32_e32 v20, v34, v20
	v_mul_f32_e32 v34, v115, v113
	v_mul_f32_e32 v112, 0xbfb8aa3b, v108
	v_mul_f32_e32 v113, 0xbfb8aa3b, v109
	v_exp_f32_e32 v112, v112
	v_exp_f32_e32 v113, v113
	v_mul_f32_e32 v21, v34, v21
	v_permlane32_swap_b32_e32 v2, v18
	v_add_f32_e32 v34, 1.0, v112
	v_add_f32_e32 v112, 1.0, v113
	v_mul_f32_e32 v113, 0xbfb8aa3b, v110
	v_rcp_f32_e32 v34, v34
	v_exp_f32_e32 v113, v113
	v_rcp_f32_e32 v112, v112
	v_permlane32_swap_b32_e32 v3, v19
	v_mul_f32_e32 v34, v108, v34
	v_add_f32_e32 v108, 1.0, v113
	v_mul_f32_e32 v22, v34, v22
	v_mul_f32_e32 v34, v109, v112
	v_rcp_f32_e32 v108, v108
	v_mul_f32_e32 v109, 0xbfb8aa3b, v111
	v_exp_f32_e32 v109, v109
	v_mul_f32_e32 v23, v34, v23
	v_mul_f32_e32 v34, v110, v108
	v_mul_f32_e32 v108, 0xbfb8aa3b, v104
	v_mul_f32_e32 v24, v34, v24
	v_add_f32_e32 v34, 1.0, v109
	v_exp_f32_e32 v108, v108
	v_mul_f32_e32 v109, 0xbfb8aa3b, v105
	v_exp_f32_e32 v109, v109
	v_rcp_f32_e32 v34, v34
	v_add_f32_e32 v108, 1.0, v108
	v_rcp_f32_e32 v108, v108
	v_add_f32_e32 v109, 1.0, v109
	v_rcp_f32_e32 v109, v109
	v_mul_f32_e32 v34, v111, v34
	v_mul_f32_e32 v25, v34, v25
	v_mul_f32_e32 v34, v104, v108
	v_mul_f32_e32 v104, 0xbfb8aa3b, v106
	v_mul_f32_e32 v26, v34, v26
	v_mul_f32_e32 v34, v105, v109
	v_exp_f32_e32 v104, v104
	v_mul_f32_e32 v105, 0xbfb8aa3b, v107
	v_exp_f32_e32 v105, v105
	v_mul_f32_e32 v27, v34, v27
	v_add_f32_e32 v34, 1.0, v104
	v_rcp_f32_e32 v34, v34
	v_add_f32_e32 v104, 1.0, v105
	v_mul_f32_e32 v105, 0xbfb8aa3b, v100
	v_rcp_f32_e32 v104, v104
	v_exp_f32_e32 v105, v105
	v_mul_f32_e32 v34, v106, v34
	v_mul_f32_e32 v28, v34, v28
	v_mul_f32_e32 v34, v107, v104
	v_add_f32_e32 v104, 1.0, v105
	v_rcp_f32_e32 v104, v104
	v_mul_f32_e32 v105, 0xbfb8aa3b, v101
	v_exp_f32_e32 v105, v105
	v_mul_f32_e32 v29, v34, v29
	v_mul_f32_e32 v34, v100, v104
	v_mul_f32_e32 v100, 0xbfb8aa3b, v102
	v_mul_f32_e32 v30, v34, v30
	v_add_f32_e32 v34, 1.0, v105
	v_exp_f32_e32 v100, v100
	v_mul_f32_e32 v104, 0xbfb8aa3b, v103
	v_rcp_f32_e32 v34, v34
	v_exp_f32_e32 v104, v104
	v_add_f32_e32 v100, 1.0, v100
	v_rcp_f32_e32 v100, v100
	v_mul_f32_e32 v34, v101, v34
	v_add_f32_e32 v101, 1.0, v104
	v_rcp_f32_e32 v101, v101
	v_mul_f32_e32 v31, v34, v31
	v_mul_f32_e32 v34, v102, v100
	v_permlane32_swap_b32_e32 v10, v26
	v_mul_f32_e32 v32, v34, v32
	v_mul_f32_e32 v34, v103, v101
	v_permlane32_swap_b32_e32 v11, v27
	v_permlane16_swap_b32_e32 v2, v10
	v_permlane16_swap_b32_e32 v18, v26
	v_mul_f32_e32 v33, v34, v33
	v_permlane16_swap_b32_e32 v3, v11
	v_permlane16_swap_b32_e32 v19, v27
	v_permlane32_swap_b32_e32 v4, v20
	v_permlane32_swap_b32_e32 v12, v28
	v_permlane32_swap_b32_e32 v5, v21
	v_permlane32_swap_b32_e32 v13, v29
	v_permlane16_swap_b32_e32 v4, v12
	v_permlane16_swap_b32_e32 v20, v28
	v_permlane16_swap_b32_e32 v5, v13
	v_permlane16_swap_b32_e32 v21, v29
	v_max_f32_e64 v34, |v2|, |v18|
	v_max3_f32 v34, v34, |v3|, |v19|
	v_permlane32_swap_b32_e32 v6, v22
	v_permlane32_swap_b32_e32 v14, v30
	v_permlane32_swap_b32_e32 v7, v23
	v_permlane32_swap_b32_e32 v15, v31
	v_permlane16_swap_b32_e32 v6, v14
	v_permlane16_swap_b32_e32 v22, v30
	v_permlane16_swap_b32_e32 v7, v15
	v_permlane16_swap_b32_e32 v23, v31
	v_max3_f32 v34, v34, |v4|, |v20|
	v_max3_f32 v34, v34, |v5|, |v21|
	v_permlane32_swap_b32_e32 v8, v24
	v_permlane32_swap_b32_e32 v16, v32
	v_permlane32_swap_b32_e32 v9, v25
	v_permlane32_swap_b32_e32 v17, v33
	v_permlane16_swap_b32_e32 v8, v16
	v_permlane16_swap_b32_e32 v24, v32
	v_permlane16_swap_b32_e32 v9, v17
	v_permlane16_swap_b32_e32 v25, v33
	v_max3_f32 v34, v34, |v6|, |v22|
	v_max3_f32 v34, v34, |v7|, |v23|
	v_max3_f32 v34, v34, |v8|, |v24|
	v_max3_f32 v34, v34, |v9|, |v25|
	v_max3_f32 v34, v34, |v10|, |v26|
	v_max3_f32 v34, v34, |v11|, |v27|
	v_max3_f32 v34, v34, |v12|, |v28|
	v_max3_f32 v34, v34, |v13|, |v29|
	v_max3_f32 v34, v34, |v14|, |v30|
	v_max3_f32 v34, v34, |v15|, |v31|
	v_max3_f32 v34, v34, |v16|, |v32|
	v_max3_f32 v34, v34, |v17|, |v33|
	v_bfe_u32 v100, v34, 23, 8
	v_and_b32_e32 v34, 0x7fffff, v34
	v_cmp_gt_u32_e32 vcc, s59, v34
	v_lshl_add_u32 v108, s46, 8, v143
	v_readlane_b32 s77, v254, 7
	v_cndmask_b32_e64 v34, -2, -3, vcc
	v_add3_u32 v34, v100, v34, s60
	v_max_i32_e32 v34, 0xffffff88, v34
	v_add_u32_e32 v34, 0x7f, v34
	v_lshlrev_b32_e32 v100, 23, v34
	v_cvt_scalef32_2xpk16_fp6_f32 v[102:107], v[2:17], v[18:33], v100
	v_mul_f32_e32 v4, 0xbfb8aa3b, v96
	v_exp_f32_e32 v4, v4
	v_mul_f32_e32 v5, 0xbfb8aa3b, v97
	v_exp_f32_e32 v5, v5
	v_mov_b64_e32 v[100:101], s[18:19]
	v_mad_i64_i32 v[2:3], s[46:47], v108, s62, v[100:101]
	v_add_f32_e32 v4, 1.0, v4
	s_lshl_b32 s46, s5, 7
	v_rcp_f32_e32 v4, v4
	v_add_f32_e32 v5, 1.0, v5
	s_ashr_i32 s47, s46, 31
	v_rcp_f32_e32 v5, v5
	v_mul_f32_e32 v10, 0xbfb8aa3b, v80
	v_mul_f32_e32 v18, 0xbfb8aa3b, v68
	v_mul_f32_e32 v26, 0xbfb8aa3b, v52
	v_lshl_add_u64 v[2:3], v[2:3], 0, s[46:47]
	v_exp_f32_e32 v10, v10
	v_mul_f32_e32 v11, 0xbfb8aa3b, v81
	v_exp_f32_e32 v18, v18
	v_mul_f32_e32 v19, 0xbfb8aa3b, v69
	v_exp_f32_e32 v26, v26
	v_mul_f32_e32 v27, 0xbfb8aa3b, v53
	v_mul_lo_u32 v34, v34, s61
	v_lshl_add_u64 v[2:3], v[2:3], 0, s[12:13]
	v_mov_b32_e32 v32, v106
	v_mov_b32_e32 v33, v107
	v_exp_f32_e32 v11, v11
	v_exp_f32_e32 v19, v19
	v_exp_f32_e32 v27, v27
	global_store_dwordx4 v[2:3], v[102:105], off
	global_store_dwordx4 v[2:3], v[32:35], off offset:64
	v_mul_f32_e32 v2, v96, v4
	v_mul_f32_e32 v4, 0xbfb8aa3b, v98
	v_mul_f32_e32 v12, 0xbfb8aa3b, v82
	v_mul_f32_e32 v20, 0xbfb8aa3b, v70
	v_mul_f32_e32 v28, 0xbfb8aa3b, v54
	v_mul_f32_e32 v30, 0xbfb8aa3b, v44
	v_mul_f32_e32 v3, v97, v5
	v_exp_f32_e32 v4, v4
	v_mul_f32_e32 v5, 0xbfb8aa3b, v99
	v_exp_f32_e32 v12, v12
	v_mul_f32_e32 v13, 0xbfb8aa3b, v83
	v_exp_f32_e32 v20, v20
	v_mul_f32_e32 v21, 0xbfb8aa3b, v71
	v_exp_f32_e32 v28, v28
	v_mul_f32_e32 v29, 0xbfb8aa3b, v55
	v_exp_f32_e32 v30, v30
	v_mul_f32_e32 v31, 0xbfb8aa3b, v45
	v_exp_f32_e32 v5, v5
	v_add_f32_e32 v10, 1.0, v10
	v_exp_f32_e32 v13, v13
	v_add_f32_e32 v18, 1.0, v18
	v_exp_f32_e32 v21, v21
	v_add_f32_e32 v26, 1.0, v26
	v_exp_f32_e32 v29, v29
	v_exp_f32_e32 v31, v31
	v_mul_f32_e32 v6, 0xbfb8aa3b, v92
	v_rcp_f32_e32 v10, v10
	v_add_f32_e32 v11, 1.0, v11
	v_mul_f32_e32 v14, 0xbfb8aa3b, v76
	v_rcp_f32_e32 v18, v18
	v_add_f32_e32 v19, 1.0, v19
	v_mul_f32_e32 v22, 0xbfb8aa3b, v56
	v_rcp_f32_e32 v26, v26
	v_add_f32_e32 v27, 1.0, v27
	v_exp_f32_e32 v6, v6
	v_mul_f32_e32 v7, 0xbfb8aa3b, v93
	v_rcp_f32_e32 v11, v11
	v_exp_f32_e32 v14, v14
	v_mul_f32_e32 v15, 0xbfb8aa3b, v77
	v_rcp_f32_e32 v19, v19
	v_exp_f32_e32 v22, v22
	v_mul_f32_e32 v23, 0xbfb8aa3b, v57
	v_rcp_f32_e32 v27, v27
	v_mul_f32_e32 v32, 0xbfb8aa3b, v46
	v_add_f32_e32 v4, 1.0, v4
	v_exp_f32_e32 v7, v7
	v_add_f32_e32 v12, 1.0, v12
	v_exp_f32_e32 v15, v15
	v_add_f32_e32 v20, 1.0, v20
	v_exp_f32_e32 v23, v23
	v_add_f32_e32 v28, 1.0, v28
	v_add_f32_e32 v30, 1.0, v30
	v_exp_f32_e32 v32, v32
	v_rcp_f32_e32 v4, v4
	v_add_f32_e32 v5, 1.0, v5
	v_mul_f32_e32 v8, 0xbfb8aa3b, v94
	v_rcp_f32_e32 v12, v12
	v_add_f32_e32 v13, 1.0, v13
	v_mul_f32_e32 v16, 0xbfb8aa3b, v78
	v_rcp_f32_e32 v20, v20
	v_add_f32_e32 v21, 1.0, v21
	v_mul_f32_e32 v24, 0xbfb8aa3b, v58
	v_rcp_f32_e32 v28, v28
	v_add_f32_e32 v29, 1.0, v29
	v_rcp_f32_e32 v30, v30
	v_add_f32_e32 v31, 1.0, v31
	v_rcp_f32_e32 v5, v5
	v_exp_f32_e32 v8, v8
	v_mul_f32_e32 v9, 0xbfb8aa3b, v95
	v_mul_f32_e32 v10, v80, v10
	v_rcp_f32_e32 v13, v13
	v_exp_f32_e32 v16, v16
	v_mul_f32_e32 v17, 0xbfb8aa3b, v79
	v_mul_f32_e32 v18, v68, v18
	v_rcp_f32_e32 v21, v21
	v_exp_f32_e32 v24, v24
	v_mul_f32_e32 v25, 0xbfb8aa3b, v59
	v_mul_f32_e32 v26, v52, v26
	v_rcp_f32_e32 v29, v29
	v_rcp_f32_e32 v31, v31
	v_mul_f32_e32 v33, 0xbfb8aa3b, v47
	v_mul_f32_e32 v2, v2, v88
	v_add_f32_e32 v6, 1.0, v6
	v_exp_f32_e32 v9, v9
	v_mul_f32_e32 v10, v10, v72
	v_mul_f32_e32 v11, v81, v11
	v_add_f32_e32 v14, 1.0, v14
	v_exp_f32_e32 v17, v17
	v_mul_f32_e32 v18, v18, v60
	v_mul_f32_e32 v19, v69, v19
	v_add_f32_e32 v22, 1.0, v22
	v_exp_f32_e32 v25, v25
	v_mul_f32_e32 v26, v26, v40
	v_mul_f32_e32 v27, v53, v27
	v_exp_f32_e32 v33, v33
	v_mul_f32_e32 v3, v3, v89
	v_rcp_f32_e32 v6, v6
	v_add_f32_e32 v7, 1.0, v7
	v_mul_f32_e32 v11, v11, v73
	v_rcp_f32_e32 v14, v14
	v_add_f32_e32 v15, 1.0, v15
	v_mul_f32_e32 v19, v19, v61
	v_rcp_f32_e32 v22, v22
	v_add_f32_e32 v23, 1.0, v23
	v_mul_f32_e32 v27, v27, v41
	v_add_f32_e32 v32, 1.0, v32
	v_permlane32_swap_b32_e32 v2, v18
	v_permlane32_swap_b32_e32 v10, v26
	v_mul_f32_e32 v4, v98, v4
	v_rcp_f32_e32 v7, v7
	v_mul_f32_e32 v12, v82, v12
	v_rcp_f32_e32 v15, v15
	v_mul_f32_e32 v20, v70, v20
	v_rcp_f32_e32 v23, v23
	v_mul_f32_e32 v28, v54, v28
	v_mul_f32_e32 v30, v44, v30
	v_rcp_f32_e32 v32, v32
	v_permlane32_swap_b32_e32 v3, v19
	v_permlane32_swap_b32_e32 v11, v27
	v_permlane16_swap_b32_e32 v2, v10
	v_permlane16_swap_b32_e32 v18, v26
	v_mul_f32_e32 v4, v4, v90
	v_mul_f32_e32 v5, v99, v5
	v_add_f32_e32 v8, 1.0, v8
	v_mul_f32_e32 v12, v12, v74
	v_mul_f32_e32 v13, v83, v13
	v_add_f32_e32 v16, 1.0, v16
	v_mul_f32_e32 v20, v20, v62
	v_mul_f32_e32 v21, v71, v21
	v_add_f32_e32 v24, 1.0, v24
	v_mul_f32_e32 v28, v28, v42
	v_mul_f32_e32 v29, v55, v29
	v_mul_f32_e32 v30, v30, v36
	v_mul_f32_e32 v31, v45, v31
	v_permlane16_swap_b32_e32 v3, v11
	v_permlane16_swap_b32_e32 v19, v27
	v_mul_f32_e32 v5, v5, v91
	v_rcp_f32_e32 v8, v8
	v_add_f32_e32 v9, 1.0, v9
	v_mul_f32_e32 v13, v13, v75
	v_rcp_f32_e32 v16, v16
	v_add_f32_e32 v17, 1.0, v17
	v_mul_f32_e32 v21, v21, v63
	v_rcp_f32_e32 v24, v24
	v_add_f32_e32 v25, 1.0, v25
	v_mul_f32_e32 v29, v29, v43
	v_add_f32_e32 v33, 1.0, v33
	v_mul_f32_e32 v31, v31, v37
	v_permlane32_swap_b32_e32 v4, v20
	v_permlane32_swap_b32_e32 v12, v28
	v_mul_f32_e32 v6, v92, v6
	v_rcp_f32_e32 v9, v9
	v_mul_f32_e32 v14, v76, v14
	v_rcp_f32_e32 v17, v17
	v_mul_f32_e32 v22, v56, v22
	v_rcp_f32_e32 v25, v25
	v_rcp_f32_e32 v33, v33
	v_permlane32_swap_b32_e32 v5, v21
	v_permlane32_swap_b32_e32 v13, v29
	v_permlane16_swap_b32_e32 v4, v12
	v_permlane16_swap_b32_e32 v20, v28
	v_mul_f32_e32 v6, v6, v84
	v_mul_f32_e32 v7, v93, v7
	v_mul_f32_e32 v14, v14, v64
	v_mul_f32_e32 v15, v77, v15
	v_mul_f32_e32 v22, v22, v48
	v_mul_f32_e32 v23, v57, v23
	v_mul_f32_e32 v32, v46, v32
	v_permlane16_swap_b32_e32 v5, v13
	v_permlane16_swap_b32_e32 v21, v29
	v_max_f32_e64 v34, |v2|, |v18|
	v_max3_f32 v34, v34, |v3|, |v19|
	v_mul_f32_e32 v7, v7, v85
	v_mul_f32_e32 v15, v15, v65
	v_mul_f32_e32 v23, v23, v49
	v_mul_f32_e32 v32, v32, v38
	v_permlane32_swap_b32_e32 v6, v22
	v_permlane32_swap_b32_e32 v14, v30
	v_mul_f32_e32 v8, v94, v8
	v_mul_f32_e32 v16, v78, v16
	v_mul_f32_e32 v24, v58, v24
	v_permlane32_swap_b32_e32 v7, v23
	v_permlane32_swap_b32_e32 v15, v31
	v_permlane16_swap_b32_e32 v6, v14
	v_permlane16_swap_b32_e32 v22, v30
	v_mul_f32_e32 v8, v8, v86
	v_mul_f32_e32 v9, v95, v9
	v_mul_f32_e32 v16, v16, v66
	v_mul_f32_e32 v17, v79, v17
	v_mul_f32_e32 v24, v24, v50
	v_mul_f32_e32 v25, v59, v25
	v_mul_f32_e32 v33, v47, v33
	v_permlane16_swap_b32_e32 v7, v15
	v_permlane16_swap_b32_e32 v23, v31
	v_max3_f32 v34, v34, |v4|, |v20|
	v_max3_f32 v34, v34, |v5|, |v21|
	v_mul_f32_e32 v9, v9, v87
	v_mul_f32_e32 v17, v17, v67
	v_mul_f32_e32 v25, v25, v51
	v_mul_f32_e32 v33, v33, v39
	v_permlane32_swap_b32_e32 v8, v24
	v_permlane32_swap_b32_e32 v16, v32
	v_permlane32_swap_b32_e32 v9, v25
	v_permlane32_swap_b32_e32 v17, v33
	v_permlane16_swap_b32_e32 v8, v16
	v_permlane16_swap_b32_e32 v24, v32
	v_permlane16_swap_b32_e32 v9, v17
	v_permlane16_swap_b32_e32 v25, v33
	v_max3_f32 v34, v34, |v6|, |v22|
	v_max3_f32 v34, v34, |v7|, |v23|
	v_max3_f32 v34, v34, |v8|, |v24|
	v_max3_f32 v34, v34, |v9|, |v25|
	v_max3_f32 v34, v34, |v10|, |v26|
	v_max3_f32 v34, v34, |v11|, |v27|
	v_max3_f32 v34, v34, |v12|, |v28|
	v_max3_f32 v34, v34, |v13|, |v29|
	v_max3_f32 v34, v34, |v14|, |v30|
	v_max3_f32 v34, v34, |v15|, |v31|
	v_max3_f32 v34, v34, |v16|, |v32|
	v_max3_f32 v34, v34, |v17|, |v33|
	v_bfe_u32 v36, v34, 23, 8
	v_and_b32_e32 v34, 0x7fffff, v34
	v_cmp_gt_u32_e32 vcc, s59, v34
	s_cmp_eq_u32 s4, s56
	s_mov_b64 s[4:5], -1
	v_cndmask_b32_e64 v34, -2, -3, vcc
	v_add3_u32 v34, v36, v34, s60
	v_max_i32_e32 v34, 0xffffff88, v34
	v_add_u32_e32 v34, 0x7f, v34
	v_lshlrev_b32_e32 v42, 23, v34
	v_cvt_scalef32_2xpk16_fp6_f32 v[36:41], v[2:17], v[18:33], v42
	v_add_u32_e32 v2, 0x80, v108
	v_mad_i64_i32 v[2:3], s[48:49], v2, s62, v[100:101]
	v_lshl_add_u64 v[2:3], v[2:3], 0, s[46:47]
	v_mul_lo_u32 v34, v34, s61
	v_lshl_add_u64 v[2:3], v[2:3], 0, s[12:13]
	v_mov_b32_e32 v32, v40
	v_mov_b32_e32 v33, v41
	global_store_dwordx4 v[2:3], v[36:39], off
	global_store_dwordx4 v[2:3], v[32:35], off offset:64
	v_readlane_b32 s78, v254, 8
	v_readlane_b32 s79, v254, 9
	v_readlane_b32 s80, v254, 10
	v_readlane_b32 s81, v254, 11
	s_cbranch_scc1 .LBB0_2183
	s_andn2_b64 vcc, exec, s[14:15]
	s_cbranch_vccnz .LBB0_2182
	s_barrier
	s_branch .LBB0_2182

.LBB0_2294:
	v_mov_b32_e32 v134, v0
	s_cmp_eq_u32 s53, 0
	v_and_b32_e32 v143, 15, v134
	s_cbranch_scc1 .LBB0_2302
	s_bfe_u32 s4, s53, 0x80008
	s_lshl_b32 s4, s4, 7
	s_and_b32 s5, s53, 0xff
	s_add_i32 s4, s5, s4
	s_add_i32 s4, s4, -1
	s_ashr_i32 s5, s4, 31
	s_lshl_b64 s[4:5], s[4:5], 8
	s_add_u32 s4, s4, s54
	s_addc_u32 s5, s5, s55
	v_or_b32_e32 v138, s4, v143
	v_mov_b32_e32 v139, s5
	v_lshlrev_b64 v[138:139], 9, v[138:139]
	v_lshl_add_u64 v[138:139], s[22:23], 0, v[138:139]
	s_mov_b64 s[46:47], 0x100
	s_cbranch_execnz .LBB0_2297
